# GEMM loops: the compiler's second s_waitcnt lgkmcnt(0) directly before each MMA block removed (36 sites; the inline-asm wait in front of it stays)
# speedup vs baseline: 1.0045x; 1.0042x over previous
; #define STG(P, GB) do { const char* _gb = (GB); \
;     _Pragma("unroll") for (int _i = 0; _i < 2; ++_i) { \
;       __builtin_amdgcn_global_load_lds((const unsigned*)(_gb + voff[_i]), \
;         (LAS unsigned*)((LAS char*)(P) + ldsw + _i * 8192), 16, 0, 0); } } while (0)
; #define LDA(dst, b, h) _Pragma("unroll") for (int m = 0; m < 4; ++m) _Pragma("unroll") for (int k = 0; k < 2; ++k) \
;     dst[m][k] = *(const LAS bf16x8*)((LAS char*)SA(b, h) + aoff + m * 2048 + k * 1024)
; #define LDB(dst, b, h) _Pragma("unroll") for (int n = 0; n < 2; ++n) _Pragma("unroll") for (int k = 0; k < 2; ++k) \
;     dst[n][k] = *(const LAS bf16x8*)((LAS char*)SB(b, h) + boff + n * 2048 + k * 1024)
; #define MMA(ai, bj, At_, Bt_) do { __builtin_amdgcn_s_setprio(1); \
;     _Pragma("unroll") for (int m = 0; m < 4; ++m) _Pragma("unroll") for (int n = 0; n < 2; ++n) _Pragma("unroll") for (int k = 0; k < 2; ++k) \
;       acc[ai][bj][m][n] = __builtin_amdgcn_mfma_f32_16x16x32_bf16(Bt_[n][k], At_[m][k], acc[ai][bj][m][n], 0, 0, 0); \
;     __builtin_amdgcn_s_setprio(0); } while (0)
; #define WAIT_L(n) asm volatile("s_waitcnt lgkmcnt(" #n ")" ::: "memory")
; #define BAR __builtin_amdgcn_s_barrier()
; #define SCHED __builtin_amdgcn_sched_barrier(0)
; __device__ __forceinline__ void gemm_phase(const bf16_t* __restrict__ A, const bf16_t* __restrict__ Bt, bf16_t* __restrict__ C, int M, int N, int K,
;                                            int ldc, const int EPI, char* smem, const int wid_u) {
;     ...
;       const bool last = (t == nt - 2);
;       const char* a1 = cA + (size_t)(t + 1) * kstep;
;       const char* a2 = last ? nA : cA + (size_t)(t + 2) * kstep;
;       const char* b2 = last ? nB : cB + (size_t)(t + 2) * kstep;
;       const char* a3 = a2 + kstep;
;       const char* b3 = b2 + kstep;
;       LDB(B0, 0, 0); SCHED; LDA(At, 0, 0); STG(SA(1, 1), a1 + hstep);
;       WAIT_L(8); BAR; WAIT_L(0); MMA(0, 0, At, B0); BAR; SCHED;
;       LDB(B1, 0, 1); STG(SB(0, 0), b2);
;       BAR; WAIT_L(0); MMA(0, 1, At, B1); BAR;
;       LDA(At, 0, 1); STG(SA(0, 0), a2);
;       BAR; WAIT_L(0); MMA(1, 0, At, B0); BAR; SCHED;
.LBB0_145:
	ds_read_b128 v[150:153], v146
	ds_read_b128 v[154:157], v146 offset:1024
	ds_read_b128 v[158:161], v146 offset:2048
	ds_read_b128 v[162:165], v146 offset:3072
	s_add_u32 s18, s16, 0x100
	s_addc_u32 s19, s17, 0
	s_cmp_eq_u32 s49, 12
	s_cselect_b32 s23, s44, s19
	s_cselect_b32 s22, s45, s18
	s_cselect_b32 s21, s11, s48
	s_cselect_b32 s20, s46, s47
	v_lshl_add_u64 v[142:143], s[16:17], 0, v[136:137]
	s_add_i32 m0, s28, 0xc000
	ds_read_b128 v[166:169], v147
	ds_read_b128 v[170:173], v147 offset:1024
	ds_read_b128 v[174:177], v147 offset:2048
	ds_read_b128 v[178:181], v147 offset:3072
	ds_read_b128 v[182:185], v147 offset:4096
	ds_read_b128 v[186:189], v147 offset:5120
	ds_read_b128 v[190:193], v147 offset:6144
	ds_read_b128 v[194:197], v147 offset:7168
	global_load_lds_dwordx4 v[142:143], off
	v_lshl_add_u64 v[142:143], s[16:17], 0, v[134:135]
	s_add_i32 m0, s28, 0xe000
	s_nop 0
	global_load_lds_dwordx4 v[142:143], off
	s_waitcnt lgkmcnt(8)
	s_barrier
	s_waitcnt lgkmcnt(0)
	v_mfma_f32_16x16x32_bf16 v[124:127], v[150:153], v[166:169], v[124:127]
	v_mfma_f32_16x16x32_bf16 v[120:123], v[158:161], v[166:169], v[120:123]
	v_mfma_f32_16x16x32_bf16 v[108:111], v[150:153], v[174:177], v[108:111]
	v_mfma_f32_16x16x32_bf16 v[104:107], v[158:161], v[174:177], v[104:107]
	v_mfma_f32_16x16x32_bf16 v[92:95], v[150:153], v[182:185], v[92:95]
	v_mfma_f32_16x16x32_bf16 v[88:91], v[158:161], v[182:185], v[88:91]
	v_mfma_f32_16x16x32_bf16 v[76:79], v[150:153], v[190:193], v[76:79]
	v_mfma_f32_16x16x32_bf16 v[72:75], v[158:161], v[190:193], v[72:75]
	v_mfma_f32_16x16x32_bf16 v[124:127], v[154:157], v[170:173], v[124:127]
	v_mfma_f32_16x16x32_bf16 v[120:123], v[162:165], v[170:173], v[120:123]
	v_mfma_f32_16x16x32_bf16 v[108:111], v[154:157], v[178:181], v[108:111]
	v_mfma_f32_16x16x32_bf16 v[104:107], v[162:165], v[178:181], v[104:107]
	v_mfma_f32_16x16x32_bf16 v[92:95], v[154:157], v[186:189], v[92:95]
	v_mfma_f32_16x16x32_bf16 v[88:91], v[162:165], v[186:189], v[88:91]
	v_mfma_f32_16x16x32_bf16 v[76:79], v[154:157], v[194:197], v[76:79]
	v_mfma_f32_16x16x32_bf16 v[72:75], v[162:165], v[194:197], v[72:75]
	s_barrier
	s_add_i32 s16, s36, s27
	v_lshl_add_u64 v[142:143], s[20:21], 0, v[130:131]
	s_mov_b32 m0, s16
	ds_read_b128 v[198:201], v148
	ds_read_b128 v[202:205], v148 offset:1024
	ds_read_b128 v[206:209], v148 offset:2048
	ds_read_b128 v[210:213], v148 offset:3072
	global_load_lds_dwordx4 v[142:143], off
	v_lshl_add_u64 v[214:215], s[20:21], 0, v[128:129]
	s_add_i32 m0, s16, 0x2000
	s_nop 0
	global_load_lds_dwordx4 v[214:215], off
	s_barrier
	s_waitcnt lgkmcnt(0)
	v_mfma_f32_16x16x32_bf16 v[116:119], v[198:201], v[166:169], v[116:119]
	v_mfma_f32_16x16x32_bf16 v[112:115], v[206:209], v[166:169], v[112:115]
	v_mfma_f32_16x16x32_bf16 v[100:103], v[198:201], v[174:177], v[100:103]
	v_mfma_f32_16x16x32_bf16 v[96:99], v[206:209], v[174:177], v[96:99]
	v_mfma_f32_16x16x32_bf16 v[84:87], v[198:201], v[182:185], v[84:87]
	v_mfma_f32_16x16x32_bf16 v[80:83], v[206:209], v[182:185], v[80:83]
	v_mfma_f32_16x16x32_bf16 v[68:71], v[198:201], v[190:193], v[68:71]
	v_mfma_f32_16x16x32_bf16 v[64:67], v[206:209], v[190:193], v[64:67]
	v_mfma_f32_16x16x32_bf16 v[116:119], v[202:205], v[170:173], v[116:119]
	v_mfma_f32_16x16x32_bf16 v[112:115], v[210:213], v[170:173], v[112:115]
	v_mfma_f32_16x16x32_bf16 v[100:103], v[202:205], v[178:181], v[100:103]
	v_mfma_f32_16x16x32_bf16 v[96:99], v[210:213], v[178:181], v[96:99]
	v_mfma_f32_16x16x32_bf16 v[84:87], v[202:205], v[186:189], v[84:87]
	v_mfma_f32_16x16x32_bf16 v[80:83], v[210:213], v[186:189], v[80:83]
	v_mfma_f32_16x16x32_bf16 v[68:71], v[202:205], v[194:197], v[68:71]
	v_mfma_f32_16x16x32_bf16 v[64:67], v[210:213], v[194:197], v[64:67]
	s_mov_b32 m0, s28
	v_lshl_add_u64 v[216:217], s[22:23], 0, v[130:131]
	s_barrier
	ds_read_b128 v[166:169], v147 offset:16384
	ds_read_b128 v[170:173], v147 offset:17408
	ds_read_b128 v[174:177], v147 offset:18432
	ds_read_b128 v[178:181], v147 offset:19456
	ds_read_b128 v[182:185], v147 offset:20480
	ds_read_b128 v[186:189], v147 offset:21504
	ds_read_b128 v[190:193], v147 offset:22528
	ds_read_b128 v[194:197], v147 offset:23552
	global_load_lds_dwordx4 v[216:217], off
	v_lshl_add_u64 v[218:219], s[22:23], 0, v[128:129]
	s_mov_b32 m0, s29
	s_nop 0
	global_load_lds_dwordx4 v[218:219], off
	s_barrier
	s_waitcnt lgkmcnt(0)
	v_mfma_f32_16x16x32_bf16 v[60:63], v[150:153], v[166:169], v[60:63]
	v_mfma_f32_16x16x32_bf16 v[56:59], v[158:161], v[166:169], v[56:59]
	v_mfma_f32_16x16x32_bf16 v[44:47], v[150:153], v[174:177], v[44:47]
	v_mfma_f32_16x16x32_bf16 v[40:43], v[158:161], v[174:177], v[40:43]
	v_mfma_f32_16x16x32_bf16 v[28:31], v[150:153], v[182:185], v[28:31]
	v_mfma_f32_16x16x32_bf16 v[24:27], v[158:161], v[182:185], v[24:27]
	v_mfma_f32_16x16x32_bf16 v[12:15], v[150:153], v[190:193], v[12:15]
	v_mfma_f32_16x16x32_bf16 v[8:11], v[158:161], v[190:193], v[8:11]
	v_mfma_f32_16x16x32_bf16 v[60:63], v[154:157], v[170:173], v[60:63]
	v_mfma_f32_16x16x32_bf16 v[56:59], v[162:165], v[170:173], v[56:59]
	v_mfma_f32_16x16x32_bf16 v[44:47], v[154:157], v[178:181], v[44:47]
	v_mfma_f32_16x16x32_bf16 v[40:43], v[162:165], v[178:181], v[40:43]
	v_mfma_f32_16x16x32_bf16 v[28:31], v[154:157], v[186:189], v[28:31]
	v_mfma_f32_16x16x32_bf16 v[24:27], v[162:165], v[186:189], v[24:27]
	v_mfma_f32_16x16x32_bf16 v[12:15], v[154:157], v[194:197], v[12:15]
	v_mfma_f32_16x16x32_bf16 v[8:11], v[162:165], v[194:197], v[8:11]
	s_barrier
; #define STG(P, GB) do { const char* _gb = (GB); \
;     _Pragma("unroll") for (int _i = 0; _i < 2; ++_i) { \
;       __builtin_amdgcn_global_load_lds((const unsigned*)(_gb + voff[_i]), \
;         (LAS unsigned*)((LAS char*)(P) + ldsw + _i * 8192), 16, 0, 0); } } while (0)
; #define LDA(dst, b, h) _Pragma("unroll") for (int m = 0; m < 4; ++m) _Pragma("unroll") for (int k = 0; k < 2; ++k) \
;     dst[m][k] = *(const LAS bf16x8*)((LAS char*)SA(b, h) + aoff + m * 2048 + k * 1024)
; #define LDB(dst, b, h) _Pragma("unroll") for (int n = 0; n < 2; ++n) _Pragma("unroll") for (int k = 0; k < 2; ++k) \
;     dst[n][k] = *(const LAS bf16x8*)((LAS char*)SB(b, h) + boff + n * 2048 + k * 1024)
; #define MMA(ai, bj, At_, Bt_) do { __builtin_amdgcn_s_setprio(1); \
;     _Pragma("unroll") for (int m = 0; m < 4; ++m) _Pragma("unroll") for (int n = 0; n < 2; ++n) _Pragma("unroll") for (int k = 0; k < 2; ++k) \
;       acc[ai][bj][m][n] = __builtin_amdgcn_mfma_f32_16x16x32_bf16(Bt_[n][k], At_[m][k], acc[ai][bj][m][n], 0, 0, 0); \
;     __builtin_amdgcn_s_setprio(0); } while (0)
; #define WAIT_V(n) asm volatile("s_waitcnt vmcnt(" #n ")" ::: "memory")
; #define WAIT_L(n) asm volatile("s_waitcnt lgkmcnt(" #n ")" ::: "memory")
; #define BAR __builtin_amdgcn_s_barrier()
; #define SCHED __builtin_amdgcn_sched_barrier(0)
; __device__ __forceinline__ void gemm_phase(const bf16_t* __restrict__ A, const bf16_t* __restrict__ Bt, bf16_t* __restrict__ C, int M, int N, int K,
;                                            int ldc, const int EPI, char* smem, const int wid_u) {
;     ...
;       STG(SB(0, 1), b2 + hstep);
;       WAIT_V(6); BAR; MMA(1, 1, At, B1); BAR;
;       LDB(B0, 1, 0); SCHED; LDA(At, 1, 0); STG(SA(0, 1), a2 + hstep);
;       WAIT_L(8); BAR; WAIT_L(0); MMA(0, 0, At, B0); BAR; SCHED;
;       LDB(B1, 1, 1); STG(SB(1, 0), b3);
;       BAR; WAIT_L(0); MMA(0, 1, At, B1); BAR;
;       LDA(At, 1, 1); STG(SA(1, 0), a3);
	s_add_u32 s16, s20, 0x40000
	s_addc_u32 s17, s21, 0
	s_add_i32 s50, s37, s27
	v_lshl_add_u64 v[150:151], s[16:17], 0, v[130:131]
	s_mov_b32 m0, s50
	s_nop 0
	global_load_lds_dwordx4 v[150:151], off
	v_lshl_add_u64 v[150:151], s[16:17], 0, v[128:129]
	s_add_i32 m0, s50, 0x2000
	s_nop 0
	global_load_lds_dwordx4 v[150:151], off
	s_waitcnt vmcnt(6)
	s_barrier
	v_mfma_f32_16x16x32_bf16 v[52:55], v[198:201], v[166:169], v[52:55]
	v_mfma_f32_16x16x32_bf16 v[48:51], v[206:209], v[166:169], v[48:51]
	v_mfma_f32_16x16x32_bf16 v[36:39], v[198:201], v[174:177], v[36:39]
	v_mfma_f32_16x16x32_bf16 v[32:35], v[206:209], v[174:177], v[32:35]
	v_mfma_f32_16x16x32_bf16 v[20:23], v[198:201], v[182:185], v[20:23]
	v_mfma_f32_16x16x32_bf16 v[16:19], v[206:209], v[182:185], v[16:19]
	v_mfma_f32_16x16x32_bf16 v[4:7], v[198:201], v[190:193], v[4:7]
	v_mfma_f32_16x16x32_bf16 v[0:3], v[206:209], v[190:193], v[0:3]
	v_mfma_f32_16x16x32_bf16 v[52:55], v[202:205], v[170:173], v[52:55]
	v_mfma_f32_16x16x32_bf16 v[48:51], v[210:213], v[170:173], v[48:51]
	v_mfma_f32_16x16x32_bf16 v[36:39], v[202:205], v[178:181], v[36:39]
	v_mfma_f32_16x16x32_bf16 v[32:35], v[210:213], v[178:181], v[32:35]
	v_mfma_f32_16x16x32_bf16 v[20:23], v[202:205], v[186:189], v[20:23]
	v_mfma_f32_16x16x32_bf16 v[16:19], v[210:213], v[186:189], v[16:19]
	v_mfma_f32_16x16x32_bf16 v[4:7], v[202:205], v[194:197], v[4:7]
	v_mfma_f32_16x16x32_bf16 v[0:3], v[210:213], v[194:197], v[0:3]
	s_add_i32 s50, 0, 0x18000
	v_add_u32_e32 v149, s50, v145
	s_barrier
	ds_read_b128 v[150:153], v149
	ds_read_b128 v[154:157], v149 offset:1024
	ds_read_b128 v[158:161], v149 offset:2048
	ds_read_b128 v[162:165], v149 offset:3072
	s_add_u32 s16, s22, 0x40000
	s_addc_u32 s17, s23, 0
	s_mov_b32 m0, s30
	v_lshl_add_u64 v[198:199], s[16:17], 0, v[130:131]
	ds_read_b128 v[166:169], v147 offset:32768
	ds_read_b128 v[170:173], v147 offset:33792
	ds_read_b128 v[174:177], v147 offset:34816
	ds_read_b128 v[178:181], v147 offset:35840
	ds_read_b128 v[182:185], v147 offset:36864
	ds_read_b128 v[186:189], v147 offset:37888
	ds_read_b128 v[190:193], v147 offset:38912
	ds_read_b128 v[194:197], v147 offset:39936
	global_load_lds_dwordx4 v[198:199], off
	v_lshl_add_u64 v[198:199], s[16:17], 0, v[128:129]
	s_mov_b32 m0, s31
	s_nop 0
	global_load_lds_dwordx4 v[198:199], off
	s_waitcnt lgkmcnt(8)
	s_barrier
	s_waitcnt lgkmcnt(0)
	v_mfma_f32_16x16x32_bf16 v[124:127], v[150:153], v[166:169], v[124:127]
	v_mfma_f32_16x16x32_bf16 v[120:123], v[158:161], v[166:169], v[120:123]
	v_mfma_f32_16x16x32_bf16 v[108:111], v[150:153], v[174:177], v[108:111]
	v_mfma_f32_16x16x32_bf16 v[104:107], v[158:161], v[174:177], v[104:107]
	v_mfma_f32_16x16x32_bf16 v[92:95], v[150:153], v[182:185], v[92:95]
	v_mfma_f32_16x16x32_bf16 v[88:91], v[158:161], v[182:185], v[88:91]
	v_mfma_f32_16x16x32_bf16 v[76:79], v[150:153], v[190:193], v[76:79]
	v_mfma_f32_16x16x32_bf16 v[72:75], v[158:161], v[190:193], v[72:75]
	v_mfma_f32_16x16x32_bf16 v[124:127], v[154:157], v[170:173], v[124:127]
	v_mfma_f32_16x16x32_bf16 v[120:123], v[162:165], v[170:173], v[120:123]
	v_mfma_f32_16x16x32_bf16 v[108:111], v[154:157], v[178:181], v[108:111]
	v_mfma_f32_16x16x32_bf16 v[104:107], v[162:165], v[178:181], v[104:107]
	v_mfma_f32_16x16x32_bf16 v[92:95], v[154:157], v[186:189], v[92:95]
	v_mfma_f32_16x16x32_bf16 v[88:91], v[162:165], v[186:189], v[88:91]
	v_mfma_f32_16x16x32_bf16 v[76:79], v[154:157], v[194:197], v[76:79]
	v_mfma_f32_16x16x32_bf16 v[72:75], v[162:165], v[194:197], v[72:75]
	s_barrier
	s_add_i32 s22, 0, 0x1c000
	s_add_i32 s16, s50, s27
	v_add_u32_e32 v149, s22, v145
	v_lshl_add_u64 v[142:143], v[142:143], 0, s[6:7]
	s_mov_b32 m0, s16
	ds_read_b128 v[198:201], v149
	ds_read_b128 v[202:205], v149 offset:1024
	ds_read_b128 v[206:209], v149 offset:2048
	ds_read_b128 v[210:213], v149 offset:3072
	global_load_lds_dwordx4 v[142:143], off
	v_lshl_add_u64 v[142:143], v[214:215], 0, s[6:7]
	s_add_i32 m0, s16, 0x2000
	s_nop 0
	global_load_lds_dwordx4 v[142:143], off
	s_barrier
	s_waitcnt lgkmcnt(0)
	v_mfma_f32_16x16x32_bf16 v[116:119], v[198:201], v[166:169], v[116:119]
	v_mfma_f32_16x16x32_bf16 v[112:115], v[206:209], v[166:169], v[112:115]
	v_mfma_f32_16x16x32_bf16 v[100:103], v[198:201], v[174:177], v[100:103]
	v_mfma_f32_16x16x32_bf16 v[96:99], v[206:209], v[174:177], v[96:99]
	v_mfma_f32_16x16x32_bf16 v[84:87], v[198:201], v[182:185], v[84:87]
	v_mfma_f32_16x16x32_bf16 v[80:83], v[206:209], v[182:185], v[80:83]
	v_mfma_f32_16x16x32_bf16 v[68:71], v[198:201], v[190:193], v[68:71]
	v_mfma_f32_16x16x32_bf16 v[64:67], v[206:209], v[190:193], v[64:67]
	v_mfma_f32_16x16x32_bf16 v[116:119], v[202:205], v[170:173], v[116:119]
	v_mfma_f32_16x16x32_bf16 v[112:115], v[210:213], v[170:173], v[112:115]
	v_mfma_f32_16x16x32_bf16 v[100:103], v[202:205], v[178:181], v[100:103]
	v_mfma_f32_16x16x32_bf16 v[96:99], v[210:213], v[178:181], v[96:99]
	v_mfma_f32_16x16x32_bf16 v[84:87], v[202:205], v[186:189], v[84:87]
	v_mfma_f32_16x16x32_bf16 v[80:83], v[210:213], v[186:189], v[80:83]
	v_mfma_f32_16x16x32_bf16 v[68:71], v[202:205], v[194:197], v[68:71]
	v_mfma_f32_16x16x32_bf16 v[64:67], v[210:213], v[194:197], v[64:67]
	s_mov_b32 m0, s34
	v_lshl_add_u64 v[142:143], v[216:217], 0, s[6:7]
	s_barrier
	ds_read_b128 v[166:169], v147 offset:49152
	ds_read_b128 v[170:173], v147 offset:50176
	ds_read_b128 v[174:177], v147 offset:51200
	ds_read_b128 v[178:181], v147 offset:52224
	ds_read_b128 v[182:185], v147 offset:53248
	ds_read_b128 v[186:189], v147 offset:54272
	ds_read_b128 v[190:193], v147 offset:55296
	ds_read_b128 v[194:197], v147 offset:56320
	global_load_lds_dwordx4 v[142:143], off
	v_lshl_add_u64 v[142:143], v[218:219], 0, s[6:7]
	s_mov_b32 m0, s35
	s_nop 0
	global_load_lds_dwordx4 v[142:143], off
	s_barrier
; #define STG(P, GB) do { const char* _gb = (GB); \
;     _Pragma("unroll") for (int _i = 0; _i < 2; ++_i) { \
;       __builtin_amdgcn_global_load_lds((const unsigned*)(_gb + voff[_i]), \
;         (LAS unsigned*)((LAS char*)(P) + ldsw + _i * 8192), 16, 0, 0); } } while (0)
; #define MMA(ai, bj, At_, Bt_) do { __builtin_amdgcn_s_setprio(1); \
;     _Pragma("unroll") for (int m = 0; m < 4; ++m) _Pragma("unroll") for (int n = 0; n < 2; ++n) _Pragma("unroll") for (int k = 0; k < 2; ++k) \
;       acc[ai][bj][m][n] = __builtin_amdgcn_mfma_f32_16x16x32_bf16(Bt_[n][k], At_[m][k], acc[ai][bj][m][n], 0, 0, 0); \
;     __builtin_amdgcn_s_setprio(0); } while (0)
; #define WAIT_V(n) asm volatile("s_waitcnt vmcnt(" #n ")" ::: "memory")
; #define WAIT_L(n) asm volatile("s_waitcnt lgkmcnt(" #n ")" ::: "memory")
; #define BAR __builtin_amdgcn_s_barrier()
; #define SCHED __builtin_amdgcn_sched_barrier(0)
; __device__ __forceinline__ void gemm_phase(const bf16_t* __restrict__ A, const bf16_t* __restrict__ Bt, bf16_t* __restrict__ C, int M, int N, int K,
;                                            int ldc, const int EPI, char* smem, const int wid_u) {
;     ...
;       BAR; WAIT_L(0); MMA(1, 0, At, B0); BAR; SCHED;
;       STG(SB(1, 1), b3 + hstep);
;       WAIT_V(6); BAR; MMA(1, 1, At, B1); BAR;
;     }
;     ...
;             float o[8];
; #pragma unroll
;             for (int n = 0; n < 2; ++n) {
;               const f32x4 a = acc[ai][0][m][n], b = acc[ai][1][m][n];
; #pragma unroll
;               for (int j = 0; j < 4; ++j) o[n * 4 + j] = a[j] * __builtin_amdgcn_rcpf(1.f + __expf(-a[j])) * b[j];
;             }
;             *(uint4*)(C + row * ldc + (bcol >> 1) + wc * 32 + fq * 8) = pack8(o);
	s_waitcnt lgkmcnt(0)
	v_mfma_f32_16x16x32_bf16 v[60:63], v[150:153], v[166:169], v[60:63]
	v_mfma_f32_16x16x32_bf16 v[56:59], v[158:161], v[166:169], v[56:59]
	v_mfma_f32_16x16x32_bf16 v[44:47], v[150:153], v[174:177], v[44:47]
	v_mfma_f32_16x16x32_bf16 v[40:43], v[158:161], v[174:177], v[40:43]
	v_mfma_f32_16x16x32_bf16 v[28:31], v[150:153], v[182:185], v[28:31]
	v_mfma_f32_16x16x32_bf16 v[24:27], v[158:161], v[182:185], v[24:27]
	v_mfma_f32_16x16x32_bf16 v[12:15], v[150:153], v[190:193], v[12:15]
	v_mfma_f32_16x16x32_bf16 v[8:11], v[158:161], v[190:193], v[8:11]
	v_mfma_f32_16x16x32_bf16 v[60:63], v[154:157], v[170:173], v[60:63]
	v_mfma_f32_16x16x32_bf16 v[56:59], v[162:165], v[170:173], v[56:59]
	v_mfma_f32_16x16x32_bf16 v[44:47], v[154:157], v[178:181], v[44:47]
	v_mfma_f32_16x16x32_bf16 v[40:43], v[162:165], v[178:181], v[40:43]
	v_mfma_f32_16x16x32_bf16 v[28:31], v[154:157], v[186:189], v[28:31]
	v_mfma_f32_16x16x32_bf16 v[24:27], v[162:165], v[186:189], v[24:27]
	v_mfma_f32_16x16x32_bf16 v[12:15], v[154:157], v[194:197], v[12:15]
	v_mfma_f32_16x16x32_bf16 v[8:11], v[162:165], v[194:197], v[8:11]
	s_barrier
	s_add_u32 s16, s20, 0x40080
	s_addc_u32 s17, s21, 0
	s_add_i32 s20, s22, s27
	v_lshl_add_u64 v[142:143], s[16:17], 0, v[130:131]
	s_mov_b32 m0, s20
	s_nop 0
	global_load_lds_dwordx4 v[142:143], off
	v_lshl_add_u64 v[142:143], s[16:17], 0, v[128:129]
	s_add_i32 m0, s20, 0x2000
	s_nop 0
	global_load_lds_dwordx4 v[142:143], off
	s_waitcnt vmcnt(6)
	s_barrier
	v_mfma_f32_16x16x32_bf16 v[52:55], v[198:201], v[166:169], v[52:55]
	v_mfma_f32_16x16x32_bf16 v[48:51], v[206:209], v[166:169], v[48:51]
	v_mfma_f32_16x16x32_bf16 v[36:39], v[198:201], v[174:177], v[36:39]
	v_mfma_f32_16x16x32_bf16 v[32:35], v[206:209], v[174:177], v[32:35]
	v_mfma_f32_16x16x32_bf16 v[20:23], v[198:201], v[182:185], v[20:23]
	v_mfma_f32_16x16x32_bf16 v[16:19], v[206:209], v[182:185], v[16:19]
	v_mfma_f32_16x16x32_bf16 v[4:7], v[198:201], v[190:193], v[4:7]
	v_mfma_f32_16x16x32_bf16 v[0:3], v[206:209], v[190:193], v[0:3]
	v_mfma_f32_16x16x32_bf16 v[52:55], v[202:205], v[170:173], v[52:55]
	v_mfma_f32_16x16x32_bf16 v[48:51], v[210:213], v[170:173], v[48:51]
	v_mfma_f32_16x16x32_bf16 v[36:39], v[202:205], v[178:181], v[36:39]
	v_mfma_f32_16x16x32_bf16 v[32:35], v[210:213], v[178:181], v[32:35]
	v_mfma_f32_16x16x32_bf16 v[20:23], v[202:205], v[186:189], v[20:23]
	v_mfma_f32_16x16x32_bf16 v[16:19], v[210:213], v[186:189], v[16:19]
	v_mfma_f32_16x16x32_bf16 v[4:7], v[202:205], v[194:197], v[4:7]
	v_mfma_f32_16x16x32_bf16 v[0:3], v[210:213], v[194:197], v[0:3]
	s_add_i32 s49, s49, 2
	s_add_u32 s47, s47, 0x100
	s_addc_u32 s48, s48, 0
	s_cmp_gt_u32 s49, 13
	s_mov_b64 s[16:17], s[18:19]
	s_barrier
	s_cbranch_scc0 .LBB0_145
	v_mul_f32_e32 v142, 0xbfb8aa3b, v124
	v_exp_f32_e32 v142, v142
	v_mul_f32_e32 v143, 0xbfb8aa3b, v125
	v_exp_f32_e32 v143, v143
	s_lshl_b32 s16, s40, 8
	v_add_f32_e32 v142, 1.0, v142
	v_rcp_f32_e32 v150, v142
	v_add_f32_e32 v142, 1.0, v143
	v_rcp_f32_e32 v151, v142
	s_mov_b32 s17, s9
	v_lshl_add_u32 v149, s41, 8, v144
	v_lshl_add_u64 v[142:143], v[132:133], 0, s[16:17]
	v_pk_mul_f32 v[124:125], v[124:125], v[150:151]
	v_mul_f32_e32 v150, 0xbfb8aa3b, v126
	v_mul_f32_e32 v151, 0xbfb8aa3b, v127
	v_exp_f32_e32 v150, v150
	v_exp_f32_e32 v151, v151
	v_pk_mul_f32 v[116:117], v[124:125], v[116:117]
	s_and_b64 vcc, exec, s[2:3]
	v_add_f32_e32 v124, 1.0, v150
	v_add_f32_e32 v125, 1.0, v151
	v_mul_f32_e32 v150, 0xbfb8aa3b, v120
	v_mul_f32_e32 v151, 0xbfb8aa3b, v121
	v_rcp_f32_e32 v124, v124
	v_rcp_f32_e32 v125, v125
	v_exp_f32_e32 v150, v150
	v_exp_f32_e32 v151, v151
	s_mov_b32 s41, s8
	v_pk_mul_f32 v[124:125], v[126:127], v[124:125]
	v_add_f32_e32 v126, 1.0, v150
	v_add_f32_e32 v127, 1.0, v151
	v_mul_f32_e32 v150, 0xbfb8aa3b, v122
	v_mul_f32_e32 v151, 0xbfb8aa3b, v123
	v_exp_f32_e32 v150, v150
	v_exp_f32_e32 v151, v151
	v_rcp_f32_e32 v126, v126
	v_rcp_f32_e32 v127, v127
	v_add_f32_e32 v150, 1.0, v150
	v_add_f32_e32 v151, 1.0, v151
	v_rcp_f32_e32 v150, v150
	v_rcp_f32_e32 v151, v151
	v_pk_mul_f32 v[120:121], v[120:121], v[126:127]
	v_pk_mul_f32 v[118:119], v[124:125], v[118:119]
	v_pk_mul_f32 v[120:121], v[120:121], v[112:113]
	v_pk_mul_f32 v[112:113], v[122:123], v[150:151]
	s_mov_b32 s40, s10
	v_pk_mul_f32 v[122:123], v[112:113], v[114:115]
	v_mul_f32_e32 v115, 0xbfb8aa3b, v108
	v_cvt_pk_bf16_f32 v112, v116, v117
	v_exp_f32_e32 v116, v115
	v_mul_f32_e32 v115, 0xbfb8aa3b, v109
	v_exp_f32_e32 v117, v115
	v_cvt_pk_bf16_f32 v113, v118, v119
	v_cvt_pk_bf16_f32 v114, v120, v121
	v_cvt_pk_bf16_f32 v115, v122, v123
	v_add_f32_e32 v116, 1.0, v116
	v_add_f32_e32 v117, 1.0, v117
	v_mad_i64_i32 v[118:119], s[16:17], v149, s38, v[142:143]
	v_rcp_f32_e32 v116, v116
	v_rcp_f32_e32 v117, v117
	global_store_dwordx4 v[118:119], v[112:115], off
	s_mov_b64 s[18:19], s[14:15]
	v_pk_mul_f32 v[108:109], v[108:109], v[116:117]
	v_mul_f32_e32 v112, 0xbfb8aa3b, v110
	v_mul_f32_e32 v113, 0xbfb8aa3b, v111
	v_exp_f32_e32 v112, v112
	v_exp_f32_e32 v113, v113
	v_pk_mul_f32 v[100:101], v[108:109], v[100:101]
	v_or_b32_e32 v114, 16, v149
	v_add_f32_e32 v108, 1.0, v112
	v_add_f32_e32 v109, 1.0, v113
	v_mul_f32_e32 v112, 0xbfb8aa3b, v104
	v_mul_f32_e32 v113, 0xbfb8aa3b, v105
	v_rcp_f32_e32 v108, v108
	v_rcp_f32_e32 v109, v109
	v_exp_f32_e32 v112, v112
	v_exp_f32_e32 v113, v113
	v_pk_mul_f32 v[108:109], v[110:111], v[108:109]
	v_add_f32_e32 v110, 1.0, v112
	v_add_f32_e32 v111, 1.0, v113
	v_mul_f32_e32 v112, 0xbfb8aa3b, v106
	v_mul_f32_e32 v113, 0xbfb8aa3b, v107
	v_exp_f32_e32 v112, v112
	v_exp_f32_e32 v113, v113
	v_rcp_f32_e32 v110, v110
	v_rcp_f32_e32 v111, v111
	v_add_f32_e32 v112, 1.0, v112
; __device__ __forceinline__ void gemm_phase(const bf16_t* __restrict__ A, const bf16_t* __restrict__ Bt, bf16_t* __restrict__ C, int M, int N, int K,
;                                            int ldc, const int EPI, char* smem, const int wid_u) {
;     ...
;             float o[8];
; #pragma unroll
;             for (int n = 0; n < 2; ++n) {
;               const f32x4 a = acc[ai][0][m][n], b = acc[ai][1][m][n];
; #pragma unroll
;               for (int j = 0; j < 4; ++j) o[n * 4 + j] = a[j] * __builtin_amdgcn_rcpf(1.f + __expf(-a[j])) * b[j];
;             }
;             *(uint4*)(C + row * ldc + (bcol >> 1) + wc * 32 + fq * 8) = pack8(o);
	v_add_f32_e32 v113, 1.0, v113
	v_rcp_f32_e32 v112, v112
	v_rcp_f32_e32 v113, v113
	v_pk_mul_f32 v[104:105], v[104:105], v[110:111]
	v_pk_mul_f32 v[102:103], v[108:109], v[102:103]
	v_pk_mul_f32 v[104:105], v[104:105], v[96:97]
	v_pk_mul_f32 v[96:97], v[106:107], v[112:113]
	s_nop 0
	v_pk_mul_f32 v[106:107], v[96:97], v[98:99]
	v_mul_f32_e32 v99, 0xbfb8aa3b, v92
	v_cvt_pk_bf16_f32 v96, v100, v101
	v_exp_f32_e32 v100, v99
	v_mul_f32_e32 v99, 0xbfb8aa3b, v93
	v_exp_f32_e32 v101, v99
	v_cvt_pk_bf16_f32 v97, v102, v103
	v_cvt_pk_bf16_f32 v98, v104, v105
	v_cvt_pk_bf16_f32 v99, v106, v107
	v_add_f32_e32 v100, 1.0, v100
	v_add_f32_e32 v101, 1.0, v101
	v_mad_i64_i32 v[102:103], s[16:17], v114, s38, v[142:143]
	v_rcp_f32_e32 v100, v100
	v_rcp_f32_e32 v101, v101
	global_store_dwordx4 v[102:103], v[96:99], off
	v_pk_mul_f32 v[92:93], v[92:93], v[100:101]
	s_nop 0
	v_mul_f32_e32 v96, 0xbfb8aa3b, v94
	v_mul_f32_e32 v97, 0xbfb8aa3b, v95
	v_exp_f32_e32 v96, v96
	v_exp_f32_e32 v97, v97
	v_pk_mul_f32 v[84:85], v[92:93], v[84:85]
	v_or_b32_e32 v98, 32, v149
	v_add_f32_e32 v92, 1.0, v96
	v_add_f32_e32 v93, 1.0, v97
	v_mul_f32_e32 v96, 0xbfb8aa3b, v88
	v_mul_f32_e32 v97, 0xbfb8aa3b, v89
	v_rcp_f32_e32 v92, v92
	v_rcp_f32_e32 v93, v93
	v_exp_f32_e32 v96, v96
	v_exp_f32_e32 v97, v97
	v_pk_mul_f32 v[92:93], v[94:95], v[92:93]
	v_add_f32_e32 v94, 1.0, v96
	v_add_f32_e32 v95, 1.0, v97
	v_mul_f32_e32 v96, 0xbfb8aa3b, v90
	v_mul_f32_e32 v97, 0xbfb8aa3b, v91
	v_exp_f32_e32 v96, v96
	v_exp_f32_e32 v97, v97
	v_rcp_f32_e32 v94, v94
	v_rcp_f32_e32 v95, v95
	v_add_f32_e32 v96, 1.0, v96
	v_add_f32_e32 v97, 1.0, v97
	v_rcp_f32_e32 v96, v96
	v_rcp_f32_e32 v97, v97
	v_pk_mul_f32 v[88:89], v[88:89], v[94:95]
	v_pk_mul_f32 v[86:87], v[92:93], v[86:87]
	v_pk_mul_f32 v[88:89], v[88:89], v[80:81]
	v_pk_mul_f32 v[80:81], v[90:91], v[96:97]
	s_nop 0
	v_pk_mul_f32 v[90:91], v[80:81], v[82:83]
	v_mul_f32_e32 v83, 0xbfb8aa3b, v76
	v_cvt_pk_bf16_f32 v80, v84, v85
	v_exp_f32_e32 v84, v83
	v_mul_f32_e32 v83, 0xbfb8aa3b, v77
	v_exp_f32_e32 v85, v83
	v_cvt_pk_bf16_f32 v81, v86, v87
	v_cvt_pk_bf16_f32 v82, v88, v89
	v_cvt_pk_bf16_f32 v83, v90, v91
	v_add_f32_e32 v84, 1.0, v84
	v_add_f32_e32 v85, 1.0, v85
	v_mad_i64_i32 v[86:87], s[16:17], v98, s38, v[142:143]
	v_rcp_f32_e32 v84, v84
	v_rcp_f32_e32 v85, v85
	global_store_dwordx4 v[86:87], v[80:83], off
	v_pk_mul_f32 v[76:77], v[76:77], v[84:85]
	s_nop 0
	v_mul_f32_e32 v80, 0xbfb8aa3b, v78
	v_mul_f32_e32 v81, 0xbfb8aa3b, v79
	v_exp_f32_e32 v80, v80
	v_exp_f32_e32 v81, v81
	v_pk_mul_f32 v[68:69], v[76:77], v[68:69]
	v_or_b32_e32 v82, 48, v149
	v_add_f32_e32 v76, 1.0, v80
	v_add_f32_e32 v77, 1.0, v81
	v_mul_f32_e32 v80, 0xbfb8aa3b, v72
	v_mul_f32_e32 v81, 0xbfb8aa3b, v73
	v_rcp_f32_e32 v76, v76
	v_rcp_f32_e32 v77, v77
	v_exp_f32_e32 v80, v80
	v_exp_f32_e32 v81, v81
	v_pk_mul_f32 v[76:77], v[78:79], v[76:77]
	v_add_f32_e32 v78, 1.0, v80
	v_add_f32_e32 v79, 1.0, v81
	v_mul_f32_e32 v80, 0xbfb8aa3b, v74
	v_mul_f32_e32 v81, 0xbfb8aa3b, v75
	v_exp_f32_e32 v80, v80
	v_exp_f32_e32 v81, v81
	v_rcp_f32_e32 v78, v78
	v_rcp_f32_e32 v79, v79
	v_add_f32_e32 v80, 1.0, v80
	v_add_f32_e32 v81, 1.0, v81
	v_rcp_f32_e32 v80, v80
	v_rcp_f32_e32 v81, v81
	v_pk_mul_f32 v[72:73], v[72:73], v[78:79]
	v_pk_mul_f32 v[70:71], v[76:77], v[70:71]
	v_pk_mul_f32 v[72:73], v[72:73], v[64:65]
	v_pk_mul_f32 v[64:65], v[74:75], v[80:81]
	s_nop 0
	v_pk_mul_f32 v[74:75], v[64:65], v[66:67]
	v_mul_f32_e32 v67, 0xbfb8aa3b, v60
	v_cvt_pk_bf16_f32 v64, v68, v69
	v_exp_f32_e32 v68, v67
	v_mul_f32_e32 v67, 0xbfb8aa3b, v61
	v_exp_f32_e32 v69, v67
	v_cvt_pk_bf16_f32 v65, v70, v71
	v_cvt_pk_bf16_f32 v66, v72, v73
	v_cvt_pk_bf16_f32 v67, v74, v75
	v_add_f32_e32 v68, 1.0, v68
	v_add_f32_e32 v69, 1.0, v69
	v_mad_i64_i32 v[70:71], s[16:17], v82, s38, v[142:143]
	v_rcp_f32_e32 v68, v68
	v_rcp_f32_e32 v69, v69
	global_store_dwordx4 v[70:71], v[64:67], off
	v_pk_mul_f32 v[60:61], v[60:61], v[68:69]
	s_nop 0
	v_mul_f32_e32 v64, 0xbfb8aa3b, v62
	v_mul_f32_e32 v65, 0xbfb8aa3b, v63
	v_exp_f32_e32 v64, v64
	v_exp_f32_e32 v65, v65
	v_pk_mul_f32 v[52:53], v[60:61], v[52:53]
	v_add_u32_e32 v66, 0x80, v149
	v_add_f32_e32 v60, 1.0, v64
	v_add_f32_e32 v61, 1.0, v65
	v_mul_f32_e32 v64, 0xbfb8aa3b, v56
	v_mul_f32_e32 v65, 0xbfb8aa3b, v57
	v_rcp_f32_e32 v60, v60
	v_rcp_f32_e32 v61, v61
	v_exp_f32_e32 v64, v64
	v_exp_f32_e32 v65, v65
	v_pk_mul_f32 v[60:61], v[62:63], v[60:61]
	v_add_f32_e32 v62, 1.0, v64
	v_add_f32_e32 v63, 1.0, v65
	v_mul_f32_e32 v64, 0xbfb8aa3b, v58
	v_mul_f32_e32 v65, 0xbfb8aa3b, v59
	v_exp_f32_e32 v64, v64
	v_exp_f32_e32 v65, v65
	v_rcp_f32_e32 v62, v62
	v_rcp_f32_e32 v63, v63
	v_add_f32_e32 v64, 1.0, v64
	v_add_f32_e32 v65, 1.0, v65
	v_rcp_f32_e32 v64, v64
	v_rcp_f32_e32 v65, v65
	v_pk_mul_f32 v[56:57], v[56:57], v[62:63]
	v_pk_mul_f32 v[54:55], v[60:61], v[54:55]
	v_pk_mul_f32 v[56:57], v[56:57], v[48:49]
	v_pk_mul_f32 v[48:49], v[58:59], v[64:65]
	s_nop 0
	v_pk_mul_f32 v[58:59], v[48:49], v[50:51]
; #define WAIT_V(n) asm volatile("s_waitcnt vmcnt(" #n ")" ::: "memory")
; #define BAR __builtin_amdgcn_s_barrier()
; __device__ __forceinline__ void gemm_phase(const bf16_t* __restrict__ A, const bf16_t* __restrict__ Bt, bf16_t* __restrict__ C, int M, int N, int K,
;                                            int ldc, const int EPI, char* smem, const int wid_u) {
;     ...
;             float o[8];
; #pragma unroll
;             for (int n = 0; n < 2; ++n) {
;               const f32x4 a = acc[ai][0][m][n], b = acc[ai][1][m][n];
; #pragma unroll
;               for (int j = 0; j < 4; ++j) o[n * 4 + j] = a[j] * __builtin_amdgcn_rcpf(1.f + __expf(-a[j])) * b[j];
;             }
;             *(uint4*)(C + row * ldc + (bcol >> 1) + wc * 32 + fq * 8) = pack8(o);
;     ...
;     if (!has_next) break;
; #pragma unroll
;     for (int a = 0; a < 2; ++a)
; #pragma unroll
;       for (int b = 0; b < 2; ++b)
; #pragma unroll
;         for (int m = 0; m < 4; ++m)
; #pragma unroll
;           for (int n = 0; n < 2; ++n) acc[a][b][m][n] = (f32x4){0.f, 0.f, 0.f, 0.f};
;     pm = npm; pn = npn; cA = nA; cB = nB; ++ui;
;   }
;   WAIT_V(0);
;   if (wr == 0) BAR;
;   BAR;
	v_mul_f32_e32 v51, 0xbfb8aa3b, v44
	v_cvt_pk_bf16_f32 v48, v52, v53
	v_exp_f32_e32 v52, v51
	v_mul_f32_e32 v51, 0xbfb8aa3b, v45
	v_exp_f32_e32 v53, v51
	v_cvt_pk_bf16_f32 v49, v54, v55
	v_cvt_pk_bf16_f32 v50, v56, v57
	v_cvt_pk_bf16_f32 v51, v58, v59
	v_add_f32_e32 v52, 1.0, v52
	v_add_f32_e32 v53, 1.0, v53
	v_mad_i64_i32 v[54:55], s[16:17], v66, s38, v[142:143]
	v_rcp_f32_e32 v52, v52
	v_rcp_f32_e32 v53, v53
	global_store_dwordx4 v[54:55], v[48:51], off
	v_pk_mul_f32 v[44:45], v[44:45], v[52:53]
	s_nop 0
	v_mul_f32_e32 v48, 0xbfb8aa3b, v46
	v_mul_f32_e32 v49, 0xbfb8aa3b, v47
	v_exp_f32_e32 v48, v48
	v_exp_f32_e32 v49, v49
	v_pk_mul_f32 v[36:37], v[44:45], v[36:37]
	v_add_u32_e32 v50, 0x90, v149
	v_add_f32_e32 v44, 1.0, v48
	v_add_f32_e32 v45, 1.0, v49
	v_mul_f32_e32 v48, 0xbfb8aa3b, v40
	v_mul_f32_e32 v49, 0xbfb8aa3b, v41
	v_rcp_f32_e32 v44, v44
	v_rcp_f32_e32 v45, v45
	v_exp_f32_e32 v48, v48
	v_exp_f32_e32 v49, v49
	v_pk_mul_f32 v[44:45], v[46:47], v[44:45]
	v_add_f32_e32 v46, 1.0, v48
	v_add_f32_e32 v47, 1.0, v49
	v_mul_f32_e32 v48, 0xbfb8aa3b, v42
	v_mul_f32_e32 v49, 0xbfb8aa3b, v43
	v_exp_f32_e32 v48, v48
	v_exp_f32_e32 v49, v49
	v_rcp_f32_e32 v46, v46
	v_rcp_f32_e32 v47, v47
	v_add_f32_e32 v48, 1.0, v48
	v_add_f32_e32 v49, 1.0, v49
	v_rcp_f32_e32 v48, v48
	v_rcp_f32_e32 v49, v49
	v_pk_mul_f32 v[40:41], v[40:41], v[46:47]
	v_pk_mul_f32 v[38:39], v[44:45], v[38:39]
	v_pk_mul_f32 v[40:41], v[40:41], v[32:33]
	v_pk_mul_f32 v[32:33], v[42:43], v[48:49]
	s_nop 0
	v_pk_mul_f32 v[42:43], v[32:33], v[34:35]
	v_mul_f32_e32 v35, 0xbfb8aa3b, v28
	v_cvt_pk_bf16_f32 v32, v36, v37
	v_exp_f32_e32 v36, v35
	v_mul_f32_e32 v35, 0xbfb8aa3b, v29
	v_exp_f32_e32 v37, v35
	v_cvt_pk_bf16_f32 v33, v38, v39
	v_cvt_pk_bf16_f32 v34, v40, v41
	v_cvt_pk_bf16_f32 v35, v42, v43
	v_add_f32_e32 v36, 1.0, v36
	v_add_f32_e32 v37, 1.0, v37
	v_mad_i64_i32 v[38:39], s[16:17], v50, s38, v[142:143]
	v_rcp_f32_e32 v36, v36
	v_rcp_f32_e32 v37, v37
	global_store_dwordx4 v[38:39], v[32:35], off
	v_pk_mul_f32 v[28:29], v[28:29], v[36:37]
	s_nop 0
	v_mul_f32_e32 v32, 0xbfb8aa3b, v30
	v_mul_f32_e32 v33, 0xbfb8aa3b, v31
	v_exp_f32_e32 v32, v32
	v_exp_f32_e32 v33, v33
	v_pk_mul_f32 v[20:21], v[28:29], v[20:21]
	v_add_u32_e32 v34, 0xa0, v149
	v_add_f32_e32 v28, 1.0, v32
	v_add_f32_e32 v29, 1.0, v33
	v_mul_f32_e32 v32, 0xbfb8aa3b, v24
	v_mul_f32_e32 v33, 0xbfb8aa3b, v25
	v_rcp_f32_e32 v28, v28
	v_rcp_f32_e32 v29, v29
	v_exp_f32_e32 v32, v32
	v_exp_f32_e32 v33, v33
	v_pk_mul_f32 v[28:29], v[30:31], v[28:29]
	v_add_f32_e32 v30, 1.0, v32
	v_add_f32_e32 v31, 1.0, v33
	v_mul_f32_e32 v32, 0xbfb8aa3b, v26
	v_mul_f32_e32 v33, 0xbfb8aa3b, v27
	v_exp_f32_e32 v32, v32
	v_exp_f32_e32 v33, v33
	v_rcp_f32_e32 v30, v30
	v_rcp_f32_e32 v31, v31
	v_add_f32_e32 v32, 1.0, v32
	v_add_f32_e32 v33, 1.0, v33
	v_rcp_f32_e32 v32, v32
	v_rcp_f32_e32 v33, v33
	v_pk_mul_f32 v[24:25], v[24:25], v[30:31]
	v_pk_mul_f32 v[22:23], v[28:29], v[22:23]
	v_pk_mul_f32 v[24:25], v[24:25], v[16:17]
	v_pk_mul_f32 v[16:17], v[26:27], v[32:33]
	s_nop 0
	v_pk_mul_f32 v[26:27], v[16:17], v[18:19]
	v_mul_f32_e32 v19, 0xbfb8aa3b, v12
	v_cvt_pk_bf16_f32 v16, v20, v21
	v_exp_f32_e32 v20, v19
	v_mul_f32_e32 v19, 0xbfb8aa3b, v13
	v_exp_f32_e32 v21, v19
	v_cvt_pk_bf16_f32 v17, v22, v23
	v_cvt_pk_bf16_f32 v18, v24, v25
	v_cvt_pk_bf16_f32 v19, v26, v27
	v_add_f32_e32 v20, 1.0, v20
	v_add_f32_e32 v21, 1.0, v21
	v_mad_i64_i32 v[22:23], s[16:17], v34, s38, v[142:143]
	v_rcp_f32_e32 v20, v20
	v_rcp_f32_e32 v21, v21
	global_store_dwordx4 v[22:23], v[16:19], off
	v_pk_mul_f32 v[12:13], v[12:13], v[20:21]
	s_nop 0
	v_mul_f32_e32 v16, 0xbfb8aa3b, v14
	v_mul_f32_e32 v17, 0xbfb8aa3b, v15
	v_exp_f32_e32 v16, v16
	v_exp_f32_e32 v17, v17
	v_pk_mul_f32 v[4:5], v[12:13], v[4:5]
	v_add_u32_e32 v18, 0xb0, v149
	v_add_f32_e32 v12, 1.0, v16
	v_add_f32_e32 v13, 1.0, v17
	v_mul_f32_e32 v16, 0xbfb8aa3b, v8
	v_mul_f32_e32 v17, 0xbfb8aa3b, v9
	v_rcp_f32_e32 v12, v12
	v_rcp_f32_e32 v13, v13
	v_exp_f32_e32 v16, v16
	v_exp_f32_e32 v17, v17
	v_pk_mul_f32 v[12:13], v[14:15], v[12:13]
	v_add_f32_e32 v14, 1.0, v16
	v_add_f32_e32 v15, 1.0, v17
	v_mul_f32_e32 v16, 0xbfb8aa3b, v10
	v_mul_f32_e32 v17, 0xbfb8aa3b, v11
	v_exp_f32_e32 v16, v16
	v_exp_f32_e32 v17, v17
	v_rcp_f32_e32 v14, v14
	v_rcp_f32_e32 v15, v15
	v_add_f32_e32 v16, 1.0, v16
	v_add_f32_e32 v17, 1.0, v17
	v_rcp_f32_e32 v16, v16
	v_rcp_f32_e32 v17, v17
	v_pk_mul_f32 v[8:9], v[8:9], v[14:15]
	v_pk_mul_f32 v[6:7], v[12:13], v[6:7]
	v_pk_mul_f32 v[8:9], v[8:9], v[0:1]
	v_pk_mul_f32 v[0:1], v[10:11], v[16:17]
	s_nop 0
	v_pk_mul_f32 v[10:11], v[0:1], v[2:3]
	v_cvt_pk_bf16_f32 v0, v4, v5
	v_mad_i64_i32 v[4:5], s[16:17], v18, s38, v[142:143]
	v_cvt_pk_bf16_f32 v1, v6, v7
	v_cvt_pk_bf16_f32 v2, v8, v9
	v_cvt_pk_bf16_f32 v3, v10, v11
	s_mov_b64 s[16:17], s[12:13]
	global_store_dwordx4 v[4:5], v[0:3], off
	s_cbranch_vccz .LBB0_142
	s_waitcnt vmcnt(0)
	s_cmpk_gt_u32 s24, 0xff
	s_cbranch_scc1 .LBB0_149
	s_barrier

; #define STG(P, GB) do { const char* _gb = (GB); \
;     _Pragma("unroll") for (int _i = 0; _i < 2; ++_i) { \
;       __builtin_amdgcn_global_load_lds((const unsigned*)(_gb + voff[_i]), \
;         (LAS unsigned*)((LAS char*)(P) + ldsw + _i * 8192), 16, 0, 0); } } while (0)
; #define LDA(dst, b, h) _Pragma("unroll") for (int m = 0; m < 4; ++m) _Pragma("unroll") for (int k = 0; k < 2; ++k) \
;     dst[m][k] = *(const LAS bf16x8*)((LAS char*)SA(b, h) + aoff + m * 2048 + k * 1024)
; #define LDB(dst, b, h) _Pragma("unroll") for (int n = 0; n < 2; ++n) _Pragma("unroll") for (int k = 0; k < 2; ++k) \
;     dst[n][k] = *(const LAS bf16x8*)((LAS char*)SB(b, h) + boff + n * 2048 + k * 1024)
; #define MMA(ai, bj, At_, Bt_) do { __builtin_amdgcn_s_setprio(1); \
;     _Pragma("unroll") for (int m = 0; m < 4; ++m) _Pragma("unroll") for (int n = 0; n < 2; ++n) _Pragma("unroll") for (int k = 0; k < 2; ++k) \
;       acc[ai][bj][m][n] = __builtin_amdgcn_mfma_f32_16x16x32_bf16(Bt_[n][k], At_[m][k], acc[ai][bj][m][n], 0, 0, 0); \
;     __builtin_amdgcn_s_setprio(0); } while (0)
; #define WAIT_V(n) asm volatile("s_waitcnt vmcnt(" #n ")" ::: "memory")
; #define WAIT_L(n) asm volatile("s_waitcnt lgkmcnt(" #n ")" ::: "memory")
; #define BAR __builtin_amdgcn_s_barrier()
; #define SCHED __builtin_amdgcn_sched_barrier(0)
; __device__ __forceinline__ void gemm_phase(const bf16_t* __restrict__ A, const bf16_t* __restrict__ Bt, bf16_t* __restrict__ C, int M, int N, int K,
;                                            int ldc, const int EPI, char* smem, const int wid_u) {
;     ...
;       const bool last = (t == nt - 2);
;       const char* a1 = cA + (size_t)(t + 1) * kstep;
;       const char* a2 = last ? nA : cA + (size_t)(t + 2) * kstep;
;       const char* b2 = last ? nB : cB + (size_t)(t + 2) * kstep;
;       const char* a3 = a2 + kstep;
;       const char* b3 = b2 + kstep;
;       LDB(B0, 0, 0); SCHED; LDA(At, 0, 0); STG(SA(1, 1), a1 + hstep);
;       WAIT_L(8); BAR; WAIT_L(0); MMA(0, 0, At, B0); BAR; SCHED;
;       LDB(B1, 0, 1); STG(SB(0, 0), b2);
;       BAR; WAIT_L(0); MMA(0, 1, At, B1); BAR;
;       LDA(At, 0, 1); STG(SA(0, 0), a2);
;       BAR; WAIT_L(0); MMA(1, 0, At, B0); BAR; SCHED;
;       STG(SB(0, 1), b2 + hstep);
;       WAIT_V(6); BAR; MMA(1, 1, At, B1); BAR;
.LBB0_213:
	ds_read_b128 v[148:151], v143
	ds_read_b128 v[152:155], v143 offset:1024
	ds_read_b128 v[156:159], v143 offset:2048
	ds_read_b128 v[160:163], v143 offset:3072
	s_add_u32 s16, s14, 0x100
	s_addc_u32 s17, s15, 0
	s_cmp_eq_u32 s53, 40
	s_cselect_b32 s21, s5, s17
	s_cselect_b32 s20, s4, s16
	s_cselect_b32 s19, s7, s52
	s_cselect_b32 s18, s6, s51
	s_mov_b32 m0, s36
	v_lshl_add_u64 v[196:197], s[14:15], 0, v[136:137]
	ds_read_b128 v[164:167], v144
	ds_read_b128 v[168:171], v144 offset:1024
	ds_read_b128 v[172:175], v144 offset:2048
	ds_read_b128 v[176:179], v144 offset:3072
	ds_read_b128 v[180:183], v144 offset:4096
	ds_read_b128 v[184:187], v144 offset:5120
	ds_read_b128 v[188:191], v144 offset:6144
	ds_read_b128 v[192:195], v144 offset:7168
	global_load_lds_dwordx4 v[196:197], off
	v_lshl_add_u64 v[196:197], s[14:15], 0, v[134:135]
	s_mov_b32 m0, s37
	s_nop 0
	global_load_lds_dwordx4 v[196:197], off
	s_waitcnt lgkmcnt(8)
	s_barrier
	s_waitcnt lgkmcnt(0)
	v_mfma_f32_16x16x32_bf16 v[124:127], v[148:151], v[164:167], v[124:127]
	v_mfma_f32_16x16x32_bf16 v[120:123], v[156:159], v[164:167], v[120:123]
	v_mfma_f32_16x16x32_bf16 v[116:119], v[148:151], v[172:175], v[116:119]
	v_mfma_f32_16x16x32_bf16 v[112:115], v[156:159], v[172:175], v[112:115]
	v_mfma_f32_16x16x32_bf16 v[100:103], v[148:151], v[180:183], v[100:103]
	v_mfma_f32_16x16x32_bf16 v[96:99], v[156:159], v[180:183], v[96:99]
	v_mfma_f32_16x16x32_bf16 v[84:87], v[148:151], v[188:191], v[84:87]
	v_mfma_f32_16x16x32_bf16 v[80:83], v[156:159], v[188:191], v[80:83]
	v_mfma_f32_16x16x32_bf16 v[124:127], v[152:155], v[168:171], v[124:127]
	v_mfma_f32_16x16x32_bf16 v[120:123], v[160:163], v[168:171], v[120:123]
	v_mfma_f32_16x16x32_bf16 v[116:119], v[152:155], v[176:179], v[116:119]
	v_mfma_f32_16x16x32_bf16 v[112:115], v[160:163], v[176:179], v[112:115]
	v_mfma_f32_16x16x32_bf16 v[100:103], v[152:155], v[184:187], v[100:103]
	v_mfma_f32_16x16x32_bf16 v[96:99], v[160:163], v[184:187], v[96:99]
	v_mfma_f32_16x16x32_bf16 v[84:87], v[152:155], v[192:195], v[84:87]
	v_mfma_f32_16x16x32_bf16 v[80:83], v[160:163], v[192:195], v[80:83]
	s_barrier
	s_mov_b32 m0, s38
	v_lshl_add_u64 v[212:213], s[18:19], 0, v[130:131]
	ds_read_b128 v[196:199], v145
	ds_read_b128 v[200:203], v145 offset:1024
	ds_read_b128 v[204:207], v145 offset:2048
	ds_read_b128 v[208:211], v145 offset:3072
	global_load_lds_dwordx4 v[212:213], off
	v_lshl_add_u64 v[214:215], s[18:19], 0, v[128:129]
	s_mov_b32 m0, s39
	s_nop 0
	global_load_lds_dwordx4 v[214:215], off
	s_barrier
	s_waitcnt lgkmcnt(0)
	v_mfma_f32_16x16x32_bf16 v[108:111], v[196:199], v[164:167], v[108:111]
	v_mfma_f32_16x16x32_bf16 v[104:107], v[204:207], v[164:167], v[104:107]
	v_mfma_f32_16x16x32_bf16 v[92:95], v[196:199], v[172:175], v[92:95]
	v_mfma_f32_16x16x32_bf16 v[88:91], v[204:207], v[172:175], v[88:91]
	v_mfma_f32_16x16x32_bf16 v[76:79], v[196:199], v[180:183], v[76:79]
	v_mfma_f32_16x16x32_bf16 v[72:75], v[204:207], v[180:183], v[72:75]
	v_mfma_f32_16x16x32_bf16 v[68:71], v[196:199], v[188:191], v[68:71]
	v_mfma_f32_16x16x32_bf16 v[64:67], v[204:207], v[188:191], v[64:67]
	v_mfma_f32_16x16x32_bf16 v[108:111], v[200:203], v[168:171], v[108:111]
	v_mfma_f32_16x16x32_bf16 v[104:107], v[208:211], v[168:171], v[104:107]
	v_mfma_f32_16x16x32_bf16 v[92:95], v[200:203], v[176:179], v[92:95]
	v_mfma_f32_16x16x32_bf16 v[88:91], v[208:211], v[176:179], v[88:91]
	v_mfma_f32_16x16x32_bf16 v[76:79], v[200:203], v[184:187], v[76:79]
	v_mfma_f32_16x16x32_bf16 v[72:75], v[208:211], v[184:187], v[72:75]
	v_mfma_f32_16x16x32_bf16 v[68:71], v[200:203], v[192:195], v[68:71]
	v_mfma_f32_16x16x32_bf16 v[64:67], v[208:211], v[192:195], v[64:67]
	s_mov_b32 m0, s28
	v_lshl_add_u64 v[216:217], s[20:21], 0, v[130:131]
	s_barrier
	ds_read_b128 v[164:167], v144 offset:16384
	ds_read_b128 v[168:171], v144 offset:17408
	ds_read_b128 v[172:175], v144 offset:18432
	ds_read_b128 v[176:179], v144 offset:19456
	ds_read_b128 v[180:183], v144 offset:20480
	ds_read_b128 v[184:187], v144 offset:21504
	ds_read_b128 v[188:191], v144 offset:22528
	ds_read_b128 v[192:195], v144 offset:23552
	global_load_lds_dwordx4 v[216:217], off
	v_lshl_add_u64 v[218:219], s[20:21], 0, v[128:129]
	s_mov_b32 m0, s29
	s_nop 0
	global_load_lds_dwordx4 v[218:219], off
	s_barrier
	s_waitcnt lgkmcnt(0)
	v_mfma_f32_16x16x32_bf16 v[60:63], v[148:151], v[164:167], v[60:63]
	v_mfma_f32_16x16x32_bf16 v[56:59], v[156:159], v[164:167], v[56:59]
	v_mfma_f32_16x16x32_bf16 v[52:55], v[148:151], v[172:175], v[52:55]
	v_mfma_f32_16x16x32_bf16 v[48:51], v[156:159], v[172:175], v[48:51]
	v_mfma_f32_16x16x32_bf16 v[36:39], v[148:151], v[180:183], v[36:39]
	v_mfma_f32_16x16x32_bf16 v[32:35], v[156:159], v[180:183], v[32:35]
	v_mfma_f32_16x16x32_bf16 v[20:23], v[148:151], v[188:191], v[20:23]
	v_mfma_f32_16x16x32_bf16 v[16:19], v[156:159], v[188:191], v[16:19]
	v_mfma_f32_16x16x32_bf16 v[60:63], v[152:155], v[168:171], v[60:63]
	v_mfma_f32_16x16x32_bf16 v[56:59], v[160:163], v[168:171], v[56:59]
	v_mfma_f32_16x16x32_bf16 v[52:55], v[152:155], v[176:179], v[52:55]
	v_mfma_f32_16x16x32_bf16 v[48:51], v[160:163], v[176:179], v[48:51]
	v_mfma_f32_16x16x32_bf16 v[36:39], v[152:155], v[184:187], v[36:39]
	v_mfma_f32_16x16x32_bf16 v[32:35], v[160:163], v[184:187], v[32:35]
	v_mfma_f32_16x16x32_bf16 v[20:23], v[152:155], v[192:195], v[20:23]
	v_mfma_f32_16x16x32_bf16 v[16:19], v[160:163], v[192:195], v[16:19]
	s_barrier
	s_add_u32 s14, s18, 0xb0000
	s_addc_u32 s15, s19, 0
	s_mov_b32 m0, s40
	v_lshl_add_u64 v[148:149], s[14:15], 0, v[130:131]
	global_load_lds_dwordx4 v[148:149], off
	v_lshl_add_u64 v[148:149], s[14:15], 0, v[128:129]
	s_mov_b32 m0, s41
	s_nop 0
	global_load_lds_dwordx4 v[148:149], off
	s_waitcnt vmcnt(6)
	s_barrier
; #define STG(P, GB) do { const char* _gb = (GB); \
;     _Pragma("unroll") for (int _i = 0; _i < 2; ++_i) { \
;       __builtin_amdgcn_global_load_lds((const unsigned*)(_gb + voff[_i]), \
;         (LAS unsigned*)((LAS char*)(P) + ldsw + _i * 8192), 16, 0, 0); } } while (0)
; #define LDA(dst, b, h) _Pragma("unroll") for (int m = 0; m < 4; ++m) _Pragma("unroll") for (int k = 0; k < 2; ++k) \
;     dst[m][k] = *(const LAS bf16x8*)((LAS char*)SA(b, h) + aoff + m * 2048 + k * 1024)
; #define LDB(dst, b, h) _Pragma("unroll") for (int n = 0; n < 2; ++n) _Pragma("unroll") for (int k = 0; k < 2; ++k) \
;     dst[n][k] = *(const LAS bf16x8*)((LAS char*)SB(b, h) + boff + n * 2048 + k * 1024)
; #define MMA(ai, bj, At_, Bt_) do { __builtin_amdgcn_s_setprio(1); \
;     _Pragma("unroll") for (int m = 0; m < 4; ++m) _Pragma("unroll") for (int n = 0; n < 2; ++n) _Pragma("unroll") for (int k = 0; k < 2; ++k) \
;       acc[ai][bj][m][n] = __builtin_amdgcn_mfma_f32_16x16x32_bf16(Bt_[n][k], At_[m][k], acc[ai][bj][m][n], 0, 0, 0); \
;     __builtin_amdgcn_s_setprio(0); } while (0)
; #define WAIT_V(n) asm volatile("s_waitcnt vmcnt(" #n ")" ::: "memory")
; #define WAIT_L(n) asm volatile("s_waitcnt lgkmcnt(" #n ")" ::: "memory")
; #define BAR __builtin_amdgcn_s_barrier()
; #define SCHED __builtin_amdgcn_sched_barrier(0)
; __device__ __forceinline__ void gemm_phase(const bf16_t* __restrict__ A, const bf16_t* __restrict__ Bt, bf16_t* __restrict__ C, int M, int N, int K,
;                                            int ldc, const int EPI, char* smem, const int wid_u) {
;     ...
;       WAIT_V(6); BAR; MMA(1, 1, At, B1); BAR;
;       LDB(B0, 1, 0); SCHED; LDA(At, 1, 0); STG(SA(0, 1), a2 + hstep);
;       WAIT_L(8); BAR; WAIT_L(0); MMA(0, 0, At, B0); BAR; SCHED;
;       LDB(B1, 1, 1); STG(SB(1, 0), b3);
;       BAR; WAIT_L(0); MMA(0, 1, At, B1); BAR;
;       LDA(At, 1, 1); STG(SA(1, 0), a3);
	v_mfma_f32_16x16x32_bf16 v[44:47], v[196:199], v[164:167], v[44:47]
	v_mfma_f32_16x16x32_bf16 v[40:43], v[204:207], v[164:167], v[40:43]
	v_mfma_f32_16x16x32_bf16 v[28:31], v[196:199], v[172:175], v[28:31]
	v_mfma_f32_16x16x32_bf16 v[24:27], v[204:207], v[172:175], v[24:27]
	v_mfma_f32_16x16x32_bf16 v[12:15], v[196:199], v[180:183], v[12:15]
	v_mfma_f32_16x16x32_bf16 v[8:11], v[204:207], v[180:183], v[8:11]
	v_mfma_f32_16x16x32_bf16 v[4:7], v[196:199], v[188:191], v[4:7]
	v_mfma_f32_16x16x32_bf16 v[0:3], v[204:207], v[188:191], v[0:3]
	v_mfma_f32_16x16x32_bf16 v[44:47], v[200:203], v[168:171], v[44:47]
	v_mfma_f32_16x16x32_bf16 v[40:43], v[208:211], v[168:171], v[40:43]
	v_mfma_f32_16x16x32_bf16 v[28:31], v[200:203], v[176:179], v[28:31]
	v_mfma_f32_16x16x32_bf16 v[24:27], v[208:211], v[176:179], v[24:27]
	v_mfma_f32_16x16x32_bf16 v[12:15], v[200:203], v[184:187], v[12:15]
	v_mfma_f32_16x16x32_bf16 v[8:11], v[208:211], v[184:187], v[8:11]
	v_mfma_f32_16x16x32_bf16 v[4:7], v[200:203], v[192:195], v[4:7]
	v_mfma_f32_16x16x32_bf16 v[0:3], v[208:211], v[192:195], v[0:3]
	s_barrier
	ds_read_b128 v[148:151], v146
	ds_read_b128 v[152:155], v146 offset:1024
	ds_read_b128 v[156:159], v146 offset:2048
	ds_read_b128 v[160:163], v146 offset:3072
	s_add_u32 s14, s20, 0xb0000
	s_addc_u32 s15, s21, 0
	s_mov_b32 m0, s30
	v_lshl_add_u64 v[196:197], s[14:15], 0, v[130:131]
	ds_read_b128 v[164:167], v144 offset:32768
	ds_read_b128 v[168:171], v144 offset:33792
	ds_read_b128 v[172:175], v144 offset:34816
	ds_read_b128 v[176:179], v144 offset:35840
	ds_read_b128 v[180:183], v144 offset:36864
	ds_read_b128 v[184:187], v144 offset:37888
	ds_read_b128 v[188:191], v144 offset:38912
	ds_read_b128 v[192:195], v144 offset:39936
	global_load_lds_dwordx4 v[196:197], off
	v_lshl_add_u64 v[196:197], s[14:15], 0, v[128:129]
	s_mov_b32 m0, s31
	s_nop 0
	global_load_lds_dwordx4 v[196:197], off
	s_waitcnt lgkmcnt(8)
	s_barrier
	s_waitcnt lgkmcnt(0)
	v_mfma_f32_16x16x32_bf16 v[124:127], v[148:151], v[164:167], v[124:127]
	v_mfma_f32_16x16x32_bf16 v[120:123], v[156:159], v[164:167], v[120:123]
	v_mfma_f32_16x16x32_bf16 v[116:119], v[148:151], v[172:175], v[116:119]
	v_mfma_f32_16x16x32_bf16 v[112:115], v[156:159], v[172:175], v[112:115]
	v_mfma_f32_16x16x32_bf16 v[100:103], v[148:151], v[180:183], v[100:103]
	v_mfma_f32_16x16x32_bf16 v[96:99], v[156:159], v[180:183], v[96:99]
	v_mfma_f32_16x16x32_bf16 v[84:87], v[148:151], v[188:191], v[84:87]
	v_mfma_f32_16x16x32_bf16 v[80:83], v[156:159], v[188:191], v[80:83]
	v_mfma_f32_16x16x32_bf16 v[124:127], v[152:155], v[168:171], v[124:127]
	v_mfma_f32_16x16x32_bf16 v[120:123], v[160:163], v[168:171], v[120:123]
	v_mfma_f32_16x16x32_bf16 v[116:119], v[152:155], v[176:179], v[116:119]
	v_mfma_f32_16x16x32_bf16 v[112:115], v[160:163], v[176:179], v[112:115]
	v_mfma_f32_16x16x32_bf16 v[100:103], v[152:155], v[184:187], v[100:103]
	v_mfma_f32_16x16x32_bf16 v[96:99], v[160:163], v[184:187], v[96:99]
	v_mfma_f32_16x16x32_bf16 v[84:87], v[152:155], v[192:195], v[84:87]
	v_mfma_f32_16x16x32_bf16 v[80:83], v[160:163], v[192:195], v[80:83]
	s_barrier
	s_mov_b32 m0, s45
	v_lshl_add_u64 v[212:213], v[212:213], 0, s[12:13]
	ds_read_b128 v[196:199], v147
	ds_read_b128 v[200:203], v147 offset:1024
	ds_read_b128 v[204:207], v147 offset:2048
	ds_read_b128 v[208:211], v147 offset:3072
	global_load_lds_dwordx4 v[212:213], off
	v_lshl_add_u64 v[212:213], v[214:215], 0, s[12:13]
	s_mov_b32 m0, s46
	s_nop 0
	global_load_lds_dwordx4 v[212:213], off
	s_barrier
	s_waitcnt lgkmcnt(0)
	v_mfma_f32_16x16x32_bf16 v[108:111], v[196:199], v[164:167], v[108:111]
	v_mfma_f32_16x16x32_bf16 v[104:107], v[204:207], v[164:167], v[104:107]
	v_mfma_f32_16x16x32_bf16 v[92:95], v[196:199], v[172:175], v[92:95]
	v_mfma_f32_16x16x32_bf16 v[88:91], v[204:207], v[172:175], v[88:91]
	v_mfma_f32_16x16x32_bf16 v[76:79], v[196:199], v[180:183], v[76:79]
	v_mfma_f32_16x16x32_bf16 v[72:75], v[204:207], v[180:183], v[72:75]
	v_mfma_f32_16x16x32_bf16 v[68:71], v[196:199], v[188:191], v[68:71]
	v_mfma_f32_16x16x32_bf16 v[64:67], v[204:207], v[188:191], v[64:67]
	v_mfma_f32_16x16x32_bf16 v[108:111], v[200:203], v[168:171], v[108:111]
	v_mfma_f32_16x16x32_bf16 v[104:107], v[208:211], v[168:171], v[104:107]
	v_mfma_f32_16x16x32_bf16 v[92:95], v[200:203], v[176:179], v[92:95]
	v_mfma_f32_16x16x32_bf16 v[88:91], v[208:211], v[176:179], v[88:91]
	v_mfma_f32_16x16x32_bf16 v[76:79], v[200:203], v[184:187], v[76:79]
	v_mfma_f32_16x16x32_bf16 v[72:75], v[208:211], v[184:187], v[72:75]
	v_mfma_f32_16x16x32_bf16 v[68:71], v[200:203], v[192:195], v[68:71]
	v_mfma_f32_16x16x32_bf16 v[64:67], v[208:211], v[192:195], v[64:67]
	s_mov_b32 m0, s34
	v_lshl_add_u64 v[212:213], v[216:217], 0, s[12:13]
	s_barrier
	ds_read_b128 v[164:167], v144 offset:49152
	ds_read_b128 v[168:171], v144 offset:50176
	ds_read_b128 v[172:175], v144 offset:51200
	ds_read_b128 v[176:179], v144 offset:52224
	ds_read_b128 v[180:183], v144 offset:53248
	ds_read_b128 v[184:187], v144 offset:54272
	ds_read_b128 v[188:191], v144 offset:55296
	ds_read_b128 v[192:195], v144 offset:56320
	global_load_lds_dwordx4 v[212:213], off
	v_lshl_add_u64 v[212:213], v[218:219], 0, s[12:13]
	s_mov_b32 m0, s35
	s_nop 0
	global_load_lds_dwordx4 v[212:213], off
	s_barrier
; #define STG(P, GB) do { const char* _gb = (GB); \
;     _Pragma("unroll") for (int _i = 0; _i < 2; ++_i) { \
;       __builtin_amdgcn_global_load_lds((const unsigned*)(_gb + voff[_i]), \
;         (LAS unsigned*)((LAS char*)(P) + ldsw + _i * 8192), 16, 0, 0); } } while (0)
; #define MMA(ai, bj, At_, Bt_) do { __builtin_amdgcn_s_setprio(1); \
;     _Pragma("unroll") for (int m = 0; m < 4; ++m) _Pragma("unroll") for (int n = 0; n < 2; ++n) _Pragma("unroll") for (int k = 0; k < 2; ++k) \
;       acc[ai][bj][m][n] = __builtin_amdgcn_mfma_f32_16x16x32_bf16(Bt_[n][k], At_[m][k], acc[ai][bj][m][n], 0, 0, 0); \
;     __builtin_amdgcn_s_setprio(0); } while (0)
; #define WAIT_V(n) asm volatile("s_waitcnt vmcnt(" #n ")" ::: "memory")
; #define WAIT_L(n) asm volatile("s_waitcnt lgkmcnt(" #n ")" ::: "memory")
; #define BAR __builtin_amdgcn_s_barrier()
; #define SCHED __builtin_amdgcn_sched_barrier(0)
; __device__ __forceinline__ void gemm_phase(const bf16_t* __restrict__ A, const bf16_t* __restrict__ Bt, bf16_t* __restrict__ C, int M, int N, int K,
;                                            int ldc, const int EPI, char* smem, const int wid_u) {
;     ...
;       BAR; WAIT_L(0); MMA(1, 0, At, B0); BAR; SCHED;
;       STG(SB(1, 1), b3 + hstep);
;       WAIT_V(6); BAR; MMA(1, 1, At, B1); BAR;
;     }
	s_waitcnt lgkmcnt(0)
	v_mfma_f32_16x16x32_bf16 v[60:63], v[148:151], v[164:167], v[60:63]
	v_mfma_f32_16x16x32_bf16 v[56:59], v[156:159], v[164:167], v[56:59]
	v_mfma_f32_16x16x32_bf16 v[52:55], v[148:151], v[172:175], v[52:55]
	v_mfma_f32_16x16x32_bf16 v[48:51], v[156:159], v[172:175], v[48:51]
	v_mfma_f32_16x16x32_bf16 v[36:39], v[148:151], v[180:183], v[36:39]
	v_mfma_f32_16x16x32_bf16 v[32:35], v[156:159], v[180:183], v[32:35]
	v_mfma_f32_16x16x32_bf16 v[20:23], v[148:151], v[188:191], v[20:23]
	v_mfma_f32_16x16x32_bf16 v[16:19], v[156:159], v[188:191], v[16:19]
	v_mfma_f32_16x16x32_bf16 v[60:63], v[152:155], v[168:171], v[60:63]
	v_mfma_f32_16x16x32_bf16 v[56:59], v[160:163], v[168:171], v[56:59]
	v_mfma_f32_16x16x32_bf16 v[52:55], v[152:155], v[176:179], v[52:55]
	v_mfma_f32_16x16x32_bf16 v[48:51], v[160:163], v[176:179], v[48:51]
	v_mfma_f32_16x16x32_bf16 v[36:39], v[152:155], v[184:187], v[36:39]
	v_mfma_f32_16x16x32_bf16 v[32:35], v[160:163], v[184:187], v[32:35]
	v_mfma_f32_16x16x32_bf16 v[20:23], v[152:155], v[192:195], v[20:23]
	v_mfma_f32_16x16x32_bf16 v[16:19], v[160:163], v[192:195], v[16:19]
	s_barrier
	s_add_u32 s14, s18, 0xb0080
	s_addc_u32 s15, s19, 0
	s_add_i32 s18, s44, s27
	v_lshl_add_u64 v[148:149], s[14:15], 0, v[130:131]
	s_mov_b32 m0, s18
	s_nop 0
	global_load_lds_dwordx4 v[148:149], off
	v_lshl_add_u64 v[148:149], s[14:15], 0, v[128:129]
	s_add_i32 m0, s18, 0x2000
	s_nop 0
	global_load_lds_dwordx4 v[148:149], off
	s_waitcnt vmcnt(6)
	s_barrier
	v_mfma_f32_16x16x32_bf16 v[44:47], v[196:199], v[164:167], v[44:47]
	v_mfma_f32_16x16x32_bf16 v[40:43], v[204:207], v[164:167], v[40:43]
	v_mfma_f32_16x16x32_bf16 v[28:31], v[196:199], v[172:175], v[28:31]
	v_mfma_f32_16x16x32_bf16 v[24:27], v[204:207], v[172:175], v[24:27]
	v_mfma_f32_16x16x32_bf16 v[12:15], v[196:199], v[180:183], v[12:15]
	v_mfma_f32_16x16x32_bf16 v[8:11], v[204:207], v[180:183], v[8:11]
	v_mfma_f32_16x16x32_bf16 v[4:7], v[196:199], v[188:191], v[4:7]
	v_mfma_f32_16x16x32_bf16 v[0:3], v[204:207], v[188:191], v[0:3]
	v_mfma_f32_16x16x32_bf16 v[44:47], v[200:203], v[168:171], v[44:47]
	v_mfma_f32_16x16x32_bf16 v[40:43], v[208:211], v[168:171], v[40:43]
	v_mfma_f32_16x16x32_bf16 v[28:31], v[200:203], v[176:179], v[28:31]
	v_mfma_f32_16x16x32_bf16 v[24:27], v[208:211], v[176:179], v[24:27]
	v_mfma_f32_16x16x32_bf16 v[12:15], v[200:203], v[184:187], v[12:15]
	v_mfma_f32_16x16x32_bf16 v[8:11], v[208:211], v[184:187], v[8:11]
	v_mfma_f32_16x16x32_bf16 v[4:7], v[200:203], v[192:195], v[4:7]
	v_mfma_f32_16x16x32_bf16 v[0:3], v[208:211], v[192:195], v[0:3]
	s_add_i32 s53, s53, 2
	s_add_u32 s51, s51, 0x100
	s_addc_u32 s52, s52, 0
	s_cmp_gt_u32 s53, 41
	s_mov_b64 s[14:15], s[16:17]
	s_barrier
	s_cbranch_scc0 .LBB0_213
; #define WAIT_V(n) asm volatile("s_waitcnt vmcnt(" #n ")" ::: "memory")
; #define BAR __builtin_amdgcn_s_barrier()
; __device__ __forceinline__ void gemm_phase(const bf16_t* __restrict__ A, const bf16_t* __restrict__ Bt, bf16_t* __restrict__ C, int M, int N, int K,
;                                            int ldc, const int EPI, char* smem, const int wid_u) {
;     ...
;           const size_t row = (size_t)(brow + ai * HALF + wr * 64 + m * 16 + fr);
;           if (EPI == 0) {
; #pragma unroll
;             for (int bj = 0; bj < 2; ++bj) {
;               const f32x4 v0 = acc[ai][bj][m][0], v1 = acc[ai][bj][m][1];
;               uint4 u; u.x = cvt_pk_bf16(v0[0], v0[1]); u.y = cvt_pk_bf16(v0[2], v0[3]); u.z = cvt_pk_bf16(v1[0], v1[1]); u.w = cvt_pk_bf16(v1[2], v1[3]);
;               *(uint4*)(C + row * ldc + bcol + bj * HALF + wc * 32 + fq * 8) = u;
;             }
;     ...
;     if (!has_next) break;
; #pragma unroll
;     for (int a = 0; a < 2; ++a)
; #pragma unroll
;       for (int b = 0; b < 2; ++b)
; #pragma unroll
;         for (int m = 0; m < 4; ++m)
; #pragma unroll
;           for (int n = 0; n < 2; ++n) acc[a][b][m][n] = (f32x4){0.f, 0.f, 0.f, 0.f};
;     pm = npm; pn = npn; cA = nA; cB = nB; ++ui;
;   }
;   WAIT_V(0);
;   if (wr == 0) BAR;
;   BAR;
	v_lshl_add_u32 v148, s10, 8, v142
	v_cvt_pk_bf16_f32 v68, v68, v69
	v_cvt_pk_bf16_f32 v69, v70, v71
	v_cvt_pk_bf16_f32 v70, v64, v65
	v_add_u32_e32 v64, 0x80, v148
	s_lshl_b32 s10, s50, 9
	v_ashrrev_i32_e32 v149, 31, v148
	v_cvt_pk_bf16_f32 v108, v108, v109
	v_cvt_pk_bf16_f32 v109, v110, v111
	v_cvt_pk_bf16_f32 v110, v104, v105
	v_or_b32_e32 v104, 16, v148
	v_ashrrev_i32_e32 v65, 31, v64
	v_cvt_pk_bf16_f32 v44, v44, v45
	v_cvt_pk_bf16_f32 v45, v46, v47
	v_cvt_pk_bf16_f32 v46, v40, v41
	v_add_u32_e32 v40, 0x90, v148
	v_lshl_add_u64 v[150:151], v[132:133], 0, s[10:11]
	v_lshlrev_b64 v[152:153], 11, v[148:149]
	v_ashrrev_i32_e32 v105, 31, v104
	v_cvt_pk_bf16_f32 v92, v92, v93
	v_cvt_pk_bf16_f32 v93, v94, v95
	v_cvt_pk_bf16_f32 v94, v88, v89
	v_or_b32_e32 v88, 32, v148
	v_lshlrev_b64 v[64:65], 11, v[64:65]
	v_ashrrev_i32_e32 v41, 31, v40
	v_cvt_pk_bf16_f32 v28, v28, v29
	v_cvt_pk_bf16_f32 v29, v30, v31
	v_cvt_pk_bf16_f32 v30, v24, v25
	v_add_u32_e32 v24, 0xa0, v148
	v_lshl_add_u64 v[152:153], v[150:151], 0, v[152:153]
	v_cvt_pk_bf16_f32 v111, v106, v107
	v_lshlrev_b64 v[104:105], 11, v[104:105]
	v_ashrrev_i32_e32 v89, 31, v88
	v_cvt_pk_bf16_f32 v76, v76, v77
	v_cvt_pk_bf16_f32 v77, v78, v79
	v_cvt_pk_bf16_f32 v78, v72, v73
	v_or_b32_e32 v72, 48, v148
	v_lshl_add_u64 v[64:65], v[150:151], 0, v[64:65]
	v_cvt_pk_bf16_f32 v47, v42, v43
	v_lshlrev_b64 v[40:41], 11, v[40:41]
	v_ashrrev_i32_e32 v25, 31, v24
	v_cvt_pk_bf16_f32 v12, v12, v13
	v_cvt_pk_bf16_f32 v13, v14, v15
	v_cvt_pk_bf16_f32 v14, v8, v9
	v_add_u32_e32 v8, 0xb0, v148
	global_store_dwordx4 v[152:153], v[108:111], off offset:256
	v_cvt_pk_bf16_f32 v95, v90, v91
	v_lshlrev_b64 v[88:89], 11, v[88:89]
	v_lshl_add_u64 v[108:109], v[150:151], 0, v[104:105]
	v_ashrrev_i32_e32 v73, 31, v72
	global_store_dwordx4 v[64:65], v[44:47], off offset:256
	v_cvt_pk_bf16_f32 v31, v26, v27
	v_lshlrev_b64 v[24:25], 11, v[24:25]
	v_lshl_add_u64 v[44:45], v[150:151], 0, v[40:41]
	v_ashrrev_i32_e32 v9, 31, v8
	global_store_dwordx4 v[108:109], v[92:95], off offset:256
	v_cvt_pk_bf16_f32 v79, v74, v75
	v_lshlrev_b64 v[72:73], 11, v[72:73]
	v_lshl_add_u64 v[92:93], v[150:151], 0, v[88:89]
	global_store_dwordx4 v[44:45], v[28:31], off offset:256
	v_cvt_pk_bf16_f32 v15, v10, v11
	v_lshlrev_b64 v[8:9], 11, v[8:9]
	v_lshl_add_u64 v[28:29], v[150:151], 0, v[24:25]
	v_cvt_pk_bf16_f32 v124, v124, v125
	v_cvt_pk_bf16_f32 v125, v126, v127
	v_cvt_pk_bf16_f32 v126, v120, v121
	v_cvt_pk_bf16_f32 v127, v122, v123
	v_cvt_pk_bf16_f32 v104, v116, v117
	v_cvt_pk_bf16_f32 v105, v118, v119
	v_cvt_pk_bf16_f32 v106, v112, v113
	v_cvt_pk_bf16_f32 v107, v114, v115
	v_cvt_pk_bf16_f32 v88, v100, v101
	v_cvt_pk_bf16_f32 v89, v102, v103
	v_cvt_pk_bf16_f32 v90, v96, v97
	v_cvt_pk_bf16_f32 v91, v98, v99
	global_store_dwordx4 v[92:93], v[76:79], off offset:256
	v_cvt_pk_bf16_f32 v74, v80, v81
	v_cvt_pk_bf16_f32 v75, v82, v83
	v_lshl_add_u64 v[76:77], v[150:151], 0, v[72:73]
	v_cvt_pk_bf16_f32 v72, v84, v85
	v_cvt_pk_bf16_f32 v73, v86, v87
	v_cvt_pk_bf16_f32 v71, v66, v67
	v_cvt_pk_bf16_f32 v60, v60, v61
	v_cvt_pk_bf16_f32 v61, v62, v63
	v_cvt_pk_bf16_f32 v62, v56, v57
	v_cvt_pk_bf16_f32 v63, v58, v59
	v_cvt_pk_bf16_f32 v40, v52, v53
	v_cvt_pk_bf16_f32 v41, v54, v55
	v_cvt_pk_bf16_f32 v42, v48, v49
	v_cvt_pk_bf16_f32 v43, v50, v51
	v_cvt_pk_bf16_f32 v24, v36, v37
	v_cvt_pk_bf16_f32 v25, v38, v39
	v_cvt_pk_bf16_f32 v26, v32, v33
	v_cvt_pk_bf16_f32 v27, v34, v35
	global_store_dwordx4 v[28:29], v[12:15], off offset:256
	v_cvt_pk_bf16_f32 v10, v16, v17
	v_cvt_pk_bf16_f32 v11, v18, v19
	v_lshl_add_u64 v[12:13], v[150:151], 0, v[8:9]
	v_cvt_pk_bf16_f32 v8, v20, v21
	v_cvt_pk_bf16_f32 v9, v22, v23
	v_cvt_pk_bf16_f32 v4, v4, v5
	v_cvt_pk_bf16_f32 v5, v6, v7
	v_cvt_pk_bf16_f32 v6, v0, v1
	v_cvt_pk_bf16_f32 v7, v2, v3
	s_and_b64 vcc, exec, s[2:3]
	s_mov_b32 s10, s48
	s_mov_b32 s50, s49
	s_mov_b64 s[16:17], s[6:7]
	s_mov_b64 s[14:15], s[4:5]
	global_store_dwordx4 v[152:153], v[124:127], off
	global_store_dwordx4 v[108:109], v[104:107], off
	global_store_dwordx4 v[92:93], v[88:91], off
	global_store_dwordx4 v[76:77], v[72:75], off
	global_store_dwordx4 v[76:77], v[68:71], off offset:256
	global_store_dwordx4 v[64:65], v[60:63], off
	global_store_dwordx4 v[44:45], v[40:43], off
	global_store_dwordx4 v[28:29], v[24:27], off
	global_store_dwordx4 v[12:13], v[8:11], off
	global_store_dwordx4 v[12:13], v[4:7], off offset:256
	s_cbranch_vccz .LBB0_206
	s_waitcnt vmcnt(0)
	s_cmpk_gt_u32 s22, 0xff
	s_cbranch_scc1 .LBB0_217
	s_barrier

; #define STG(P, GB) do { const char* _gb = (GB); \
;     _Pragma("unroll") for (int _i = 0; _i < 2; ++_i) { \
;       __builtin_amdgcn_global_load_lds((const unsigned*)(_gb + voff[_i]), \
;         (LAS unsigned*)((LAS char*)(P) + ldsw + _i * 8192), 16, 0, 0); } } while (0)
; #define LDA(dst, b, h) _Pragma("unroll") for (int m = 0; m < 4; ++m) _Pragma("unroll") for (int k = 0; k < 2; ++k) \
;     dst[m][k] = *(const LAS bf16x8*)((LAS char*)SA(b, h) + aoff + m * 2048 + k * 1024)
; #define LDB(dst, b, h) _Pragma("unroll") for (int n = 0; n < 2; ++n) _Pragma("unroll") for (int k = 0; k < 2; ++k) \
;     dst[n][k] = *(const LAS bf16x8*)((LAS char*)SB(b, h) + boff + n * 2048 + k * 1024)
; #define MMA(ai, bj, At_, Bt_) do { __builtin_amdgcn_s_setprio(1); \
;     _Pragma("unroll") for (int m = 0; m < 4; ++m) _Pragma("unroll") for (int n = 0; n < 2; ++n) _Pragma("unroll") for (int k = 0; k < 2; ++k) \
;       acc[ai][bj][m][n] = __builtin_amdgcn_mfma_f32_16x16x32_bf16(Bt_[n][k], At_[m][k], acc[ai][bj][m][n], 0, 0, 0); \
;     __builtin_amdgcn_s_setprio(0); } while (0)
; #define WAIT_L(n) asm volatile("s_waitcnt lgkmcnt(" #n ")" ::: "memory")
; #define BAR __builtin_amdgcn_s_barrier()
; #define SCHED __builtin_amdgcn_sched_barrier(0)
; __device__ __forceinline__ void gemm_phase(const bf16_t* __restrict__ A, const bf16_t* __restrict__ Bt, bf16_t* __restrict__ C, int M, int N, int K,
;                                            int ldc, const int EPI, char* smem, const int wid_u) {
;     ...
;       const bool last = (t == nt - 2);
;       const char* a1 = cA + (size_t)(t + 1) * kstep;
;       const char* a2 = last ? nA : cA + (size_t)(t + 2) * kstep;
;       const char* b2 = last ? nB : cB + (size_t)(t + 2) * kstep;
;       const char* a3 = a2 + kstep;
;       const char* b3 = b2 + kstep;
;       LDB(B0, 0, 0); SCHED; LDA(At, 0, 0); STG(SA(1, 1), a1 + hstep);
;       WAIT_L(8); BAR; WAIT_L(0); MMA(0, 0, At, B0); BAR; SCHED;
;       LDB(B1, 0, 1); STG(SB(0, 0), b2);
;       BAR; WAIT_L(0); MMA(0, 1, At, B1); BAR;
;       LDA(At, 0, 1); STG(SA(0, 0), a2);
;       BAR; WAIT_L(0); MMA(1, 0, At, B0); BAR; SCHED;
.LBB0_334:
	ds_read_b128 v[148:151], v144
	ds_read_b128 v[152:155], v144 offset:1024
	ds_read_b128 v[156:159], v144 offset:2048
	ds_read_b128 v[160:163], v144 offset:3072
	s_add_u32 s18, s16, 0x100
	s_addc_u32 s19, s17, 0
	s_cmp_eq_u32 s51, 12
	s_cselect_b32 s23, s46, s19
	s_cselect_b32 s22, s47, s18
	s_cselect_b32 s21, s11, s50
	s_cselect_b32 s20, s48, s49
	v_lshl_add_u64 v[196:197], s[16:17], 0, v[136:137]
	s_add_i32 m0, s30, 0xc000
	ds_read_b128 v[164:167], v145
	ds_read_b128 v[168:171], v145 offset:1024
	ds_read_b128 v[172:175], v145 offset:2048
	ds_read_b128 v[176:179], v145 offset:3072
	ds_read_b128 v[180:183], v145 offset:4096
	ds_read_b128 v[184:187], v145 offset:5120
	ds_read_b128 v[188:191], v145 offset:6144
	ds_read_b128 v[192:195], v145 offset:7168
	global_load_lds_dwordx4 v[196:197], off
	v_lshl_add_u64 v[196:197], s[16:17], 0, v[134:135]
	s_add_i32 m0, s30, 0xe000
	s_nop 0
	global_load_lds_dwordx4 v[196:197], off
	s_waitcnt lgkmcnt(8)
	s_barrier
	s_waitcnt lgkmcnt(0)
	v_mfma_f32_16x16x32_bf16 v[124:127], v[148:151], v[164:167], v[124:127]
	v_mfma_f32_16x16x32_bf16 v[120:123], v[156:159], v[164:167], v[120:123]
	v_mfma_f32_16x16x32_bf16 v[116:119], v[148:151], v[172:175], v[116:119]
	v_mfma_f32_16x16x32_bf16 v[112:115], v[156:159], v[172:175], v[112:115]
	v_mfma_f32_16x16x32_bf16 v[100:103], v[148:151], v[180:183], v[100:103]
	v_mfma_f32_16x16x32_bf16 v[96:99], v[156:159], v[180:183], v[96:99]
	v_mfma_f32_16x16x32_bf16 v[84:87], v[148:151], v[188:191], v[84:87]
	v_mfma_f32_16x16x32_bf16 v[80:83], v[156:159], v[188:191], v[80:83]
	v_mfma_f32_16x16x32_bf16 v[124:127], v[152:155], v[168:171], v[124:127]
	v_mfma_f32_16x16x32_bf16 v[120:123], v[160:163], v[168:171], v[120:123]
	v_mfma_f32_16x16x32_bf16 v[116:119], v[152:155], v[176:179], v[116:119]
	v_mfma_f32_16x16x32_bf16 v[112:115], v[160:163], v[176:179], v[112:115]
	v_mfma_f32_16x16x32_bf16 v[100:103], v[152:155], v[184:187], v[100:103]
	v_mfma_f32_16x16x32_bf16 v[96:99], v[160:163], v[184:187], v[96:99]
	v_mfma_f32_16x16x32_bf16 v[84:87], v[152:155], v[192:195], v[84:87]
	v_mfma_f32_16x16x32_bf16 v[80:83], v[160:163], v[192:195], v[80:83]
	s_barrier
	s_add_i32 s16, s38, s29
	v_lshl_add_u64 v[212:213], s[20:21], 0, v[130:131]
	s_mov_b32 m0, s16
	ds_read_b128 v[196:199], v146
	ds_read_b128 v[200:203], v146 offset:1024
	ds_read_b128 v[204:207], v146 offset:2048
	ds_read_b128 v[208:211], v146 offset:3072
	global_load_lds_dwordx4 v[212:213], off
	v_lshl_add_u64 v[214:215], s[20:21], 0, v[128:129]
	s_add_i32 m0, s16, 0x2000
	s_nop 0
	global_load_lds_dwordx4 v[214:215], off
	s_barrier
	s_waitcnt lgkmcnt(0)
	v_mfma_f32_16x16x32_bf16 v[108:111], v[196:199], v[164:167], v[108:111]
	v_mfma_f32_16x16x32_bf16 v[104:107], v[204:207], v[164:167], v[104:107]
	v_mfma_f32_16x16x32_bf16 v[92:95], v[196:199], v[172:175], v[92:95]
	v_mfma_f32_16x16x32_bf16 v[88:91], v[204:207], v[172:175], v[88:91]
	v_mfma_f32_16x16x32_bf16 v[76:79], v[196:199], v[180:183], v[76:79]
	v_mfma_f32_16x16x32_bf16 v[72:75], v[204:207], v[180:183], v[72:75]
	v_mfma_f32_16x16x32_bf16 v[68:71], v[196:199], v[188:191], v[68:71]
	v_mfma_f32_16x16x32_bf16 v[64:67], v[204:207], v[188:191], v[64:67]
	v_mfma_f32_16x16x32_bf16 v[108:111], v[200:203], v[168:171], v[108:111]
	v_mfma_f32_16x16x32_bf16 v[104:107], v[208:211], v[168:171], v[104:107]
	v_mfma_f32_16x16x32_bf16 v[92:95], v[200:203], v[176:179], v[92:95]
	v_mfma_f32_16x16x32_bf16 v[88:91], v[208:211], v[176:179], v[88:91]
	v_mfma_f32_16x16x32_bf16 v[76:79], v[200:203], v[184:187], v[76:79]
	v_mfma_f32_16x16x32_bf16 v[72:75], v[208:211], v[184:187], v[72:75]
	v_mfma_f32_16x16x32_bf16 v[68:71], v[200:203], v[192:195], v[68:71]
	v_mfma_f32_16x16x32_bf16 v[64:67], v[208:211], v[192:195], v[64:67]
	s_mov_b32 m0, s30
	v_lshl_add_u64 v[216:217], s[22:23], 0, v[130:131]
	s_barrier
	ds_read_b128 v[164:167], v145 offset:16384
	ds_read_b128 v[168:171], v145 offset:17408
	ds_read_b128 v[172:175], v145 offset:18432
	ds_read_b128 v[176:179], v145 offset:19456
	ds_read_b128 v[180:183], v145 offset:20480
	ds_read_b128 v[184:187], v145 offset:21504
	ds_read_b128 v[188:191], v145 offset:22528
	ds_read_b128 v[192:195], v145 offset:23552
	global_load_lds_dwordx4 v[216:217], off
	v_lshl_add_u64 v[218:219], s[22:23], 0, v[128:129]
	s_mov_b32 m0, s31
	s_nop 0
	global_load_lds_dwordx4 v[218:219], off
	s_barrier
	s_waitcnt lgkmcnt(0)
	v_mfma_f32_16x16x32_bf16 v[60:63], v[148:151], v[164:167], v[60:63]
	v_mfma_f32_16x16x32_bf16 v[56:59], v[156:159], v[164:167], v[56:59]
	v_mfma_f32_16x16x32_bf16 v[52:55], v[148:151], v[172:175], v[52:55]
	v_mfma_f32_16x16x32_bf16 v[48:51], v[156:159], v[172:175], v[48:51]
	v_mfma_f32_16x16x32_bf16 v[36:39], v[148:151], v[180:183], v[36:39]
	v_mfma_f32_16x16x32_bf16 v[32:35], v[156:159], v[180:183], v[32:35]
	v_mfma_f32_16x16x32_bf16 v[20:23], v[148:151], v[188:191], v[20:23]
	v_mfma_f32_16x16x32_bf16 v[16:19], v[156:159], v[188:191], v[16:19]
	v_mfma_f32_16x16x32_bf16 v[60:63], v[152:155], v[168:171], v[60:63]
	v_mfma_f32_16x16x32_bf16 v[56:59], v[160:163], v[168:171], v[56:59]
	v_mfma_f32_16x16x32_bf16 v[52:55], v[152:155], v[176:179], v[52:55]
	v_mfma_f32_16x16x32_bf16 v[48:51], v[160:163], v[176:179], v[48:51]
	v_mfma_f32_16x16x32_bf16 v[36:39], v[152:155], v[184:187], v[36:39]
	v_mfma_f32_16x16x32_bf16 v[32:35], v[160:163], v[184:187], v[32:35]
	v_mfma_f32_16x16x32_bf16 v[20:23], v[152:155], v[192:195], v[20:23]
	v_mfma_f32_16x16x32_bf16 v[16:19], v[160:163], v[192:195], v[16:19]
	s_barrier
; #define STG(P, GB) do { const char* _gb = (GB); \
;     _Pragma("unroll") for (int _i = 0; _i < 2; ++_i) { \
;       __builtin_amdgcn_global_load_lds((const unsigned*)(_gb + voff[_i]), \
;         (LAS unsigned*)((LAS char*)(P) + ldsw + _i * 8192), 16, 0, 0); } } while (0)
; #define LDA(dst, b, h) _Pragma("unroll") for (int m = 0; m < 4; ++m) _Pragma("unroll") for (int k = 0; k < 2; ++k) \
;     dst[m][k] = *(const LAS bf16x8*)((LAS char*)SA(b, h) + aoff + m * 2048 + k * 1024)
; #define LDB(dst, b, h) _Pragma("unroll") for (int n = 0; n < 2; ++n) _Pragma("unroll") for (int k = 0; k < 2; ++k) \
;     dst[n][k] = *(const LAS bf16x8*)((LAS char*)SB(b, h) + boff + n * 2048 + k * 1024)
; #define MMA(ai, bj, At_, Bt_) do { __builtin_amdgcn_s_setprio(1); \
;     _Pragma("unroll") for (int m = 0; m < 4; ++m) _Pragma("unroll") for (int n = 0; n < 2; ++n) _Pragma("unroll") for (int k = 0; k < 2; ++k) \
;       acc[ai][bj][m][n] = __builtin_amdgcn_mfma_f32_16x16x32_bf16(Bt_[n][k], At_[m][k], acc[ai][bj][m][n], 0, 0, 0); \
;     __builtin_amdgcn_s_setprio(0); } while (0)
; #define WAIT_V(n) asm volatile("s_waitcnt vmcnt(" #n ")" ::: "memory")
; #define WAIT_L(n) asm volatile("s_waitcnt lgkmcnt(" #n ")" ::: "memory")
; #define BAR __builtin_amdgcn_s_barrier()
; #define SCHED __builtin_amdgcn_sched_barrier(0)
; __device__ __forceinline__ void gemm_phase(const bf16_t* __restrict__ A, const bf16_t* __restrict__ Bt, bf16_t* __restrict__ C, int M, int N, int K,
;                                            int ldc, const int EPI, char* smem, const int wid_u) {
;     ...
;       STG(SB(0, 1), b2 + hstep);
;       WAIT_V(6); BAR; MMA(1, 1, At, B1); BAR;
;       LDB(B0, 1, 0); SCHED; LDA(At, 1, 0); STG(SA(0, 1), a2 + hstep);
;       WAIT_L(8); BAR; WAIT_L(0); MMA(0, 0, At, B0); BAR; SCHED;
;       LDB(B1, 1, 1); STG(SB(1, 0), b3);
;       BAR; WAIT_L(0); MMA(0, 1, At, B1); BAR;
;       LDA(At, 1, 1); STG(SA(1, 0), a3);
	s_add_u32 s16, s20, 0x40000
	s_addc_u32 s17, s21, 0
	s_add_i32 s52, s39, s29
	v_lshl_add_u64 v[148:149], s[16:17], 0, v[130:131]
	s_mov_b32 m0, s52
	s_nop 0
	global_load_lds_dwordx4 v[148:149], off
	v_lshl_add_u64 v[148:149], s[16:17], 0, v[128:129]
	s_add_i32 m0, s52, 0x2000
	s_nop 0
	global_load_lds_dwordx4 v[148:149], off
	s_waitcnt vmcnt(6)
	s_barrier
	v_mfma_f32_16x16x32_bf16 v[44:47], v[196:199], v[164:167], v[44:47]
	v_mfma_f32_16x16x32_bf16 v[40:43], v[204:207], v[164:167], v[40:43]
	v_mfma_f32_16x16x32_bf16 v[28:31], v[196:199], v[172:175], v[28:31]
	v_mfma_f32_16x16x32_bf16 v[24:27], v[204:207], v[172:175], v[24:27]
	v_mfma_f32_16x16x32_bf16 v[12:15], v[196:199], v[180:183], v[12:15]
	v_mfma_f32_16x16x32_bf16 v[8:11], v[204:207], v[180:183], v[8:11]
	v_mfma_f32_16x16x32_bf16 v[4:7], v[196:199], v[188:191], v[4:7]
	v_mfma_f32_16x16x32_bf16 v[0:3], v[204:207], v[188:191], v[0:3]
	v_mfma_f32_16x16x32_bf16 v[44:47], v[200:203], v[168:171], v[44:47]
	v_mfma_f32_16x16x32_bf16 v[40:43], v[208:211], v[168:171], v[40:43]
	v_mfma_f32_16x16x32_bf16 v[28:31], v[200:203], v[176:179], v[28:31]
	v_mfma_f32_16x16x32_bf16 v[24:27], v[208:211], v[176:179], v[24:27]
	v_mfma_f32_16x16x32_bf16 v[12:15], v[200:203], v[184:187], v[12:15]
	v_mfma_f32_16x16x32_bf16 v[8:11], v[208:211], v[184:187], v[8:11]
	v_mfma_f32_16x16x32_bf16 v[4:7], v[200:203], v[192:195], v[4:7]
	v_mfma_f32_16x16x32_bf16 v[0:3], v[208:211], v[192:195], v[0:3]
	s_add_i32 s52, 0, 0x18000
	v_add_u32_e32 v147, s52, v143
	s_barrier
	ds_read_b128 v[148:151], v147
	ds_read_b128 v[152:155], v147 offset:1024
	ds_read_b128 v[156:159], v147 offset:2048
	ds_read_b128 v[160:163], v147 offset:3072
	s_add_u32 s16, s22, 0x40000
	s_addc_u32 s17, s23, 0
	s_mov_b32 m0, s34
	v_lshl_add_u64 v[196:197], s[16:17], 0, v[130:131]
	ds_read_b128 v[164:167], v145 offset:32768
	ds_read_b128 v[168:171], v145 offset:33792
	ds_read_b128 v[172:175], v145 offset:34816
	ds_read_b128 v[176:179], v145 offset:35840
	ds_read_b128 v[180:183], v145 offset:36864
	ds_read_b128 v[184:187], v145 offset:37888
	ds_read_b128 v[188:191], v145 offset:38912
	ds_read_b128 v[192:195], v145 offset:39936
	global_load_lds_dwordx4 v[196:197], off
	v_lshl_add_u64 v[196:197], s[16:17], 0, v[128:129]
	s_mov_b32 m0, s35
	s_nop 0
	global_load_lds_dwordx4 v[196:197], off
	s_waitcnt lgkmcnt(8)
	s_barrier
	s_waitcnt lgkmcnt(0)
	v_mfma_f32_16x16x32_bf16 v[124:127], v[148:151], v[164:167], v[124:127]
	v_mfma_f32_16x16x32_bf16 v[120:123], v[156:159], v[164:167], v[120:123]
	v_mfma_f32_16x16x32_bf16 v[116:119], v[148:151], v[172:175], v[116:119]
	v_mfma_f32_16x16x32_bf16 v[112:115], v[156:159], v[172:175], v[112:115]
	v_mfma_f32_16x16x32_bf16 v[100:103], v[148:151], v[180:183], v[100:103]
	v_mfma_f32_16x16x32_bf16 v[96:99], v[156:159], v[180:183], v[96:99]
	v_mfma_f32_16x16x32_bf16 v[84:87], v[148:151], v[188:191], v[84:87]
	v_mfma_f32_16x16x32_bf16 v[80:83], v[156:159], v[188:191], v[80:83]
	v_mfma_f32_16x16x32_bf16 v[124:127], v[152:155], v[168:171], v[124:127]
	v_mfma_f32_16x16x32_bf16 v[120:123], v[160:163], v[168:171], v[120:123]
	v_mfma_f32_16x16x32_bf16 v[116:119], v[152:155], v[176:179], v[116:119]
	v_mfma_f32_16x16x32_bf16 v[112:115], v[160:163], v[176:179], v[112:115]
	v_mfma_f32_16x16x32_bf16 v[100:103], v[152:155], v[184:187], v[100:103]
	v_mfma_f32_16x16x32_bf16 v[96:99], v[160:163], v[184:187], v[96:99]
	v_mfma_f32_16x16x32_bf16 v[84:87], v[152:155], v[192:195], v[84:87]
	v_mfma_f32_16x16x32_bf16 v[80:83], v[160:163], v[192:195], v[80:83]
	s_barrier
	s_add_i32 s22, 0, 0x1c000
	s_add_i32 s16, s52, s29
	v_add_u32_e32 v147, s22, v143
	v_lshl_add_u64 v[212:213], v[212:213], 0, s[8:9]
	s_mov_b32 m0, s16
	ds_read_b128 v[196:199], v147
	ds_read_b128 v[200:203], v147 offset:1024
	ds_read_b128 v[204:207], v147 offset:2048
	ds_read_b128 v[208:211], v147 offset:3072
	global_load_lds_dwordx4 v[212:213], off
	v_lshl_add_u64 v[212:213], v[214:215], 0, s[8:9]
	s_add_i32 m0, s16, 0x2000
	s_nop 0
	global_load_lds_dwordx4 v[212:213], off
	s_barrier
	s_waitcnt lgkmcnt(0)
	v_mfma_f32_16x16x32_bf16 v[108:111], v[196:199], v[164:167], v[108:111]
	v_mfma_f32_16x16x32_bf16 v[104:107], v[204:207], v[164:167], v[104:107]
	v_mfma_f32_16x16x32_bf16 v[92:95], v[196:199], v[172:175], v[92:95]
	v_mfma_f32_16x16x32_bf16 v[88:91], v[204:207], v[172:175], v[88:91]
	v_mfma_f32_16x16x32_bf16 v[76:79], v[196:199], v[180:183], v[76:79]
	v_mfma_f32_16x16x32_bf16 v[72:75], v[204:207], v[180:183], v[72:75]
	v_mfma_f32_16x16x32_bf16 v[68:71], v[196:199], v[188:191], v[68:71]
	v_mfma_f32_16x16x32_bf16 v[64:67], v[204:207], v[188:191], v[64:67]
	v_mfma_f32_16x16x32_bf16 v[108:111], v[200:203], v[168:171], v[108:111]
	v_mfma_f32_16x16x32_bf16 v[104:107], v[208:211], v[168:171], v[104:107]
	v_mfma_f32_16x16x32_bf16 v[92:95], v[200:203], v[176:179], v[92:95]
	v_mfma_f32_16x16x32_bf16 v[88:91], v[208:211], v[176:179], v[88:91]
	v_mfma_f32_16x16x32_bf16 v[76:79], v[200:203], v[184:187], v[76:79]
	v_mfma_f32_16x16x32_bf16 v[72:75], v[208:211], v[184:187], v[72:75]
	v_mfma_f32_16x16x32_bf16 v[68:71], v[200:203], v[192:195], v[68:71]
	v_mfma_f32_16x16x32_bf16 v[64:67], v[208:211], v[192:195], v[64:67]
	s_mov_b32 m0, s36
	v_lshl_add_u64 v[212:213], v[216:217], 0, s[8:9]
	s_barrier
	ds_read_b128 v[164:167], v145 offset:49152
	ds_read_b128 v[168:171], v145 offset:50176
	ds_read_b128 v[172:175], v145 offset:51200
	ds_read_b128 v[176:179], v145 offset:52224
	ds_read_b128 v[180:183], v145 offset:53248
	ds_read_b128 v[184:187], v145 offset:54272
	ds_read_b128 v[188:191], v145 offset:55296
	ds_read_b128 v[192:195], v145 offset:56320
	global_load_lds_dwordx4 v[212:213], off
	v_lshl_add_u64 v[212:213], v[218:219], 0, s[8:9]
	s_mov_b32 m0, s37
	s_nop 0
	global_load_lds_dwordx4 v[212:213], off
	s_barrier
; #define STG(P, GB) do { const char* _gb = (GB); \
;     _Pragma("unroll") for (int _i = 0; _i < 2; ++_i) { \
;       __builtin_amdgcn_global_load_lds((const unsigned*)(_gb + voff[_i]), \
;         (LAS unsigned*)((LAS char*)(P) + ldsw + _i * 8192), 16, 0, 0); } } while (0)
; #define MMA(ai, bj, At_, Bt_) do { __builtin_amdgcn_s_setprio(1); \
;     _Pragma("unroll") for (int m = 0; m < 4; ++m) _Pragma("unroll") for (int n = 0; n < 2; ++n) _Pragma("unroll") for (int k = 0; k < 2; ++k) \
;       acc[ai][bj][m][n] = __builtin_amdgcn_mfma_f32_16x16x32_bf16(Bt_[n][k], At_[m][k], acc[ai][bj][m][n], 0, 0, 0); \
;     __builtin_amdgcn_s_setprio(0); } while (0)
; #define WAIT_V(n) asm volatile("s_waitcnt vmcnt(" #n ")" ::: "memory")
; #define WAIT_L(n) asm volatile("s_waitcnt lgkmcnt(" #n ")" ::: "memory")
; #define BAR __builtin_amdgcn_s_barrier()
; #define SCHED __builtin_amdgcn_sched_barrier(0)
; __device__ __forceinline__ void gemm_phase(const bf16_t* __restrict__ A, const bf16_t* __restrict__ Bt, bf16_t* __restrict__ C, int M, int N, int K,
;                                            int ldc, const int EPI, char* smem, const int wid_u) {
;     ...
;       BAR; WAIT_L(0); MMA(1, 0, At, B0); BAR; SCHED;
;       STG(SB(1, 1), b3 + hstep);
;       WAIT_V(6); BAR; MMA(1, 1, At, B1); BAR;
;     }
;     {
;       const int brow = pm * BM, bcol = pn * BM;
; #pragma unroll
;       for (int ai = 0; ai < 2; ++ai)
; #pragma unroll
;         for (int m = 0; m < 4; ++m) {
;           const size_t row = (size_t)(brow + ai * HALF + wr * 64 + m * 16 + fr);
;           if (EPI == 0) {
; #pragma unroll
;             for (int bj = 0; bj < 2; ++bj) {
;               const f32x4 v0 = acc[ai][bj][m][0], v1 = acc[ai][bj][m][1];
;               uint4 u; u.x = cvt_pk_bf16(v0[0], v0[1]); u.y = cvt_pk_bf16(v0[2], v0[3]); u.z = cvt_pk_bf16(v1[0], v1[1]); u.w = cvt_pk_bf16(v1[2], v1[3]);
;               *(uint4*)(C + row * ldc + bcol + bj * HALF + wc * 32 + fq * 8) = u;
;             }
	s_waitcnt lgkmcnt(0)
	v_mfma_f32_16x16x32_bf16 v[60:63], v[148:151], v[164:167], v[60:63]
	v_mfma_f32_16x16x32_bf16 v[56:59], v[156:159], v[164:167], v[56:59]
	v_mfma_f32_16x16x32_bf16 v[52:55], v[148:151], v[172:175], v[52:55]
	v_mfma_f32_16x16x32_bf16 v[48:51], v[156:159], v[172:175], v[48:51]
	v_mfma_f32_16x16x32_bf16 v[36:39], v[148:151], v[180:183], v[36:39]
	v_mfma_f32_16x16x32_bf16 v[32:35], v[156:159], v[180:183], v[32:35]
	v_mfma_f32_16x16x32_bf16 v[20:23], v[148:151], v[188:191], v[20:23]
	v_mfma_f32_16x16x32_bf16 v[16:19], v[156:159], v[188:191], v[16:19]
	v_mfma_f32_16x16x32_bf16 v[60:63], v[152:155], v[168:171], v[60:63]
	v_mfma_f32_16x16x32_bf16 v[56:59], v[160:163], v[168:171], v[56:59]
	v_mfma_f32_16x16x32_bf16 v[52:55], v[152:155], v[176:179], v[52:55]
	v_mfma_f32_16x16x32_bf16 v[48:51], v[160:163], v[176:179], v[48:51]
	v_mfma_f32_16x16x32_bf16 v[36:39], v[152:155], v[184:187], v[36:39]
	v_mfma_f32_16x16x32_bf16 v[32:35], v[160:163], v[184:187], v[32:35]
	v_mfma_f32_16x16x32_bf16 v[20:23], v[152:155], v[192:195], v[20:23]
	v_mfma_f32_16x16x32_bf16 v[16:19], v[160:163], v[192:195], v[16:19]
	s_barrier
	s_add_u32 s16, s20, 0x40080
	s_addc_u32 s17, s21, 0
	s_add_i32 s20, s22, s29
	v_lshl_add_u64 v[148:149], s[16:17], 0, v[130:131]
	s_mov_b32 m0, s20
	s_nop 0
	global_load_lds_dwordx4 v[148:149], off
	v_lshl_add_u64 v[148:149], s[16:17], 0, v[128:129]
	s_add_i32 m0, s20, 0x2000
	s_nop 0
	global_load_lds_dwordx4 v[148:149], off
	s_waitcnt vmcnt(6)
	s_barrier
	v_mfma_f32_16x16x32_bf16 v[44:47], v[196:199], v[164:167], v[44:47]
	v_mfma_f32_16x16x32_bf16 v[40:43], v[204:207], v[164:167], v[40:43]
	v_mfma_f32_16x16x32_bf16 v[28:31], v[196:199], v[172:175], v[28:31]
	v_mfma_f32_16x16x32_bf16 v[24:27], v[204:207], v[172:175], v[24:27]
	v_mfma_f32_16x16x32_bf16 v[12:15], v[196:199], v[180:183], v[12:15]
	v_mfma_f32_16x16x32_bf16 v[8:11], v[204:207], v[180:183], v[8:11]
	v_mfma_f32_16x16x32_bf16 v[4:7], v[196:199], v[188:191], v[4:7]
	v_mfma_f32_16x16x32_bf16 v[0:3], v[204:207], v[188:191], v[0:3]
	v_mfma_f32_16x16x32_bf16 v[44:47], v[200:203], v[168:171], v[44:47]
	v_mfma_f32_16x16x32_bf16 v[40:43], v[208:211], v[168:171], v[40:43]
	v_mfma_f32_16x16x32_bf16 v[28:31], v[200:203], v[176:179], v[28:31]
	v_mfma_f32_16x16x32_bf16 v[24:27], v[208:211], v[176:179], v[24:27]
	v_mfma_f32_16x16x32_bf16 v[12:15], v[200:203], v[184:187], v[12:15]
	v_mfma_f32_16x16x32_bf16 v[8:11], v[208:211], v[184:187], v[8:11]
	v_mfma_f32_16x16x32_bf16 v[4:7], v[200:203], v[192:195], v[4:7]
	v_mfma_f32_16x16x32_bf16 v[0:3], v[208:211], v[192:195], v[0:3]
	s_add_i32 s51, s51, 2
	s_add_u32 s49, s49, 0x100
	s_addc_u32 s50, s50, 0
	s_cmp_gt_u32 s51, 13
	s_mov_b64 s[16:17], s[18:19]
	s_barrier
	s_cbranch_scc0 .LBB0_334
	v_lshl_add_u32 v147, s44, 8, v142
	s_lshl_b32 s16, s45, 9
	s_mov_b32 s17, s7
	v_lshl_add_u64 v[148:149], v[132:133], 0, s[16:17]
	v_cvt_pk_bf16_f32 v68, v68, v69
	v_cvt_pk_bf16_f32 v69, v70, v71
	v_cvt_pk_bf16_f32 v70, v64, v65
	v_add_u32_e32 v64, 0x80, v147
	v_mad_i64_i32 v[150:151], s[16:17], v147, s40, v[148:149]
	v_cvt_pk_bf16_f32 v108, v108, v109
	v_cvt_pk_bf16_f32 v109, v110, v111
	v_cvt_pk_bf16_f32 v110, v104, v105
	v_cvt_pk_bf16_f32 v111, v106, v107
	v_or_b32_e32 v104, 16, v147
	v_mad_i64_i32 v[64:65], s[16:17], v64, s40, v[148:149]
	v_cvt_pk_bf16_f32 v44, v44, v45
	v_cvt_pk_bf16_f32 v45, v46, v47
	v_cvt_pk_bf16_f32 v46, v40, v41
	v_cvt_pk_bf16_f32 v47, v42, v43
	v_add_u32_e32 v40, 0x90, v147
	global_store_dwordx4 v[150:151], v[108:111], off offset:256
	v_cvt_pk_bf16_f32 v92, v92, v93
	v_cvt_pk_bf16_f32 v93, v94, v95
	v_mad_i64_i32 v[108:109], s[16:17], v104, s40, v[148:149]
	v_cvt_pk_bf16_f32 v94, v88, v89
	v_cvt_pk_bf16_f32 v95, v90, v91
	v_or_b32_e32 v88, 32, v147
	global_store_dwordx4 v[64:65], v[44:47], off offset:256
	v_cvt_pk_bf16_f32 v28, v28, v29
	v_cvt_pk_bf16_f32 v29, v30, v31
	v_mad_i64_i32 v[44:45], s[16:17], v40, s40, v[148:149]
	v_cvt_pk_bf16_f32 v30, v24, v25
	v_cvt_pk_bf16_f32 v31, v26, v27
	v_add_u32_e32 v24, 0xa0, v147
	global_store_dwordx4 v[108:109], v[92:95], off offset:256
	v_cvt_pk_bf16_f32 v76, v76, v77
	v_cvt_pk_bf16_f32 v77, v78, v79
	v_mad_i64_i32 v[92:93], s[16:17], v88, s40, v[148:149]
	v_cvt_pk_bf16_f32 v78, v72, v73
	v_cvt_pk_bf16_f32 v79, v74, v75
	v_or_b32_e32 v72, 48, v147
	global_store_dwordx4 v[44:45], v[28:31], off offset:256
	v_cvt_pk_bf16_f32 v12, v12, v13
	v_cvt_pk_bf16_f32 v13, v14, v15
	v_mad_i64_i32 v[28:29], s[16:17], v24, s40, v[148:149]
	v_cvt_pk_bf16_f32 v14, v8, v9
	v_cvt_pk_bf16_f32 v15, v10, v11
	v_add_u32_e32 v8, 0xb0, v147
	global_store_dwordx4 v[92:93], v[76:79], off offset:256
	global_store_dwordx4 v[28:29], v[12:15], off offset:256
	v_cvt_pk_bf16_f32 v124, v124, v125
	v_mad_i64_i32 v[76:77], s[16:17], v72, s40, v[148:149]
	v_mad_i64_i32 v[12:13], s[16:17], v8, s40, v[148:149]
	v_cvt_pk_bf16_f32 v125, v126, v127
	v_cvt_pk_bf16_f32 v126, v120, v121
	v_cvt_pk_bf16_f32 v127, v122, v123
	v_cvt_pk_bf16_f32 v104, v116, v117
	v_cvt_pk_bf16_f32 v105, v118, v119
	v_cvt_pk_bf16_f32 v106, v112, v113
	v_cvt_pk_bf16_f32 v107, v114, v115
	v_cvt_pk_bf16_f32 v88, v100, v101
	v_cvt_pk_bf16_f32 v89, v102, v103
	v_cvt_pk_bf16_f32 v90, v96, v97
	v_cvt_pk_bf16_f32 v91, v98, v99
	v_cvt_pk_bf16_f32 v72, v84, v85
	v_cvt_pk_bf16_f32 v73, v86, v87
	v_cvt_pk_bf16_f32 v74, v80, v81
	v_cvt_pk_bf16_f32 v75, v82, v83
	v_cvt_pk_bf16_f32 v71, v66, v67
	v_cvt_pk_bf16_f32 v60, v60, v61
	v_cvt_pk_bf16_f32 v61, v62, v63
	v_cvt_pk_bf16_f32 v62, v56, v57
	v_cvt_pk_bf16_f32 v63, v58, v59
	v_cvt_pk_bf16_f32 v40, v52, v53
	v_cvt_pk_bf16_f32 v41, v54, v55
	v_cvt_pk_bf16_f32 v42, v48, v49
	v_cvt_pk_bf16_f32 v43, v50, v51
	v_cvt_pk_bf16_f32 v24, v36, v37
	v_cvt_pk_bf16_f32 v25, v38, v39
	v_cvt_pk_bf16_f32 v26, v32, v33
	v_cvt_pk_bf16_f32 v27, v34, v35
	v_cvt_pk_bf16_f32 v8, v20, v21
	v_cvt_pk_bf16_f32 v9, v22, v23
	v_cvt_pk_bf16_f32 v10, v16, v17
	v_cvt_pk_bf16_f32 v11, v18, v19
	v_cvt_pk_bf16_f32 v4, v4, v5
	v_cvt_pk_bf16_f32 v5, v6, v7
	v_cvt_pk_bf16_f32 v6, v0, v1
	v_cvt_pk_bf16_f32 v7, v2, v3
	s_and_b64 vcc, exec, s[2:3]
	s_mov_b32 s44, s6
	s_mov_b32 s45, s10
	s_mov_b64 s[18:19], s[14:15]
	s_mov_b64 s[16:17], s[12:13]
	global_store_dwordx4 v[150:151], v[124:127], off
	global_store_dwordx4 v[108:109], v[104:107], off
	global_store_dwordx4 v[92:93], v[88:91], off
	global_store_dwordx4 v[76:77], v[72:75], off
	global_store_dwordx4 v[76:77], v[68:71], off offset:256
	global_store_dwordx4 v[64:65], v[60:63], off
	global_store_dwordx4 v[44:45], v[40:43], off
	global_store_dwordx4 v[28:29], v[24:27], off
	global_store_dwordx4 v[12:13], v[8:11], off
	global_store_dwordx4 v[12:13], v[4:7], off offset:256
	s_cbranch_vccz .LBB0_331
	s_waitcnt vmcnt(0)
	s_cmpk_gt_u32 s24, 0xff
	s_cbranch_scc1 .LBB0_338
	s_barrier

; #define STG(P, GB) do { const char* _gb = (GB); \
;     _Pragma("unroll") for (int _i = 0; _i < 2; ++_i) { \
;       __builtin_amdgcn_global_load_lds((const unsigned*)(_gb + voff[_i]), \
;         (LAS unsigned*)((LAS char*)(P) + ldsw + _i * 8192), 16, 0, 0); } } while (0)
; #define LDA(dst, b, h) _Pragma("unroll") for (int m = 0; m < 4; ++m) _Pragma("unroll") for (int k = 0; k < 2; ++k) \
;     dst[m][k] = *(const LAS bf16x8*)((LAS char*)SA(b, h) + aoff + m * 2048 + k * 1024)
; #define LDB(dst, b, h) _Pragma("unroll") for (int n = 0; n < 2; ++n) _Pragma("unroll") for (int k = 0; k < 2; ++k) \
;     dst[n][k] = *(const LAS bf16x8*)((LAS char*)SB(b, h) + boff + n * 2048 + k * 1024)
; #define MMA(ai, bj, At_, Bt_) do { __builtin_amdgcn_s_setprio(1); \
;     _Pragma("unroll") for (int m = 0; m < 4; ++m) _Pragma("unroll") for (int n = 0; n < 2; ++n) _Pragma("unroll") for (int k = 0; k < 2; ++k) \
;       acc[ai][bj][m][n] = __builtin_amdgcn_mfma_f32_16x16x32_bf16(Bt_[n][k], At_[m][k], acc[ai][bj][m][n], 0, 0, 0); \
;     __builtin_amdgcn_s_setprio(0); } while (0)
; #define WAIT_V(n) asm volatile("s_waitcnt vmcnt(" #n ")" ::: "memory")
; #define WAIT_L(n) asm volatile("s_waitcnt lgkmcnt(" #n ")" ::: "memory")
; #define BAR __builtin_amdgcn_s_barrier()
; #define SCHED __builtin_amdgcn_sched_barrier(0)
; __device__ __forceinline__ void gemm_phase(const bf16_t* __restrict__ A, const bf16_t* __restrict__ Bt, bf16_t* __restrict__ C, int M, int N, int K,
;                                            int ldc, const int EPI, char* smem, const int wid_u) {
;     ...
;       const bool last = (t == nt - 2);
;       const char* a1 = cA + (size_t)(t + 1) * kstep;
;       const char* a2 = last ? nA : cA + (size_t)(t + 2) * kstep;
;       const char* b2 = last ? nB : cB + (size_t)(t + 2) * kstep;
;       const char* a3 = a2 + kstep;
;       const char* b3 = b2 + kstep;
;       LDB(B0, 0, 0); SCHED; LDA(At, 0, 0); STG(SA(1, 1), a1 + hstep);
;       WAIT_L(8); BAR; WAIT_L(0); MMA(0, 0, At, B0); BAR; SCHED;
;       LDB(B1, 0, 1); STG(SB(0, 0), b2);
;       BAR; WAIT_L(0); MMA(0, 1, At, B1); BAR;
;       LDA(At, 0, 1); STG(SA(0, 0), a2);
;       BAR; WAIT_L(0); MMA(1, 0, At, B0); BAR; SCHED;
;       STG(SB(0, 1), b2 + hstep);
;       WAIT_V(6); BAR; MMA(1, 1, At, B1); BAR;
.LBB0_905:
	ds_read_b128 v[148:151], v144
	ds_read_b128 v[152:155], v144 offset:1024
	ds_read_b128 v[156:159], v144 offset:2048
	ds_read_b128 v[160:163], v144 offset:3072
	s_add_u32 s18, s16, 0x100
	s_addc_u32 s19, s17, 0
	s_cmp_eq_u32 s55, 12
	s_cselect_b32 s23, s49, s19
	s_cselect_b32 s22, s50, s18
	s_cselect_b32 s21, s51, s54
	s_cselect_b32 s20, s52, s53
	s_mov_b32 m0, s38
	v_lshl_add_u64 v[196:197], s[16:17], 0, v[136:137]
	ds_read_b128 v[164:167], v145
	ds_read_b128 v[168:171], v145 offset:1024
	ds_read_b128 v[172:175], v145 offset:2048
	ds_read_b128 v[176:179], v145 offset:3072
	ds_read_b128 v[180:183], v145 offset:4096
	ds_read_b128 v[184:187], v145 offset:5120
	ds_read_b128 v[188:191], v145 offset:6144
	ds_read_b128 v[192:195], v145 offset:7168
	global_load_lds_dwordx4 v[196:197], off
	v_lshl_add_u64 v[196:197], s[16:17], 0, v[134:135]
	s_mov_b32 m0, s39
	s_nop 0
	global_load_lds_dwordx4 v[196:197], off
	s_waitcnt lgkmcnt(8)
	s_barrier
	s_waitcnt lgkmcnt(0)
	v_mfma_f32_16x16x32_bf16 v[124:127], v[148:151], v[164:167], v[124:127]
	v_mfma_f32_16x16x32_bf16 v[120:123], v[156:159], v[164:167], v[120:123]
	v_mfma_f32_16x16x32_bf16 v[116:119], v[148:151], v[172:175], v[116:119]
	v_mfma_f32_16x16x32_bf16 v[112:115], v[156:159], v[172:175], v[112:115]
	v_mfma_f32_16x16x32_bf16 v[100:103], v[148:151], v[180:183], v[100:103]
	v_mfma_f32_16x16x32_bf16 v[96:99], v[156:159], v[180:183], v[96:99]
	v_mfma_f32_16x16x32_bf16 v[84:87], v[148:151], v[188:191], v[84:87]
	v_mfma_f32_16x16x32_bf16 v[80:83], v[156:159], v[188:191], v[80:83]
	v_mfma_f32_16x16x32_bf16 v[124:127], v[152:155], v[168:171], v[124:127]
	v_mfma_f32_16x16x32_bf16 v[120:123], v[160:163], v[168:171], v[120:123]
	v_mfma_f32_16x16x32_bf16 v[116:119], v[152:155], v[176:179], v[116:119]
	v_mfma_f32_16x16x32_bf16 v[112:115], v[160:163], v[176:179], v[112:115]
	v_mfma_f32_16x16x32_bf16 v[100:103], v[152:155], v[184:187], v[100:103]
	v_mfma_f32_16x16x32_bf16 v[96:99], v[160:163], v[184:187], v[96:99]
	v_mfma_f32_16x16x32_bf16 v[84:87], v[152:155], v[192:195], v[84:87]
	v_mfma_f32_16x16x32_bf16 v[80:83], v[160:163], v[192:195], v[80:83]
	s_barrier
	s_mov_b32 m0, s40
	v_lshl_add_u64 v[212:213], s[20:21], 0, v[130:131]
	ds_read_b128 v[196:199], v146
	ds_read_b128 v[200:203], v146 offset:1024
	ds_read_b128 v[204:207], v146 offset:2048
	ds_read_b128 v[208:211], v146 offset:3072
	global_load_lds_dwordx4 v[212:213], off
	v_lshl_add_u64 v[214:215], s[20:21], 0, v[128:129]
	s_mov_b32 m0, s41
	s_nop 0
	global_load_lds_dwordx4 v[214:215], off
	s_barrier
	s_waitcnt lgkmcnt(0)
	v_mfma_f32_16x16x32_bf16 v[108:111], v[196:199], v[164:167], v[108:111]
	v_mfma_f32_16x16x32_bf16 v[104:107], v[204:207], v[164:167], v[104:107]
	v_mfma_f32_16x16x32_bf16 v[92:95], v[196:199], v[172:175], v[92:95]
	v_mfma_f32_16x16x32_bf16 v[88:91], v[204:207], v[172:175], v[88:91]
	v_mfma_f32_16x16x32_bf16 v[76:79], v[196:199], v[180:183], v[76:79]
	v_mfma_f32_16x16x32_bf16 v[72:75], v[204:207], v[180:183], v[72:75]
	v_mfma_f32_16x16x32_bf16 v[68:71], v[196:199], v[188:191], v[68:71]
	v_mfma_f32_16x16x32_bf16 v[64:67], v[204:207], v[188:191], v[64:67]
	v_mfma_f32_16x16x32_bf16 v[108:111], v[200:203], v[168:171], v[108:111]
	v_mfma_f32_16x16x32_bf16 v[104:107], v[208:211], v[168:171], v[104:107]
	v_mfma_f32_16x16x32_bf16 v[92:95], v[200:203], v[176:179], v[92:95]
	v_mfma_f32_16x16x32_bf16 v[88:91], v[208:211], v[176:179], v[88:91]
	v_mfma_f32_16x16x32_bf16 v[76:79], v[200:203], v[184:187], v[76:79]
	v_mfma_f32_16x16x32_bf16 v[72:75], v[208:211], v[184:187], v[72:75]
	v_mfma_f32_16x16x32_bf16 v[68:71], v[200:203], v[192:195], v[68:71]
	v_mfma_f32_16x16x32_bf16 v[64:67], v[208:211], v[192:195], v[64:67]
	s_mov_b32 m0, s30
	v_lshl_add_u64 v[216:217], s[22:23], 0, v[130:131]
	s_barrier
	ds_read_b128 v[164:167], v145 offset:16384
	ds_read_b128 v[168:171], v145 offset:17408
	ds_read_b128 v[172:175], v145 offset:18432
	ds_read_b128 v[176:179], v145 offset:19456
	ds_read_b128 v[180:183], v145 offset:20480
	ds_read_b128 v[184:187], v145 offset:21504
	ds_read_b128 v[188:191], v145 offset:22528
	ds_read_b128 v[192:195], v145 offset:23552
	global_load_lds_dwordx4 v[216:217], off
	v_lshl_add_u64 v[218:219], s[22:23], 0, v[128:129]
	s_mov_b32 m0, s31
	s_nop 0
	global_load_lds_dwordx4 v[218:219], off
	s_barrier
	s_waitcnt lgkmcnt(0)
	v_mfma_f32_16x16x32_bf16 v[60:63], v[148:151], v[164:167], v[60:63]
	v_mfma_f32_16x16x32_bf16 v[56:59], v[156:159], v[164:167], v[56:59]
	v_mfma_f32_16x16x32_bf16 v[52:55], v[148:151], v[172:175], v[52:55]
	v_mfma_f32_16x16x32_bf16 v[48:51], v[156:159], v[172:175], v[48:51]
	v_mfma_f32_16x16x32_bf16 v[36:39], v[148:151], v[180:183], v[36:39]
	v_mfma_f32_16x16x32_bf16 v[32:35], v[156:159], v[180:183], v[32:35]
	v_mfma_f32_16x16x32_bf16 v[20:23], v[148:151], v[188:191], v[20:23]
	v_mfma_f32_16x16x32_bf16 v[16:19], v[156:159], v[188:191], v[16:19]
	v_mfma_f32_16x16x32_bf16 v[60:63], v[152:155], v[168:171], v[60:63]
	v_mfma_f32_16x16x32_bf16 v[56:59], v[160:163], v[168:171], v[56:59]
	v_mfma_f32_16x16x32_bf16 v[52:55], v[152:155], v[176:179], v[52:55]
	v_mfma_f32_16x16x32_bf16 v[48:51], v[160:163], v[176:179], v[48:51]
	v_mfma_f32_16x16x32_bf16 v[36:39], v[152:155], v[184:187], v[36:39]
	v_mfma_f32_16x16x32_bf16 v[32:35], v[160:163], v[184:187], v[32:35]
	v_mfma_f32_16x16x32_bf16 v[20:23], v[152:155], v[192:195], v[20:23]
	v_mfma_f32_16x16x32_bf16 v[16:19], v[160:163], v[192:195], v[16:19]
	s_barrier
	s_add_u32 s16, s20, 0x40000
	s_addc_u32 s17, s21, 0
	s_mov_b32 m0, s44
	v_lshl_add_u64 v[148:149], s[16:17], 0, v[130:131]
	global_load_lds_dwordx4 v[148:149], off
	v_lshl_add_u64 v[148:149], s[16:17], 0, v[128:129]
	s_add_i32 m0, s44, 0x2000
	s_nop 0
	global_load_lds_dwordx4 v[148:149], off
	s_waitcnt vmcnt(6)
	s_barrier
; #define STG(P, GB) do { const char* _gb = (GB); \
;     _Pragma("unroll") for (int _i = 0; _i < 2; ++_i) { \
;       __builtin_amdgcn_global_load_lds((const unsigned*)(_gb + voff[_i]), \
;         (LAS unsigned*)((LAS char*)(P) + ldsw + _i * 8192), 16, 0, 0); } } while (0)
; #define LDA(dst, b, h) _Pragma("unroll") for (int m = 0; m < 4; ++m) _Pragma("unroll") for (int k = 0; k < 2; ++k) \
;     dst[m][k] = *(const LAS bf16x8*)((LAS char*)SA(b, h) + aoff + m * 2048 + k * 1024)
; #define LDB(dst, b, h) _Pragma("unroll") for (int n = 0; n < 2; ++n) _Pragma("unroll") for (int k = 0; k < 2; ++k) \
;     dst[n][k] = *(const LAS bf16x8*)((LAS char*)SB(b, h) + boff + n * 2048 + k * 1024)
; #define MMA(ai, bj, At_, Bt_) do { __builtin_amdgcn_s_setprio(1); \
;     _Pragma("unroll") for (int m = 0; m < 4; ++m) _Pragma("unroll") for (int n = 0; n < 2; ++n) _Pragma("unroll") for (int k = 0; k < 2; ++k) \
;       acc[ai][bj][m][n] = __builtin_amdgcn_mfma_f32_16x16x32_bf16(Bt_[n][k], At_[m][k], acc[ai][bj][m][n], 0, 0, 0); \
;     __builtin_amdgcn_s_setprio(0); } while (0)
; #define WAIT_V(n) asm volatile("s_waitcnt vmcnt(" #n ")" ::: "memory")
; #define WAIT_L(n) asm volatile("s_waitcnt lgkmcnt(" #n ")" ::: "memory")
; #define BAR __builtin_amdgcn_s_barrier()
; #define SCHED __builtin_amdgcn_sched_barrier(0)
; __device__ __forceinline__ void gemm_phase(const bf16_t* __restrict__ A, const bf16_t* __restrict__ Bt, bf16_t* __restrict__ C, int M, int N, int K,
;                                            int ldc, const int EPI, char* smem, const int wid_u) {
;     ...
;       WAIT_V(6); BAR; MMA(1, 1, At, B1); BAR;
;       LDB(B0, 1, 0); SCHED; LDA(At, 1, 0); STG(SA(0, 1), a2 + hstep);
;       WAIT_L(8); BAR; WAIT_L(0); MMA(0, 0, At, B0); BAR; SCHED;
;       LDB(B1, 1, 1); STG(SB(1, 0), b3);
;       BAR; WAIT_L(0); MMA(0, 1, At, B1); BAR;
;       LDA(At, 1, 1); STG(SA(1, 0), a3);
	v_mfma_f32_16x16x32_bf16 v[44:47], v[196:199], v[164:167], v[44:47]
	v_mfma_f32_16x16x32_bf16 v[40:43], v[204:207], v[164:167], v[40:43]
	v_mfma_f32_16x16x32_bf16 v[28:31], v[196:199], v[172:175], v[28:31]
	v_mfma_f32_16x16x32_bf16 v[24:27], v[204:207], v[172:175], v[24:27]
	v_mfma_f32_16x16x32_bf16 v[12:15], v[196:199], v[180:183], v[12:15]
	v_mfma_f32_16x16x32_bf16 v[8:11], v[204:207], v[180:183], v[8:11]
	v_mfma_f32_16x16x32_bf16 v[4:7], v[196:199], v[188:191], v[4:7]
	v_mfma_f32_16x16x32_bf16 v[0:3], v[204:207], v[188:191], v[0:3]
	v_mfma_f32_16x16x32_bf16 v[44:47], v[200:203], v[168:171], v[44:47]
	v_mfma_f32_16x16x32_bf16 v[40:43], v[208:211], v[168:171], v[40:43]
	v_mfma_f32_16x16x32_bf16 v[28:31], v[200:203], v[176:179], v[28:31]
	v_mfma_f32_16x16x32_bf16 v[24:27], v[208:211], v[176:179], v[24:27]
	v_mfma_f32_16x16x32_bf16 v[12:15], v[200:203], v[184:187], v[12:15]
	v_mfma_f32_16x16x32_bf16 v[8:11], v[208:211], v[184:187], v[8:11]
	v_mfma_f32_16x16x32_bf16 v[4:7], v[200:203], v[192:195], v[4:7]
	v_mfma_f32_16x16x32_bf16 v[0:3], v[208:211], v[192:195], v[0:3]
	s_add_i32 s56, 0, 0x18000
	v_add_u32_e32 v147, s56, v143
	s_barrier
	ds_read_b128 v[148:151], v147
	ds_read_b128 v[152:155], v147 offset:1024
	ds_read_b128 v[156:159], v147 offset:2048
	ds_read_b128 v[160:163], v147 offset:3072
	s_add_u32 s16, s22, 0x40000
	s_addc_u32 s17, s23, 0
	s_mov_b32 m0, s34
	v_lshl_add_u64 v[196:197], s[16:17], 0, v[130:131]
	ds_read_b128 v[164:167], v145 offset:32768
	ds_read_b128 v[168:171], v145 offset:33792
	ds_read_b128 v[172:175], v145 offset:34816
	ds_read_b128 v[176:179], v145 offset:35840
	ds_read_b128 v[180:183], v145 offset:36864
	ds_read_b128 v[184:187], v145 offset:37888
	ds_read_b128 v[188:191], v145 offset:38912
	ds_read_b128 v[192:195], v145 offset:39936
	global_load_lds_dwordx4 v[196:197], off
	v_lshl_add_u64 v[196:197], s[16:17], 0, v[128:129]
	s_mov_b32 m0, s35
	s_nop 0
	global_load_lds_dwordx4 v[196:197], off
	s_waitcnt lgkmcnt(8)
	s_barrier
	s_waitcnt lgkmcnt(0)
	v_mfma_f32_16x16x32_bf16 v[124:127], v[148:151], v[164:167], v[124:127]
	v_mfma_f32_16x16x32_bf16 v[120:123], v[156:159], v[164:167], v[120:123]
	v_mfma_f32_16x16x32_bf16 v[116:119], v[148:151], v[172:175], v[116:119]
	v_mfma_f32_16x16x32_bf16 v[112:115], v[156:159], v[172:175], v[112:115]
	v_mfma_f32_16x16x32_bf16 v[100:103], v[148:151], v[180:183], v[100:103]
	v_mfma_f32_16x16x32_bf16 v[96:99], v[156:159], v[180:183], v[96:99]
	v_mfma_f32_16x16x32_bf16 v[84:87], v[148:151], v[188:191], v[84:87]
	v_mfma_f32_16x16x32_bf16 v[80:83], v[156:159], v[188:191], v[80:83]
	v_mfma_f32_16x16x32_bf16 v[124:127], v[152:155], v[168:171], v[124:127]
	v_mfma_f32_16x16x32_bf16 v[120:123], v[160:163], v[168:171], v[120:123]
	v_mfma_f32_16x16x32_bf16 v[116:119], v[152:155], v[176:179], v[116:119]
	v_mfma_f32_16x16x32_bf16 v[112:115], v[160:163], v[176:179], v[112:115]
	v_mfma_f32_16x16x32_bf16 v[100:103], v[152:155], v[184:187], v[100:103]
	v_mfma_f32_16x16x32_bf16 v[96:99], v[160:163], v[184:187], v[96:99]
	v_mfma_f32_16x16x32_bf16 v[84:87], v[152:155], v[192:195], v[84:87]
	v_mfma_f32_16x16x32_bf16 v[80:83], v[160:163], v[192:195], v[80:83]
	s_barrier
	s_add_i32 s22, 0, 0x1c000
	s_add_i32 s16, s56, s29
	v_add_u32_e32 v147, s22, v143
	v_lshl_add_u64 v[212:213], v[212:213], 0, s[10:11]
	s_mov_b32 m0, s16
	ds_read_b128 v[196:199], v147
	ds_read_b128 v[200:203], v147 offset:1024
	ds_read_b128 v[204:207], v147 offset:2048
	ds_read_b128 v[208:211], v147 offset:3072
	global_load_lds_dwordx4 v[212:213], off
	v_lshl_add_u64 v[212:213], v[214:215], 0, s[10:11]
	s_add_i32 m0, s16, 0x2000
	s_nop 0
	global_load_lds_dwordx4 v[212:213], off
	s_barrier
	s_waitcnt lgkmcnt(0)
	v_mfma_f32_16x16x32_bf16 v[108:111], v[196:199], v[164:167], v[108:111]
	v_mfma_f32_16x16x32_bf16 v[104:107], v[204:207], v[164:167], v[104:107]
	v_mfma_f32_16x16x32_bf16 v[92:95], v[196:199], v[172:175], v[92:95]
	v_mfma_f32_16x16x32_bf16 v[88:91], v[204:207], v[172:175], v[88:91]
	v_mfma_f32_16x16x32_bf16 v[76:79], v[196:199], v[180:183], v[76:79]
	v_mfma_f32_16x16x32_bf16 v[72:75], v[204:207], v[180:183], v[72:75]
	v_mfma_f32_16x16x32_bf16 v[68:71], v[196:199], v[188:191], v[68:71]
	v_mfma_f32_16x16x32_bf16 v[64:67], v[204:207], v[188:191], v[64:67]
	v_mfma_f32_16x16x32_bf16 v[108:111], v[200:203], v[168:171], v[108:111]
	v_mfma_f32_16x16x32_bf16 v[104:107], v[208:211], v[168:171], v[104:107]
	v_mfma_f32_16x16x32_bf16 v[92:95], v[200:203], v[176:179], v[92:95]
	v_mfma_f32_16x16x32_bf16 v[88:91], v[208:211], v[176:179], v[88:91]
	v_mfma_f32_16x16x32_bf16 v[76:79], v[200:203], v[184:187], v[76:79]
	v_mfma_f32_16x16x32_bf16 v[72:75], v[208:211], v[184:187], v[72:75]
	v_mfma_f32_16x16x32_bf16 v[68:71], v[200:203], v[192:195], v[68:71]
	v_mfma_f32_16x16x32_bf16 v[64:67], v[208:211], v[192:195], v[64:67]
	s_mov_b32 m0, s36
	v_lshl_add_u64 v[212:213], v[216:217], 0, s[10:11]
	s_barrier
	ds_read_b128 v[164:167], v145 offset:49152
	ds_read_b128 v[168:171], v145 offset:50176
	ds_read_b128 v[172:175], v145 offset:51200
	ds_read_b128 v[176:179], v145 offset:52224
	ds_read_b128 v[180:183], v145 offset:53248
	ds_read_b128 v[184:187], v145 offset:54272
	ds_read_b128 v[188:191], v145 offset:55296
	ds_read_b128 v[192:195], v145 offset:56320
	global_load_lds_dwordx4 v[212:213], off
	v_lshl_add_u64 v[212:213], v[218:219], 0, s[10:11]
	s_mov_b32 m0, s37
	s_nop 0
	global_load_lds_dwordx4 v[212:213], off
	s_barrier
; #define STG(P, GB) do { const char* _gb = (GB); \
;     _Pragma("unroll") for (int _i = 0; _i < 2; ++_i) { \
;       __builtin_amdgcn_global_load_lds((const unsigned*)(_gb + voff[_i]), \
;         (LAS unsigned*)((LAS char*)(P) + ldsw + _i * 8192), 16, 0, 0); } } while (0)
; #define MMA(ai, bj, At_, Bt_) do { __builtin_amdgcn_s_setprio(1); \
;     _Pragma("unroll") for (int m = 0; m < 4; ++m) _Pragma("unroll") for (int n = 0; n < 2; ++n) _Pragma("unroll") for (int k = 0; k < 2; ++k) \
;       acc[ai][bj][m][n] = __builtin_amdgcn_mfma_f32_16x16x32_bf16(Bt_[n][k], At_[m][k], acc[ai][bj][m][n], 0, 0, 0); \
;     __builtin_amdgcn_s_setprio(0); } while (0)
; #define WAIT_V(n) asm volatile("s_waitcnt vmcnt(" #n ")" ::: "memory")
; #define WAIT_L(n) asm volatile("s_waitcnt lgkmcnt(" #n ")" ::: "memory")
; #define BAR __builtin_amdgcn_s_barrier()
; #define SCHED __builtin_amdgcn_sched_barrier(0)
; __device__ __forceinline__ void gemm_phase(const bf16_t* __restrict__ A, const bf16_t* __restrict__ Bt, bf16_t* __restrict__ C, int M, int N, int K,
;                                            int ldc, const int EPI, char* smem, const int wid_u) {
;     ...
;       BAR; WAIT_L(0); MMA(1, 0, At, B0); BAR; SCHED;
;       STG(SB(1, 1), b3 + hstep);
;       WAIT_V(6); BAR; MMA(1, 1, At, B1); BAR;
;     }
	s_waitcnt lgkmcnt(0)
	v_mfma_f32_16x16x32_bf16 v[60:63], v[148:151], v[164:167], v[60:63]
	v_mfma_f32_16x16x32_bf16 v[56:59], v[156:159], v[164:167], v[56:59]
	v_mfma_f32_16x16x32_bf16 v[52:55], v[148:151], v[172:175], v[52:55]
	v_mfma_f32_16x16x32_bf16 v[48:51], v[156:159], v[172:175], v[48:51]
	v_mfma_f32_16x16x32_bf16 v[36:39], v[148:151], v[180:183], v[36:39]
	v_mfma_f32_16x16x32_bf16 v[32:35], v[156:159], v[180:183], v[32:35]
	v_mfma_f32_16x16x32_bf16 v[20:23], v[148:151], v[188:191], v[20:23]
	v_mfma_f32_16x16x32_bf16 v[16:19], v[156:159], v[188:191], v[16:19]
	v_mfma_f32_16x16x32_bf16 v[60:63], v[152:155], v[168:171], v[60:63]
	v_mfma_f32_16x16x32_bf16 v[56:59], v[160:163], v[168:171], v[56:59]
	v_mfma_f32_16x16x32_bf16 v[52:55], v[152:155], v[176:179], v[52:55]
	v_mfma_f32_16x16x32_bf16 v[48:51], v[160:163], v[176:179], v[48:51]
	v_mfma_f32_16x16x32_bf16 v[36:39], v[152:155], v[184:187], v[36:39]
	v_mfma_f32_16x16x32_bf16 v[32:35], v[160:163], v[184:187], v[32:35]
	v_mfma_f32_16x16x32_bf16 v[20:23], v[152:155], v[192:195], v[20:23]
	v_mfma_f32_16x16x32_bf16 v[16:19], v[160:163], v[192:195], v[16:19]
	s_barrier
	s_add_u32 s16, s20, 0x40080
	s_addc_u32 s17, s21, 0
	s_add_i32 s20, s22, s29
	v_lshl_add_u64 v[148:149], s[16:17], 0, v[130:131]
	s_mov_b32 m0, s20
	s_nop 0
	global_load_lds_dwordx4 v[148:149], off
	v_lshl_add_u64 v[148:149], s[16:17], 0, v[128:129]
	s_add_i32 m0, s20, 0x2000
	s_nop 0
	global_load_lds_dwordx4 v[148:149], off
	s_waitcnt vmcnt(6)
	s_barrier
	v_mfma_f32_16x16x32_bf16 v[44:47], v[196:199], v[164:167], v[44:47]
	v_mfma_f32_16x16x32_bf16 v[40:43], v[204:207], v[164:167], v[40:43]
	v_mfma_f32_16x16x32_bf16 v[28:31], v[196:199], v[172:175], v[28:31]
	v_mfma_f32_16x16x32_bf16 v[24:27], v[204:207], v[172:175], v[24:27]
	v_mfma_f32_16x16x32_bf16 v[12:15], v[196:199], v[180:183], v[12:15]
	v_mfma_f32_16x16x32_bf16 v[8:11], v[204:207], v[180:183], v[8:11]
	v_mfma_f32_16x16x32_bf16 v[4:7], v[196:199], v[188:191], v[4:7]
	v_mfma_f32_16x16x32_bf16 v[0:3], v[204:207], v[188:191], v[0:3]
	v_mfma_f32_16x16x32_bf16 v[44:47], v[200:203], v[168:171], v[44:47]
	v_mfma_f32_16x16x32_bf16 v[40:43], v[208:211], v[168:171], v[40:43]
	v_mfma_f32_16x16x32_bf16 v[28:31], v[200:203], v[176:179], v[28:31]
	v_mfma_f32_16x16x32_bf16 v[24:27], v[208:211], v[176:179], v[24:27]
	v_mfma_f32_16x16x32_bf16 v[12:15], v[200:203], v[184:187], v[12:15]
	v_mfma_f32_16x16x32_bf16 v[8:11], v[208:211], v[184:187], v[8:11]
	v_mfma_f32_16x16x32_bf16 v[4:7], v[200:203], v[192:195], v[4:7]
	v_mfma_f32_16x16x32_bf16 v[0:3], v[208:211], v[192:195], v[0:3]
	s_add_i32 s55, s55, 2
	s_add_u32 s53, s53, 0x100
	s_addc_u32 s54, s54, 0
	s_cmp_gt_u32 s55, 13
	s_mov_b64 s[16:17], s[18:19]
	s_barrier
	s_cbranch_scc0 .LBB0_905
; #define WAIT_V(n) asm volatile("s_waitcnt vmcnt(" #n ")" ::: "memory")
; #define BAR __builtin_amdgcn_s_barrier()
; __device__ __forceinline__ void gemm_phase(const bf16_t* __restrict__ A, const bf16_t* __restrict__ Bt, bf16_t* __restrict__ C, int M, int N, int K,
;                                            int ldc, const int EPI, char* smem, const int wid_u) {
;     ...
;           const size_t row = (size_t)(brow + ai * HALF + wr * 64 + m * 16 + fr);
;           if (EPI == 0) {
; #pragma unroll
;             for (int bj = 0; bj < 2; ++bj) {
;               const f32x4 v0 = acc[ai][bj][m][0], v1 = acc[ai][bj][m][1];
;               uint4 u; u.x = cvt_pk_bf16(v0[0], v0[1]); u.y = cvt_pk_bf16(v0[2], v0[3]); u.z = cvt_pk_bf16(v1[0], v1[1]); u.w = cvt_pk_bf16(v1[2], v1[3]);
;               *(uint4*)(C + row * ldc + bcol + bj * HALF + wc * 32 + fq * 8) = u;
;             }
;     ...
;     if (!has_next) break;
; #pragma unroll
;     for (int a = 0; a < 2; ++a)
; #pragma unroll
;       for (int b = 0; b < 2; ++b)
; #pragma unroll
;         for (int m = 0; m < 4; ++m)
; #pragma unroll
;           for (int n = 0; n < 2; ++n) acc[a][b][m][n] = (f32x4){0.f, 0.f, 0.f, 0.f};
;     pm = npm; pn = npn; cA = nA; cB = nB; ++ui;
;   }
;   WAIT_V(0);
;   if (wr == 0) BAR;
;   BAR;
	v_lshl_add_u32 v148, s47, 8, v142
	v_cvt_pk_bf16_f32 v68, v68, v69
	v_cvt_pk_bf16_f32 v69, v70, v71
	v_cvt_pk_bf16_f32 v70, v64, v65
	v_add_u32_e32 v64, 0x80, v148
	s_lshl_b32 s16, s48, 9
	s_mov_b32 s17, s9
	v_ashrrev_i32_e32 v149, 31, v148
	v_cvt_pk_bf16_f32 v108, v108, v109
	v_cvt_pk_bf16_f32 v109, v110, v111
	v_cvt_pk_bf16_f32 v110, v104, v105
	v_or_b32_e32 v104, 16, v148
	v_ashrrev_i32_e32 v65, 31, v64
	v_cvt_pk_bf16_f32 v44, v44, v45
	v_cvt_pk_bf16_f32 v45, v46, v47
	v_cvt_pk_bf16_f32 v46, v40, v41
	v_add_u32_e32 v40, 0x90, v148
	v_lshl_add_u64 v[150:151], v[132:133], 0, s[16:17]
	v_lshlrev_b64 v[152:153], 11, v[148:149]
	v_ashrrev_i32_e32 v105, 31, v104
	v_cvt_pk_bf16_f32 v92, v92, v93
	v_cvt_pk_bf16_f32 v93, v94, v95
	v_cvt_pk_bf16_f32 v94, v88, v89
	v_or_b32_e32 v88, 32, v148
	v_lshlrev_b64 v[64:65], 11, v[64:65]
	v_ashrrev_i32_e32 v41, 31, v40
	v_cvt_pk_bf16_f32 v28, v28, v29
	v_cvt_pk_bf16_f32 v29, v30, v31
	v_cvt_pk_bf16_f32 v30, v24, v25
	v_add_u32_e32 v24, 0xa0, v148
	v_lshl_add_u64 v[152:153], v[150:151], 0, v[152:153]
	v_cvt_pk_bf16_f32 v111, v106, v107
	v_lshlrev_b64 v[104:105], 11, v[104:105]
	v_ashrrev_i32_e32 v89, 31, v88
	v_cvt_pk_bf16_f32 v76, v76, v77
	v_cvt_pk_bf16_f32 v77, v78, v79
	v_cvt_pk_bf16_f32 v78, v72, v73
	v_or_b32_e32 v72, 48, v148
	v_lshl_add_u64 v[64:65], v[150:151], 0, v[64:65]
	v_cvt_pk_bf16_f32 v47, v42, v43
	v_lshlrev_b64 v[40:41], 11, v[40:41]
	v_ashrrev_i32_e32 v25, 31, v24
	v_cvt_pk_bf16_f32 v12, v12, v13
	v_cvt_pk_bf16_f32 v13, v14, v15
	v_cvt_pk_bf16_f32 v14, v8, v9
	v_add_u32_e32 v8, 0xb0, v148
	global_store_dwordx4 v[152:153], v[108:111], off offset:256
	v_cvt_pk_bf16_f32 v95, v90, v91
	v_lshlrev_b64 v[88:89], 11, v[88:89]
	v_lshl_add_u64 v[108:109], v[150:151], 0, v[104:105]
	v_ashrrev_i32_e32 v73, 31, v72
	global_store_dwordx4 v[64:65], v[44:47], off offset:256
	v_cvt_pk_bf16_f32 v31, v26, v27
	v_lshlrev_b64 v[24:25], 11, v[24:25]
	v_lshl_add_u64 v[44:45], v[150:151], 0, v[40:41]
	v_ashrrev_i32_e32 v9, 31, v8
	global_store_dwordx4 v[108:109], v[92:95], off offset:256
	v_cvt_pk_bf16_f32 v79, v74, v75
	v_lshlrev_b64 v[72:73], 11, v[72:73]
	v_lshl_add_u64 v[92:93], v[150:151], 0, v[88:89]
	global_store_dwordx4 v[44:45], v[28:31], off offset:256
	v_cvt_pk_bf16_f32 v15, v10, v11
	v_lshlrev_b64 v[8:9], 11, v[8:9]
	v_lshl_add_u64 v[28:29], v[150:151], 0, v[24:25]
	v_cvt_pk_bf16_f32 v124, v124, v125
	v_cvt_pk_bf16_f32 v125, v126, v127
	v_cvt_pk_bf16_f32 v126, v120, v121
	v_cvt_pk_bf16_f32 v127, v122, v123
	v_cvt_pk_bf16_f32 v104, v116, v117
	v_cvt_pk_bf16_f32 v105, v118, v119
	v_cvt_pk_bf16_f32 v106, v112, v113
	v_cvt_pk_bf16_f32 v107, v114, v115
	v_cvt_pk_bf16_f32 v88, v100, v101
	v_cvt_pk_bf16_f32 v89, v102, v103
	v_cvt_pk_bf16_f32 v90, v96, v97
	v_cvt_pk_bf16_f32 v91, v98, v99
	global_store_dwordx4 v[92:93], v[76:79], off offset:256
	v_cvt_pk_bf16_f32 v74, v80, v81
	v_cvt_pk_bf16_f32 v75, v82, v83
	v_lshl_add_u64 v[76:77], v[150:151], 0, v[72:73]
	v_cvt_pk_bf16_f32 v72, v84, v85
	v_cvt_pk_bf16_f32 v73, v86, v87
	v_cvt_pk_bf16_f32 v71, v66, v67
	v_cvt_pk_bf16_f32 v60, v60, v61
	v_cvt_pk_bf16_f32 v61, v62, v63
	v_cvt_pk_bf16_f32 v62, v56, v57
	v_cvt_pk_bf16_f32 v63, v58, v59
	v_cvt_pk_bf16_f32 v40, v52, v53
	v_cvt_pk_bf16_f32 v41, v54, v55
	v_cvt_pk_bf16_f32 v42, v48, v49
	v_cvt_pk_bf16_f32 v43, v50, v51
	v_cvt_pk_bf16_f32 v24, v36, v37
	v_cvt_pk_bf16_f32 v25, v38, v39
	v_cvt_pk_bf16_f32 v26, v32, v33
	v_cvt_pk_bf16_f32 v27, v34, v35
	global_store_dwordx4 v[28:29], v[12:15], off offset:256
	v_cvt_pk_bf16_f32 v10, v16, v17
	v_cvt_pk_bf16_f32 v11, v18, v19
	v_lshl_add_u64 v[12:13], v[150:151], 0, v[8:9]
	v_cvt_pk_bf16_f32 v8, v20, v21
	v_cvt_pk_bf16_f32 v9, v22, v23
	v_cvt_pk_bf16_f32 v4, v4, v5
	v_cvt_pk_bf16_f32 v5, v6, v7
	v_cvt_pk_bf16_f32 v6, v0, v1
	v_cvt_pk_bf16_f32 v7, v2, v3
	s_and_b64 vcc, exec, s[4:5]
	s_mov_b32 s47, s8
	s_mov_b32 s48, s46
	s_mov_b64 s[18:19], s[14:15]
	s_mov_b64 s[16:17], s[12:13]
	global_store_dwordx4 v[152:153], v[124:127], off
	global_store_dwordx4 v[108:109], v[104:107], off
	global_store_dwordx4 v[92:93], v[88:91], off
	global_store_dwordx4 v[76:77], v[72:75], off
	global_store_dwordx4 v[76:77], v[68:71], off offset:256
	global_store_dwordx4 v[64:65], v[60:63], off
	global_store_dwordx4 v[44:45], v[40:43], off
	global_store_dwordx4 v[28:29], v[24:27], off
	global_store_dwordx4 v[12:13], v[8:11], off
	global_store_dwordx4 v[12:13], v[4:7], off offset:256
	s_cbranch_vccz .LBB0_902
	s_waitcnt vmcnt(0)
	s_cmpk_gt_u32 s24, 0xff
	s_cbranch_scc1 .LBB0_909
	s_barrier

; #define STG(P, GB) do { const char* _gb = (GB); \
;     _Pragma("unroll") for (int _i = 0; _i < 2; ++_i) { \
;       __builtin_amdgcn_global_load_lds((const unsigned*)(_gb + voff[_i]), \
;         (LAS unsigned*)((LAS char*)(P) + ldsw + _i * 8192), 16, 0, 0); } } while (0)
; #define LDA(dst, b, h) _Pragma("unroll") for (int m = 0; m < 4; ++m) _Pragma("unroll") for (int k = 0; k < 2; ++k) \
;     dst[m][k] = *(const LAS bf16x8*)((LAS char*)SA(b, h) + aoff + m * 2048 + k * 1024)
; #define LDB(dst, b, h) _Pragma("unroll") for (int n = 0; n < 2; ++n) _Pragma("unroll") for (int k = 0; k < 2; ++k) \
;     dst[n][k] = *(const LAS bf16x8*)((LAS char*)SB(b, h) + boff + n * 2048 + k * 1024)
; #define MMA(ai, bj, At_, Bt_) do { __builtin_amdgcn_s_setprio(1); \
;     _Pragma("unroll") for (int m = 0; m < 4; ++m) _Pragma("unroll") for (int n = 0; n < 2; ++n) _Pragma("unroll") for (int k = 0; k < 2; ++k) \
;       acc[ai][bj][m][n] = __builtin_amdgcn_mfma_f32_16x16x32_bf16(Bt_[n][k], At_[m][k], acc[ai][bj][m][n], 0, 0, 0); \
;     __builtin_amdgcn_s_setprio(0); } while (0)
; #define WAIT_L(n) asm volatile("s_waitcnt lgkmcnt(" #n ")" ::: "memory")
; #define BAR __builtin_amdgcn_s_barrier()
; #define SCHED __builtin_amdgcn_sched_barrier(0)
; __device__ __forceinline__ void gemm_phase(const bf16_t* __restrict__ A, const bf16_t* __restrict__ Bt, bf16_t* __restrict__ C, int M, int N, int K,
;                                            int ldc, const int EPI, char* smem, const int wid_u) {
;     ...
;       const bool last = (t == nt - 2);
;       const char* a1 = cA + (size_t)(t + 1) * kstep;
;       const char* a2 = last ? nA : cA + (size_t)(t + 2) * kstep;
;       const char* b2 = last ? nB : cB + (size_t)(t + 2) * kstep;
;       const char* a3 = a2 + kstep;
;       const char* b3 = b2 + kstep;
;       LDB(B0, 0, 0); SCHED; LDA(At, 0, 0); STG(SA(1, 1), a1 + hstep);
;       WAIT_L(8); BAR; WAIT_L(0); MMA(0, 0, At, B0); BAR; SCHED;
;       LDB(B1, 0, 1); STG(SB(0, 0), b2);
;       BAR; WAIT_L(0); MMA(0, 1, At, B1); BAR;
;       LDA(At, 0, 1); STG(SA(0, 0), a2);
;       BAR; WAIT_L(0); MMA(1, 0, At, B0); BAR; SCHED;
.LBB0_1026:
	ds_read_b128 v[150:153], v146
	ds_read_b128 v[154:157], v146 offset:1024
	ds_read_b128 v[158:161], v146 offset:2048
	ds_read_b128 v[162:165], v146 offset:3072
	s_add_u32 s20, s18, 0x100
	s_addc_u32 s21, s19, 0
	s_cmp_eq_u32 s53, 12
	s_cselect_b32 s25, s48, s21
	s_cselect_b32 s24, s49, s20
	s_cselect_b32 s23, s13, s52
	s_cselect_b32 s22, s50, s51
	v_lshl_add_u64 v[142:143], s[18:19], 0, v[136:137]
	s_add_i32 m0, s34, 0xc000
	ds_read_b128 v[166:169], v147
	ds_read_b128 v[170:173], v147 offset:1024
	ds_read_b128 v[174:177], v147 offset:2048
	ds_read_b128 v[178:181], v147 offset:3072
	ds_read_b128 v[182:185], v147 offset:4096
	ds_read_b128 v[186:189], v147 offset:5120
	ds_read_b128 v[190:193], v147 offset:6144
	ds_read_b128 v[194:197], v147 offset:7168
	global_load_lds_dwordx4 v[142:143], off
	v_lshl_add_u64 v[142:143], s[18:19], 0, v[134:135]
	s_add_i32 m0, s34, 0xe000
	s_nop 0
	global_load_lds_dwordx4 v[142:143], off
	s_waitcnt lgkmcnt(8)
	s_barrier
	s_waitcnt lgkmcnt(0)
	v_mfma_f32_16x16x32_bf16 v[124:127], v[150:153], v[166:169], v[124:127]
	v_mfma_f32_16x16x32_bf16 v[120:123], v[158:161], v[166:169], v[120:123]
	v_mfma_f32_16x16x32_bf16 v[108:111], v[150:153], v[174:177], v[108:111]
	v_mfma_f32_16x16x32_bf16 v[104:107], v[158:161], v[174:177], v[104:107]
	v_mfma_f32_16x16x32_bf16 v[92:95], v[150:153], v[182:185], v[92:95]
	v_mfma_f32_16x16x32_bf16 v[88:91], v[158:161], v[182:185], v[88:91]
	v_mfma_f32_16x16x32_bf16 v[76:79], v[150:153], v[190:193], v[76:79]
	v_mfma_f32_16x16x32_bf16 v[72:75], v[158:161], v[190:193], v[72:75]
	v_mfma_f32_16x16x32_bf16 v[124:127], v[154:157], v[170:173], v[124:127]
	v_mfma_f32_16x16x32_bf16 v[120:123], v[162:165], v[170:173], v[120:123]
	v_mfma_f32_16x16x32_bf16 v[108:111], v[154:157], v[178:181], v[108:111]
	v_mfma_f32_16x16x32_bf16 v[104:107], v[162:165], v[178:181], v[104:107]
	v_mfma_f32_16x16x32_bf16 v[92:95], v[154:157], v[186:189], v[92:95]
	v_mfma_f32_16x16x32_bf16 v[88:91], v[162:165], v[186:189], v[88:91]
	v_mfma_f32_16x16x32_bf16 v[76:79], v[154:157], v[194:197], v[76:79]
	v_mfma_f32_16x16x32_bf16 v[72:75], v[162:165], v[194:197], v[72:75]
	s_barrier
	s_add_i32 s18, s40, s31
	v_lshl_add_u64 v[142:143], s[22:23], 0, v[130:131]
	s_mov_b32 m0, s18
	ds_read_b128 v[198:201], v148
	ds_read_b128 v[202:205], v148 offset:1024
	ds_read_b128 v[206:209], v148 offset:2048
	ds_read_b128 v[210:213], v148 offset:3072
	global_load_lds_dwordx4 v[142:143], off
	v_lshl_add_u64 v[214:215], s[22:23], 0, v[128:129]
	s_add_i32 m0, s18, 0x2000
	s_nop 0
	global_load_lds_dwordx4 v[214:215], off
	s_barrier
	s_waitcnt lgkmcnt(0)
	v_mfma_f32_16x16x32_bf16 v[116:119], v[198:201], v[166:169], v[116:119]
	v_mfma_f32_16x16x32_bf16 v[112:115], v[206:209], v[166:169], v[112:115]
	v_mfma_f32_16x16x32_bf16 v[100:103], v[198:201], v[174:177], v[100:103]
	v_mfma_f32_16x16x32_bf16 v[96:99], v[206:209], v[174:177], v[96:99]
	v_mfma_f32_16x16x32_bf16 v[84:87], v[198:201], v[182:185], v[84:87]
	v_mfma_f32_16x16x32_bf16 v[80:83], v[206:209], v[182:185], v[80:83]
	v_mfma_f32_16x16x32_bf16 v[68:71], v[198:201], v[190:193], v[68:71]
	v_mfma_f32_16x16x32_bf16 v[64:67], v[206:209], v[190:193], v[64:67]
	v_mfma_f32_16x16x32_bf16 v[116:119], v[202:205], v[170:173], v[116:119]
	v_mfma_f32_16x16x32_bf16 v[112:115], v[210:213], v[170:173], v[112:115]
	v_mfma_f32_16x16x32_bf16 v[100:103], v[202:205], v[178:181], v[100:103]
	v_mfma_f32_16x16x32_bf16 v[96:99], v[210:213], v[178:181], v[96:99]
	v_mfma_f32_16x16x32_bf16 v[84:87], v[202:205], v[186:189], v[84:87]
	v_mfma_f32_16x16x32_bf16 v[80:83], v[210:213], v[186:189], v[80:83]
	v_mfma_f32_16x16x32_bf16 v[68:71], v[202:205], v[194:197], v[68:71]
	v_mfma_f32_16x16x32_bf16 v[64:67], v[210:213], v[194:197], v[64:67]
	s_mov_b32 m0, s34
	v_lshl_add_u64 v[216:217], s[24:25], 0, v[130:131]
	s_barrier
	ds_read_b128 v[166:169], v147 offset:16384
	ds_read_b128 v[170:173], v147 offset:17408
	ds_read_b128 v[174:177], v147 offset:18432
	ds_read_b128 v[178:181], v147 offset:19456
	ds_read_b128 v[182:185], v147 offset:20480
	ds_read_b128 v[186:189], v147 offset:21504
	ds_read_b128 v[190:193], v147 offset:22528
	ds_read_b128 v[194:197], v147 offset:23552
	global_load_lds_dwordx4 v[216:217], off
	v_lshl_add_u64 v[218:219], s[24:25], 0, v[128:129]
	s_mov_b32 m0, s35
	s_nop 0
	global_load_lds_dwordx4 v[218:219], off
	s_barrier
	s_waitcnt lgkmcnt(0)
	v_mfma_f32_16x16x32_bf16 v[60:63], v[150:153], v[166:169], v[60:63]
	v_mfma_f32_16x16x32_bf16 v[56:59], v[158:161], v[166:169], v[56:59]
	v_mfma_f32_16x16x32_bf16 v[44:47], v[150:153], v[174:177], v[44:47]
	v_mfma_f32_16x16x32_bf16 v[40:43], v[158:161], v[174:177], v[40:43]
	v_mfma_f32_16x16x32_bf16 v[28:31], v[150:153], v[182:185], v[28:31]
	v_mfma_f32_16x16x32_bf16 v[24:27], v[158:161], v[182:185], v[24:27]
	v_mfma_f32_16x16x32_bf16 v[12:15], v[150:153], v[190:193], v[12:15]
	v_mfma_f32_16x16x32_bf16 v[8:11], v[158:161], v[190:193], v[8:11]
	v_mfma_f32_16x16x32_bf16 v[60:63], v[154:157], v[170:173], v[60:63]
	v_mfma_f32_16x16x32_bf16 v[56:59], v[162:165], v[170:173], v[56:59]
	v_mfma_f32_16x16x32_bf16 v[44:47], v[154:157], v[178:181], v[44:47]
	v_mfma_f32_16x16x32_bf16 v[40:43], v[162:165], v[178:181], v[40:43]
	v_mfma_f32_16x16x32_bf16 v[28:31], v[154:157], v[186:189], v[28:31]
	v_mfma_f32_16x16x32_bf16 v[24:27], v[162:165], v[186:189], v[24:27]
	v_mfma_f32_16x16x32_bf16 v[12:15], v[154:157], v[194:197], v[12:15]
	v_mfma_f32_16x16x32_bf16 v[8:11], v[162:165], v[194:197], v[8:11]
	s_barrier
; #define STG(P, GB) do { const char* _gb = (GB); \
;     _Pragma("unroll") for (int _i = 0; _i < 2; ++_i) { \
;       __builtin_amdgcn_global_load_lds((const unsigned*)(_gb + voff[_i]), \
;         (LAS unsigned*)((LAS char*)(P) + ldsw + _i * 8192), 16, 0, 0); } } while (0)
; #define LDA(dst, b, h) _Pragma("unroll") for (int m = 0; m < 4; ++m) _Pragma("unroll") for (int k = 0; k < 2; ++k) \
;     dst[m][k] = *(const LAS bf16x8*)((LAS char*)SA(b, h) + aoff + m * 2048 + k * 1024)
; #define LDB(dst, b, h) _Pragma("unroll") for (int n = 0; n < 2; ++n) _Pragma("unroll") for (int k = 0; k < 2; ++k) \
;     dst[n][k] = *(const LAS bf16x8*)((LAS char*)SB(b, h) + boff + n * 2048 + k * 1024)
; #define MMA(ai, bj, At_, Bt_) do { __builtin_amdgcn_s_setprio(1); \
;     _Pragma("unroll") for (int m = 0; m < 4; ++m) _Pragma("unroll") for (int n = 0; n < 2; ++n) _Pragma("unroll") for (int k = 0; k < 2; ++k) \
;       acc[ai][bj][m][n] = __builtin_amdgcn_mfma_f32_16x16x32_bf16(Bt_[n][k], At_[m][k], acc[ai][bj][m][n], 0, 0, 0); \
;     __builtin_amdgcn_s_setprio(0); } while (0)
; #define WAIT_V(n) asm volatile("s_waitcnt vmcnt(" #n ")" ::: "memory")
; #define WAIT_L(n) asm volatile("s_waitcnt lgkmcnt(" #n ")" ::: "memory")
; #define BAR __builtin_amdgcn_s_barrier()
; #define SCHED __builtin_amdgcn_sched_barrier(0)
; __device__ __forceinline__ void gemm_phase(const bf16_t* __restrict__ A, const bf16_t* __restrict__ Bt, bf16_t* __restrict__ C, int M, int N, int K,
;                                            int ldc, const int EPI, char* smem, const int wid_u) {
;     ...
;       STG(SB(0, 1), b2 + hstep);
;       WAIT_V(6); BAR; MMA(1, 1, At, B1); BAR;
;       LDB(B0, 1, 0); SCHED; LDA(At, 1, 0); STG(SA(0, 1), a2 + hstep);
;       WAIT_L(8); BAR; WAIT_L(0); MMA(0, 0, At, B0); BAR; SCHED;
;       LDB(B1, 1, 1); STG(SB(1, 0), b3);
;       BAR; WAIT_L(0); MMA(0, 1, At, B1); BAR;
;       LDA(At, 1, 1); STG(SA(1, 0), a3);
	s_add_u32 s18, s22, 0x40000
	s_addc_u32 s19, s23, 0
	s_add_i32 s54, s41, s31
	v_lshl_add_u64 v[150:151], s[18:19], 0, v[130:131]
	s_mov_b32 m0, s54
	s_nop 0
	global_load_lds_dwordx4 v[150:151], off
	v_lshl_add_u64 v[150:151], s[18:19], 0, v[128:129]
	s_add_i32 m0, s54, 0x2000
	s_nop 0
	global_load_lds_dwordx4 v[150:151], off
	s_waitcnt vmcnt(6)
	s_barrier
	v_mfma_f32_16x16x32_bf16 v[52:55], v[198:201], v[166:169], v[52:55]
	v_mfma_f32_16x16x32_bf16 v[48:51], v[206:209], v[166:169], v[48:51]
	v_mfma_f32_16x16x32_bf16 v[36:39], v[198:201], v[174:177], v[36:39]
	v_mfma_f32_16x16x32_bf16 v[32:35], v[206:209], v[174:177], v[32:35]
	v_mfma_f32_16x16x32_bf16 v[20:23], v[198:201], v[182:185], v[20:23]
	v_mfma_f32_16x16x32_bf16 v[16:19], v[206:209], v[182:185], v[16:19]
	v_mfma_f32_16x16x32_bf16 v[4:7], v[198:201], v[190:193], v[4:7]
	v_mfma_f32_16x16x32_bf16 v[0:3], v[206:209], v[190:193], v[0:3]
	v_mfma_f32_16x16x32_bf16 v[52:55], v[202:205], v[170:173], v[52:55]
	v_mfma_f32_16x16x32_bf16 v[48:51], v[210:213], v[170:173], v[48:51]
	v_mfma_f32_16x16x32_bf16 v[36:39], v[202:205], v[178:181], v[36:39]
	v_mfma_f32_16x16x32_bf16 v[32:35], v[210:213], v[178:181], v[32:35]
	v_mfma_f32_16x16x32_bf16 v[20:23], v[202:205], v[186:189], v[20:23]
	v_mfma_f32_16x16x32_bf16 v[16:19], v[210:213], v[186:189], v[16:19]
	v_mfma_f32_16x16x32_bf16 v[4:7], v[202:205], v[194:197], v[4:7]
	v_mfma_f32_16x16x32_bf16 v[0:3], v[210:213], v[194:197], v[0:3]
	s_add_i32 s54, 0, 0x18000
	v_add_u32_e32 v149, s54, v145
	s_barrier
	ds_read_b128 v[150:153], v149
	ds_read_b128 v[154:157], v149 offset:1024
	ds_read_b128 v[158:161], v149 offset:2048
	ds_read_b128 v[162:165], v149 offset:3072
	s_add_u32 s18, s24, 0x40000
	s_addc_u32 s19, s25, 0
	s_mov_b32 m0, s36
	v_lshl_add_u64 v[198:199], s[18:19], 0, v[130:131]
	ds_read_b128 v[166:169], v147 offset:32768
	ds_read_b128 v[170:173], v147 offset:33792
	ds_read_b128 v[174:177], v147 offset:34816
	ds_read_b128 v[178:181], v147 offset:35840
	ds_read_b128 v[182:185], v147 offset:36864
	ds_read_b128 v[186:189], v147 offset:37888
	ds_read_b128 v[190:193], v147 offset:38912
	ds_read_b128 v[194:197], v147 offset:39936
	global_load_lds_dwordx4 v[198:199], off
	v_lshl_add_u64 v[198:199], s[18:19], 0, v[128:129]
	s_mov_b32 m0, s37
	s_nop 0
	global_load_lds_dwordx4 v[198:199], off
	s_waitcnt lgkmcnt(8)
	s_barrier
	s_waitcnt lgkmcnt(0)
	v_mfma_f32_16x16x32_bf16 v[124:127], v[150:153], v[166:169], v[124:127]
	v_mfma_f32_16x16x32_bf16 v[120:123], v[158:161], v[166:169], v[120:123]
	v_mfma_f32_16x16x32_bf16 v[108:111], v[150:153], v[174:177], v[108:111]
	v_mfma_f32_16x16x32_bf16 v[104:107], v[158:161], v[174:177], v[104:107]
	v_mfma_f32_16x16x32_bf16 v[92:95], v[150:153], v[182:185], v[92:95]
	v_mfma_f32_16x16x32_bf16 v[88:91], v[158:161], v[182:185], v[88:91]
	v_mfma_f32_16x16x32_bf16 v[76:79], v[150:153], v[190:193], v[76:79]
	v_mfma_f32_16x16x32_bf16 v[72:75], v[158:161], v[190:193], v[72:75]
	v_mfma_f32_16x16x32_bf16 v[124:127], v[154:157], v[170:173], v[124:127]
	v_mfma_f32_16x16x32_bf16 v[120:123], v[162:165], v[170:173], v[120:123]
	v_mfma_f32_16x16x32_bf16 v[108:111], v[154:157], v[178:181], v[108:111]
	v_mfma_f32_16x16x32_bf16 v[104:107], v[162:165], v[178:181], v[104:107]
	v_mfma_f32_16x16x32_bf16 v[92:95], v[154:157], v[186:189], v[92:95]
	v_mfma_f32_16x16x32_bf16 v[88:91], v[162:165], v[186:189], v[88:91]
	v_mfma_f32_16x16x32_bf16 v[76:79], v[154:157], v[194:197], v[76:79]
	v_mfma_f32_16x16x32_bf16 v[72:75], v[162:165], v[194:197], v[72:75]
	s_barrier
	s_add_i32 s24, 0, 0x1c000
	s_add_i32 s18, s54, s31
	v_add_u32_e32 v149, s24, v145
	v_lshl_add_u64 v[142:143], v[142:143], 0, s[10:11]
	s_mov_b32 m0, s18
	ds_read_b128 v[198:201], v149
	ds_read_b128 v[202:205], v149 offset:1024
	ds_read_b128 v[206:209], v149 offset:2048
	ds_read_b128 v[210:213], v149 offset:3072
	global_load_lds_dwordx4 v[142:143], off
	v_lshl_add_u64 v[142:143], v[214:215], 0, s[10:11]
	s_add_i32 m0, s18, 0x2000
	s_nop 0
	global_load_lds_dwordx4 v[142:143], off
	s_barrier
	s_waitcnt lgkmcnt(0)
	v_mfma_f32_16x16x32_bf16 v[116:119], v[198:201], v[166:169], v[116:119]
	v_mfma_f32_16x16x32_bf16 v[112:115], v[206:209], v[166:169], v[112:115]
	v_mfma_f32_16x16x32_bf16 v[100:103], v[198:201], v[174:177], v[100:103]
	v_mfma_f32_16x16x32_bf16 v[96:99], v[206:209], v[174:177], v[96:99]
	v_mfma_f32_16x16x32_bf16 v[84:87], v[198:201], v[182:185], v[84:87]
	v_mfma_f32_16x16x32_bf16 v[80:83], v[206:209], v[182:185], v[80:83]
	v_mfma_f32_16x16x32_bf16 v[68:71], v[198:201], v[190:193], v[68:71]
	v_mfma_f32_16x16x32_bf16 v[64:67], v[206:209], v[190:193], v[64:67]
	v_mfma_f32_16x16x32_bf16 v[116:119], v[202:205], v[170:173], v[116:119]
	v_mfma_f32_16x16x32_bf16 v[112:115], v[210:213], v[170:173], v[112:115]
	v_mfma_f32_16x16x32_bf16 v[100:103], v[202:205], v[178:181], v[100:103]
	v_mfma_f32_16x16x32_bf16 v[96:99], v[210:213], v[178:181], v[96:99]
	v_mfma_f32_16x16x32_bf16 v[84:87], v[202:205], v[186:189], v[84:87]
	v_mfma_f32_16x16x32_bf16 v[80:83], v[210:213], v[186:189], v[80:83]
	v_mfma_f32_16x16x32_bf16 v[68:71], v[202:205], v[194:197], v[68:71]
	v_mfma_f32_16x16x32_bf16 v[64:67], v[210:213], v[194:197], v[64:67]
	s_mov_b32 m0, s38
	v_lshl_add_u64 v[142:143], v[216:217], 0, s[10:11]
	s_barrier
	ds_read_b128 v[166:169], v147 offset:49152
	ds_read_b128 v[170:173], v147 offset:50176
	ds_read_b128 v[174:177], v147 offset:51200
	ds_read_b128 v[178:181], v147 offset:52224
	ds_read_b128 v[182:185], v147 offset:53248
	ds_read_b128 v[186:189], v147 offset:54272
	ds_read_b128 v[190:193], v147 offset:55296
	ds_read_b128 v[194:197], v147 offset:56320
	global_load_lds_dwordx4 v[142:143], off
	v_lshl_add_u64 v[142:143], v[218:219], 0, s[10:11]
	s_mov_b32 m0, s39
	s_nop 0
	global_load_lds_dwordx4 v[142:143], off
	s_barrier
; #define STG(P, GB) do { const char* _gb = (GB); \
;     _Pragma("unroll") for (int _i = 0; _i < 2; ++_i) { \
;       __builtin_amdgcn_global_load_lds((const unsigned*)(_gb + voff[_i]), \
;         (LAS unsigned*)((LAS char*)(P) + ldsw + _i * 8192), 16, 0, 0); } } while (0)
; #define MMA(ai, bj, At_, Bt_) do { __builtin_amdgcn_s_setprio(1); \
;     _Pragma("unroll") for (int m = 0; m < 4; ++m) _Pragma("unroll") for (int n = 0; n < 2; ++n) _Pragma("unroll") for (int k = 0; k < 2; ++k) \
;       acc[ai][bj][m][n] = __builtin_amdgcn_mfma_f32_16x16x32_bf16(Bt_[n][k], At_[m][k], acc[ai][bj][m][n], 0, 0, 0); \
;     __builtin_amdgcn_s_setprio(0); } while (0)
; #define WAIT_V(n) asm volatile("s_waitcnt vmcnt(" #n ")" ::: "memory")
; #define WAIT_L(n) asm volatile("s_waitcnt lgkmcnt(" #n ")" ::: "memory")
; #define BAR __builtin_amdgcn_s_barrier()
; #define SCHED __builtin_amdgcn_sched_barrier(0)
; __device__ __forceinline__ void gemm_phase(const bf16_t* __restrict__ A, const bf16_t* __restrict__ Bt, bf16_t* __restrict__ C, int M, int N, int K,
;                                            int ldc, const int EPI, char* smem, const int wid_u) {
;     ...
;       BAR; WAIT_L(0); MMA(1, 0, At, B0); BAR; SCHED;
;       STG(SB(1, 1), b3 + hstep);
;       WAIT_V(6); BAR; MMA(1, 1, At, B1); BAR;
;     }
;     ...
;             float o[8];
; #pragma unroll
;             for (int n = 0; n < 2; ++n) {
;               const f32x4 a = acc[ai][0][m][n], b = acc[ai][1][m][n];
; #pragma unroll
;               for (int j = 0; j < 4; ++j) o[n * 4 + j] = a[j] * __builtin_amdgcn_rcpf(1.f + __expf(-a[j])) * b[j];
;             }
;             *(uint4*)(C + row * ldc + (bcol >> 1) + wc * 32 + fq * 8) = pack8(o);
	s_waitcnt lgkmcnt(0)
	v_mfma_f32_16x16x32_bf16 v[60:63], v[150:153], v[166:169], v[60:63]
	v_mfma_f32_16x16x32_bf16 v[56:59], v[158:161], v[166:169], v[56:59]
	v_mfma_f32_16x16x32_bf16 v[44:47], v[150:153], v[174:177], v[44:47]
	v_mfma_f32_16x16x32_bf16 v[40:43], v[158:161], v[174:177], v[40:43]
	v_mfma_f32_16x16x32_bf16 v[28:31], v[150:153], v[182:185], v[28:31]
	v_mfma_f32_16x16x32_bf16 v[24:27], v[158:161], v[182:185], v[24:27]
	v_mfma_f32_16x16x32_bf16 v[12:15], v[150:153], v[190:193], v[12:15]
	v_mfma_f32_16x16x32_bf16 v[8:11], v[158:161], v[190:193], v[8:11]
	v_mfma_f32_16x16x32_bf16 v[60:63], v[154:157], v[170:173], v[60:63]
	v_mfma_f32_16x16x32_bf16 v[56:59], v[162:165], v[170:173], v[56:59]
	v_mfma_f32_16x16x32_bf16 v[44:47], v[154:157], v[178:181], v[44:47]
	v_mfma_f32_16x16x32_bf16 v[40:43], v[162:165], v[178:181], v[40:43]
	v_mfma_f32_16x16x32_bf16 v[28:31], v[154:157], v[186:189], v[28:31]
	v_mfma_f32_16x16x32_bf16 v[24:27], v[162:165], v[186:189], v[24:27]
	v_mfma_f32_16x16x32_bf16 v[12:15], v[154:157], v[194:197], v[12:15]
	v_mfma_f32_16x16x32_bf16 v[8:11], v[162:165], v[194:197], v[8:11]
	s_barrier
	s_add_u32 s18, s22, 0x40080
	s_addc_u32 s19, s23, 0
	s_add_i32 s22, s24, s31
	v_lshl_add_u64 v[142:143], s[18:19], 0, v[130:131]
	s_mov_b32 m0, s22
	s_nop 0
	global_load_lds_dwordx4 v[142:143], off
	v_lshl_add_u64 v[142:143], s[18:19], 0, v[128:129]
	s_add_i32 m0, s22, 0x2000
	s_nop 0
	global_load_lds_dwordx4 v[142:143], off
	s_waitcnt vmcnt(6)
	s_barrier
	v_mfma_f32_16x16x32_bf16 v[52:55], v[198:201], v[166:169], v[52:55]
	v_mfma_f32_16x16x32_bf16 v[48:51], v[206:209], v[166:169], v[48:51]
	v_mfma_f32_16x16x32_bf16 v[36:39], v[198:201], v[174:177], v[36:39]
	v_mfma_f32_16x16x32_bf16 v[32:35], v[206:209], v[174:177], v[32:35]
	v_mfma_f32_16x16x32_bf16 v[20:23], v[198:201], v[182:185], v[20:23]
	v_mfma_f32_16x16x32_bf16 v[16:19], v[206:209], v[182:185], v[16:19]
	v_mfma_f32_16x16x32_bf16 v[4:7], v[198:201], v[190:193], v[4:7]
	v_mfma_f32_16x16x32_bf16 v[0:3], v[206:209], v[190:193], v[0:3]
	v_mfma_f32_16x16x32_bf16 v[52:55], v[202:205], v[170:173], v[52:55]
	v_mfma_f32_16x16x32_bf16 v[48:51], v[210:213], v[170:173], v[48:51]
	v_mfma_f32_16x16x32_bf16 v[36:39], v[202:205], v[178:181], v[36:39]
	v_mfma_f32_16x16x32_bf16 v[32:35], v[210:213], v[178:181], v[32:35]
	v_mfma_f32_16x16x32_bf16 v[20:23], v[202:205], v[186:189], v[20:23]
	v_mfma_f32_16x16x32_bf16 v[16:19], v[210:213], v[186:189], v[16:19]
	v_mfma_f32_16x16x32_bf16 v[4:7], v[202:205], v[194:197], v[4:7]
	v_mfma_f32_16x16x32_bf16 v[0:3], v[210:213], v[194:197], v[0:3]
	s_add_i32 s53, s53, 2
	s_add_u32 s51, s51, 0x100
	s_addc_u32 s52, s52, 0
	s_cmp_gt_u32 s53, 13
	s_mov_b64 s[18:19], s[20:21]
	s_barrier
	s_cbranch_scc0 .LBB0_1026
	v_mul_f32_e32 v142, 0xbfb8aa3b, v124
	v_exp_f32_e32 v142, v142
	v_mul_f32_e32 v143, 0xbfb8aa3b, v125
	v_exp_f32_e32 v143, v143
	s_lshl_b32 s18, s46, 8
	v_add_f32_e32 v142, 1.0, v142
	v_rcp_f32_e32 v150, v142
	v_add_f32_e32 v142, 1.0, v143
	v_rcp_f32_e32 v151, v142
	s_mov_b32 s19, s9
	v_lshl_add_u32 v149, s47, 8, v144
	v_lshl_add_u64 v[142:143], v[132:133], 0, s[18:19]
	v_pk_mul_f32 v[124:125], v[124:125], v[150:151]
	v_mul_f32_e32 v150, 0xbfb8aa3b, v126
	v_mul_f32_e32 v151, 0xbfb8aa3b, v127
	v_exp_f32_e32 v150, v150
	v_exp_f32_e32 v151, v151
	v_pk_mul_f32 v[116:117], v[124:125], v[116:117]
	s_and_b64 vcc, exec, s[4:5]
	v_add_f32_e32 v124, 1.0, v150
	v_add_f32_e32 v125, 1.0, v151
	v_mul_f32_e32 v150, 0xbfb8aa3b, v120
	v_mul_f32_e32 v151, 0xbfb8aa3b, v121
	v_rcp_f32_e32 v124, v124
	v_rcp_f32_e32 v125, v125
	v_exp_f32_e32 v150, v150
	v_exp_f32_e32 v151, v151
	s_mov_b32 s47, s8
	v_pk_mul_f32 v[124:125], v[126:127], v[124:125]
	v_add_f32_e32 v126, 1.0, v150
	v_add_f32_e32 v127, 1.0, v151
	v_mul_f32_e32 v150, 0xbfb8aa3b, v122
	v_mul_f32_e32 v151, 0xbfb8aa3b, v123
	v_exp_f32_e32 v150, v150
	v_exp_f32_e32 v151, v151
	v_rcp_f32_e32 v126, v126
	v_rcp_f32_e32 v127, v127
	v_add_f32_e32 v150, 1.0, v150
	v_add_f32_e32 v151, 1.0, v151
	v_rcp_f32_e32 v150, v150
	v_rcp_f32_e32 v151, v151
	v_pk_mul_f32 v[120:121], v[120:121], v[126:127]
	v_pk_mul_f32 v[118:119], v[124:125], v[118:119]
	v_pk_mul_f32 v[120:121], v[120:121], v[112:113]
	v_pk_mul_f32 v[112:113], v[122:123], v[150:151]
	s_mov_b32 s46, s12
	v_pk_mul_f32 v[122:123], v[112:113], v[114:115]
	v_mul_f32_e32 v115, 0xbfb8aa3b, v108
	v_cvt_pk_bf16_f32 v112, v116, v117
	v_exp_f32_e32 v116, v115
	v_mul_f32_e32 v115, 0xbfb8aa3b, v109
	v_exp_f32_e32 v117, v115
	v_cvt_pk_bf16_f32 v113, v118, v119
	v_cvt_pk_bf16_f32 v114, v120, v121
	v_cvt_pk_bf16_f32 v115, v122, v123
	v_add_f32_e32 v116, 1.0, v116
	v_add_f32_e32 v117, 1.0, v117
	v_mad_i64_i32 v[118:119], s[18:19], v149, s44, v[142:143]
	v_rcp_f32_e32 v116, v116
	v_rcp_f32_e32 v117, v117
	global_store_dwordx4 v[118:119], v[112:115], off
	s_mov_b64 s[20:21], s[16:17]
	v_pk_mul_f32 v[108:109], v[108:109], v[116:117]
	v_mul_f32_e32 v112, 0xbfb8aa3b, v110
	v_mul_f32_e32 v113, 0xbfb8aa3b, v111
	v_exp_f32_e32 v112, v112
	v_exp_f32_e32 v113, v113
	v_pk_mul_f32 v[100:101], v[108:109], v[100:101]
	v_or_b32_e32 v114, 16, v149
	v_add_f32_e32 v108, 1.0, v112
	v_add_f32_e32 v109, 1.0, v113
	v_mul_f32_e32 v112, 0xbfb8aa3b, v104
	v_mul_f32_e32 v113, 0xbfb8aa3b, v105
	v_rcp_f32_e32 v108, v108
	v_rcp_f32_e32 v109, v109
	v_exp_f32_e32 v112, v112
	v_exp_f32_e32 v113, v113
	v_pk_mul_f32 v[108:109], v[110:111], v[108:109]
	v_add_f32_e32 v110, 1.0, v112
	v_add_f32_e32 v111, 1.0, v113
	v_mul_f32_e32 v112, 0xbfb8aa3b, v106
	v_mul_f32_e32 v113, 0xbfb8aa3b, v107
	v_exp_f32_e32 v112, v112
	v_exp_f32_e32 v113, v113
	v_rcp_f32_e32 v110, v110
	v_rcp_f32_e32 v111, v111
	v_add_f32_e32 v112, 1.0, v112
; __device__ __forceinline__ void gemm_phase(const bf16_t* __restrict__ A, const bf16_t* __restrict__ Bt, bf16_t* __restrict__ C, int M, int N, int K,
;                                            int ldc, const int EPI, char* smem, const int wid_u) {
;     ...
;             float o[8];
; #pragma unroll
;             for (int n = 0; n < 2; ++n) {
;               const f32x4 a = acc[ai][0][m][n], b = acc[ai][1][m][n];
; #pragma unroll
;               for (int j = 0; j < 4; ++j) o[n * 4 + j] = a[j] * __builtin_amdgcn_rcpf(1.f + __expf(-a[j])) * b[j];
;             }
;             *(uint4*)(C + row * ldc + (bcol >> 1) + wc * 32 + fq * 8) = pack8(o);
	v_add_f32_e32 v113, 1.0, v113
	v_rcp_f32_e32 v112, v112
	v_rcp_f32_e32 v113, v113
	v_pk_mul_f32 v[104:105], v[104:105], v[110:111]
	v_pk_mul_f32 v[102:103], v[108:109], v[102:103]
	v_pk_mul_f32 v[104:105], v[104:105], v[96:97]
	v_pk_mul_f32 v[96:97], v[106:107], v[112:113]
	s_nop 0
	v_pk_mul_f32 v[106:107], v[96:97], v[98:99]
	v_mul_f32_e32 v99, 0xbfb8aa3b, v92
	v_cvt_pk_bf16_f32 v96, v100, v101
	v_exp_f32_e32 v100, v99
	v_mul_f32_e32 v99, 0xbfb8aa3b, v93
	v_exp_f32_e32 v101, v99
	v_cvt_pk_bf16_f32 v97, v102, v103
	v_cvt_pk_bf16_f32 v98, v104, v105
	v_cvt_pk_bf16_f32 v99, v106, v107
	v_add_f32_e32 v100, 1.0, v100
	v_add_f32_e32 v101, 1.0, v101
	v_mad_i64_i32 v[102:103], s[18:19], v114, s44, v[142:143]
	v_rcp_f32_e32 v100, v100
	v_rcp_f32_e32 v101, v101
	global_store_dwordx4 v[102:103], v[96:99], off
	v_pk_mul_f32 v[92:93], v[92:93], v[100:101]
	s_nop 0
	v_mul_f32_e32 v96, 0xbfb8aa3b, v94
	v_mul_f32_e32 v97, 0xbfb8aa3b, v95
	v_exp_f32_e32 v96, v96
	v_exp_f32_e32 v97, v97
	v_pk_mul_f32 v[84:85], v[92:93], v[84:85]
	v_or_b32_e32 v98, 32, v149
	v_add_f32_e32 v92, 1.0, v96
	v_add_f32_e32 v93, 1.0, v97
	v_mul_f32_e32 v96, 0xbfb8aa3b, v88
	v_mul_f32_e32 v97, 0xbfb8aa3b, v89
	v_rcp_f32_e32 v92, v92
	v_rcp_f32_e32 v93, v93
	v_exp_f32_e32 v96, v96
	v_exp_f32_e32 v97, v97
	v_pk_mul_f32 v[92:93], v[94:95], v[92:93]
	v_add_f32_e32 v94, 1.0, v96
	v_add_f32_e32 v95, 1.0, v97
	v_mul_f32_e32 v96, 0xbfb8aa3b, v90
	v_mul_f32_e32 v97, 0xbfb8aa3b, v91
	v_exp_f32_e32 v96, v96
	v_exp_f32_e32 v97, v97
	v_rcp_f32_e32 v94, v94
	v_rcp_f32_e32 v95, v95
	v_add_f32_e32 v96, 1.0, v96
	v_add_f32_e32 v97, 1.0, v97
	v_rcp_f32_e32 v96, v96
	v_rcp_f32_e32 v97, v97
	v_pk_mul_f32 v[88:89], v[88:89], v[94:95]
	v_pk_mul_f32 v[86:87], v[92:93], v[86:87]
	v_pk_mul_f32 v[88:89], v[88:89], v[80:81]
	v_pk_mul_f32 v[80:81], v[90:91], v[96:97]
	s_nop 0
	v_pk_mul_f32 v[90:91], v[80:81], v[82:83]
	v_mul_f32_e32 v83, 0xbfb8aa3b, v76
	v_cvt_pk_bf16_f32 v80, v84, v85
	v_exp_f32_e32 v84, v83
	v_mul_f32_e32 v83, 0xbfb8aa3b, v77
	v_exp_f32_e32 v85, v83
	v_cvt_pk_bf16_f32 v81, v86, v87
	v_cvt_pk_bf16_f32 v82, v88, v89
	v_cvt_pk_bf16_f32 v83, v90, v91
	v_add_f32_e32 v84, 1.0, v84
	v_add_f32_e32 v85, 1.0, v85
	v_mad_i64_i32 v[86:87], s[18:19], v98, s44, v[142:143]
	v_rcp_f32_e32 v84, v84
	v_rcp_f32_e32 v85, v85
	global_store_dwordx4 v[86:87], v[80:83], off
	v_pk_mul_f32 v[76:77], v[76:77], v[84:85]
	s_nop 0
	v_mul_f32_e32 v80, 0xbfb8aa3b, v78
	v_mul_f32_e32 v81, 0xbfb8aa3b, v79
	v_exp_f32_e32 v80, v80
	v_exp_f32_e32 v81, v81
	v_pk_mul_f32 v[68:69], v[76:77], v[68:69]
	v_or_b32_e32 v82, 48, v149
	v_add_f32_e32 v76, 1.0, v80
	v_add_f32_e32 v77, 1.0, v81
	v_mul_f32_e32 v80, 0xbfb8aa3b, v72
	v_mul_f32_e32 v81, 0xbfb8aa3b, v73
	v_rcp_f32_e32 v76, v76
	v_rcp_f32_e32 v77, v77
	v_exp_f32_e32 v80, v80
	v_exp_f32_e32 v81, v81
	v_pk_mul_f32 v[76:77], v[78:79], v[76:77]
	v_add_f32_e32 v78, 1.0, v80
	v_add_f32_e32 v79, 1.0, v81
	v_mul_f32_e32 v80, 0xbfb8aa3b, v74
	v_mul_f32_e32 v81, 0xbfb8aa3b, v75
	v_exp_f32_e32 v80, v80
	v_exp_f32_e32 v81, v81
	v_rcp_f32_e32 v78, v78
	v_rcp_f32_e32 v79, v79
	v_add_f32_e32 v80, 1.0, v80
	v_add_f32_e32 v81, 1.0, v81
	v_rcp_f32_e32 v80, v80
	v_rcp_f32_e32 v81, v81
	v_pk_mul_f32 v[72:73], v[72:73], v[78:79]
	v_pk_mul_f32 v[70:71], v[76:77], v[70:71]
	v_pk_mul_f32 v[72:73], v[72:73], v[64:65]
	v_pk_mul_f32 v[64:65], v[74:75], v[80:81]
	s_nop 0
	v_pk_mul_f32 v[74:75], v[64:65], v[66:67]
	v_mul_f32_e32 v67, 0xbfb8aa3b, v60
	v_cvt_pk_bf16_f32 v64, v68, v69
	v_exp_f32_e32 v68, v67
	v_mul_f32_e32 v67, 0xbfb8aa3b, v61
	v_exp_f32_e32 v69, v67
	v_cvt_pk_bf16_f32 v65, v70, v71
	v_cvt_pk_bf16_f32 v66, v72, v73
	v_cvt_pk_bf16_f32 v67, v74, v75
	v_add_f32_e32 v68, 1.0, v68
	v_add_f32_e32 v69, 1.0, v69
	v_mad_i64_i32 v[70:71], s[18:19], v82, s44, v[142:143]
	v_rcp_f32_e32 v68, v68
	v_rcp_f32_e32 v69, v69
	global_store_dwordx4 v[70:71], v[64:67], off
	v_pk_mul_f32 v[60:61], v[60:61], v[68:69]
	s_nop 0
	v_mul_f32_e32 v64, 0xbfb8aa3b, v62
	v_mul_f32_e32 v65, 0xbfb8aa3b, v63
	v_exp_f32_e32 v64, v64
	v_exp_f32_e32 v65, v65
	v_pk_mul_f32 v[52:53], v[60:61], v[52:53]
	v_add_u32_e32 v66, 0x80, v149
	v_add_f32_e32 v60, 1.0, v64
	v_add_f32_e32 v61, 1.0, v65
	v_mul_f32_e32 v64, 0xbfb8aa3b, v56
	v_mul_f32_e32 v65, 0xbfb8aa3b, v57
	v_rcp_f32_e32 v60, v60
	v_rcp_f32_e32 v61, v61
	v_exp_f32_e32 v64, v64
	v_exp_f32_e32 v65, v65
	v_pk_mul_f32 v[60:61], v[62:63], v[60:61]
	v_add_f32_e32 v62, 1.0, v64
	v_add_f32_e32 v63, 1.0, v65
	v_mul_f32_e32 v64, 0xbfb8aa3b, v58
	v_mul_f32_e32 v65, 0xbfb8aa3b, v59
	v_exp_f32_e32 v64, v64
	v_exp_f32_e32 v65, v65
	v_rcp_f32_e32 v62, v62
	v_rcp_f32_e32 v63, v63
	v_add_f32_e32 v64, 1.0, v64
	v_add_f32_e32 v65, 1.0, v65
	v_rcp_f32_e32 v64, v64
	v_rcp_f32_e32 v65, v65
	v_pk_mul_f32 v[56:57], v[56:57], v[62:63]
	v_pk_mul_f32 v[54:55], v[60:61], v[54:55]
	v_pk_mul_f32 v[56:57], v[56:57], v[48:49]
	v_pk_mul_f32 v[48:49], v[58:59], v[64:65]
	s_nop 0
	v_pk_mul_f32 v[58:59], v[48:49], v[50:51]
; #define WAIT_V(n) asm volatile("s_waitcnt vmcnt(" #n ")" ::: "memory")
; #define BAR __builtin_amdgcn_s_barrier()
; __device__ __forceinline__ void gemm_phase(const bf16_t* __restrict__ A, const bf16_t* __restrict__ Bt, bf16_t* __restrict__ C, int M, int N, int K,
;                                            int ldc, const int EPI, char* smem, const int wid_u) {
;     ...
;             float o[8];
; #pragma unroll
;             for (int n = 0; n < 2; ++n) {
;               const f32x4 a = acc[ai][0][m][n], b = acc[ai][1][m][n];
; #pragma unroll
;               for (int j = 0; j < 4; ++j) o[n * 4 + j] = a[j] * __builtin_amdgcn_rcpf(1.f + __expf(-a[j])) * b[j];
;             }
;             *(uint4*)(C + row * ldc + (bcol >> 1) + wc * 32 + fq * 8) = pack8(o);
;     ...
;     if (!has_next) break;
; #pragma unroll
;     for (int a = 0; a < 2; ++a)
; #pragma unroll
;       for (int b = 0; b < 2; ++b)
; #pragma unroll
;         for (int m = 0; m < 4; ++m)
; #pragma unroll
;           for (int n = 0; n < 2; ++n) acc[a][b][m][n] = (f32x4){0.f, 0.f, 0.f, 0.f};
;     pm = npm; pn = npn; cA = nA; cB = nB; ++ui;
;   }
;   WAIT_V(0);
;   if (wr == 0) BAR;
;   BAR;
	v_mul_f32_e32 v51, 0xbfb8aa3b, v44
	v_cvt_pk_bf16_f32 v48, v52, v53
	v_exp_f32_e32 v52, v51
	v_mul_f32_e32 v51, 0xbfb8aa3b, v45
	v_exp_f32_e32 v53, v51
	v_cvt_pk_bf16_f32 v49, v54, v55
	v_cvt_pk_bf16_f32 v50, v56, v57
	v_cvt_pk_bf16_f32 v51, v58, v59
	v_add_f32_e32 v52, 1.0, v52
	v_add_f32_e32 v53, 1.0, v53
	v_mad_i64_i32 v[54:55], s[18:19], v66, s44, v[142:143]
	v_rcp_f32_e32 v52, v52
	v_rcp_f32_e32 v53, v53
	global_store_dwordx4 v[54:55], v[48:51], off
	v_pk_mul_f32 v[44:45], v[44:45], v[52:53]
	s_nop 0
	v_mul_f32_e32 v48, 0xbfb8aa3b, v46
	v_mul_f32_e32 v49, 0xbfb8aa3b, v47
	v_exp_f32_e32 v48, v48
	v_exp_f32_e32 v49, v49
	v_pk_mul_f32 v[36:37], v[44:45], v[36:37]
	v_add_u32_e32 v50, 0x90, v149
	v_add_f32_e32 v44, 1.0, v48
	v_add_f32_e32 v45, 1.0, v49
	v_mul_f32_e32 v48, 0xbfb8aa3b, v40
	v_mul_f32_e32 v49, 0xbfb8aa3b, v41
	v_rcp_f32_e32 v44, v44
	v_rcp_f32_e32 v45, v45
	v_exp_f32_e32 v48, v48
	v_exp_f32_e32 v49, v49
	v_pk_mul_f32 v[44:45], v[46:47], v[44:45]
	v_add_f32_e32 v46, 1.0, v48
	v_add_f32_e32 v47, 1.0, v49
	v_mul_f32_e32 v48, 0xbfb8aa3b, v42
	v_mul_f32_e32 v49, 0xbfb8aa3b, v43
	v_exp_f32_e32 v48, v48
	v_exp_f32_e32 v49, v49
	v_rcp_f32_e32 v46, v46
	v_rcp_f32_e32 v47, v47
	v_add_f32_e32 v48, 1.0, v48
	v_add_f32_e32 v49, 1.0, v49
	v_rcp_f32_e32 v48, v48
	v_rcp_f32_e32 v49, v49
	v_pk_mul_f32 v[40:41], v[40:41], v[46:47]
	v_pk_mul_f32 v[38:39], v[44:45], v[38:39]
	v_pk_mul_f32 v[40:41], v[40:41], v[32:33]
	v_pk_mul_f32 v[32:33], v[42:43], v[48:49]
	s_nop 0
	v_pk_mul_f32 v[42:43], v[32:33], v[34:35]
	v_mul_f32_e32 v35, 0xbfb8aa3b, v28
	v_cvt_pk_bf16_f32 v32, v36, v37
	v_exp_f32_e32 v36, v35
	v_mul_f32_e32 v35, 0xbfb8aa3b, v29
	v_exp_f32_e32 v37, v35
	v_cvt_pk_bf16_f32 v33, v38, v39
	v_cvt_pk_bf16_f32 v34, v40, v41
	v_cvt_pk_bf16_f32 v35, v42, v43
	v_add_f32_e32 v36, 1.0, v36
	v_add_f32_e32 v37, 1.0, v37
	v_mad_i64_i32 v[38:39], s[18:19], v50, s44, v[142:143]
	v_rcp_f32_e32 v36, v36
	v_rcp_f32_e32 v37, v37
	global_store_dwordx4 v[38:39], v[32:35], off
	v_pk_mul_f32 v[28:29], v[28:29], v[36:37]
	s_nop 0
	v_mul_f32_e32 v32, 0xbfb8aa3b, v30
	v_mul_f32_e32 v33, 0xbfb8aa3b, v31
	v_exp_f32_e32 v32, v32
	v_exp_f32_e32 v33, v33
	v_pk_mul_f32 v[20:21], v[28:29], v[20:21]
	v_add_u32_e32 v34, 0xa0, v149
	v_add_f32_e32 v28, 1.0, v32
	v_add_f32_e32 v29, 1.0, v33
	v_mul_f32_e32 v32, 0xbfb8aa3b, v24
	v_mul_f32_e32 v33, 0xbfb8aa3b, v25
	v_rcp_f32_e32 v28, v28
	v_rcp_f32_e32 v29, v29
	v_exp_f32_e32 v32, v32
	v_exp_f32_e32 v33, v33
	v_pk_mul_f32 v[28:29], v[30:31], v[28:29]
	v_add_f32_e32 v30, 1.0, v32
	v_add_f32_e32 v31, 1.0, v33
	v_mul_f32_e32 v32, 0xbfb8aa3b, v26
	v_mul_f32_e32 v33, 0xbfb8aa3b, v27
	v_exp_f32_e32 v32, v32
	v_exp_f32_e32 v33, v33
	v_rcp_f32_e32 v30, v30
	v_rcp_f32_e32 v31, v31
	v_add_f32_e32 v32, 1.0, v32
	v_add_f32_e32 v33, 1.0, v33
	v_rcp_f32_e32 v32, v32
	v_rcp_f32_e32 v33, v33
	v_pk_mul_f32 v[24:25], v[24:25], v[30:31]
	v_pk_mul_f32 v[22:23], v[28:29], v[22:23]
	v_pk_mul_f32 v[24:25], v[24:25], v[16:17]
	v_pk_mul_f32 v[16:17], v[26:27], v[32:33]
	s_nop 0
	v_pk_mul_f32 v[26:27], v[16:17], v[18:19]
	v_mul_f32_e32 v19, 0xbfb8aa3b, v12
	v_cvt_pk_bf16_f32 v16, v20, v21
	v_exp_f32_e32 v20, v19
	v_mul_f32_e32 v19, 0xbfb8aa3b, v13
	v_exp_f32_e32 v21, v19
	v_cvt_pk_bf16_f32 v17, v22, v23
	v_cvt_pk_bf16_f32 v18, v24, v25
	v_cvt_pk_bf16_f32 v19, v26, v27
	v_add_f32_e32 v20, 1.0, v20
	v_add_f32_e32 v21, 1.0, v21
	v_mad_i64_i32 v[22:23], s[18:19], v34, s44, v[142:143]
	v_rcp_f32_e32 v20, v20
	v_rcp_f32_e32 v21, v21
	global_store_dwordx4 v[22:23], v[16:19], off
	v_pk_mul_f32 v[12:13], v[12:13], v[20:21]
	s_nop 0
	v_mul_f32_e32 v16, 0xbfb8aa3b, v14
	v_mul_f32_e32 v17, 0xbfb8aa3b, v15
	v_exp_f32_e32 v16, v16
	v_exp_f32_e32 v17, v17
	v_pk_mul_f32 v[4:5], v[12:13], v[4:5]
	v_add_u32_e32 v18, 0xb0, v149
	v_add_f32_e32 v12, 1.0, v16
	v_add_f32_e32 v13, 1.0, v17
	v_mul_f32_e32 v16, 0xbfb8aa3b, v8
	v_mul_f32_e32 v17, 0xbfb8aa3b, v9
	v_rcp_f32_e32 v12, v12
	v_rcp_f32_e32 v13, v13
	v_exp_f32_e32 v16, v16
	v_exp_f32_e32 v17, v17
	v_pk_mul_f32 v[12:13], v[14:15], v[12:13]
	v_add_f32_e32 v14, 1.0, v16
	v_add_f32_e32 v15, 1.0, v17
	v_mul_f32_e32 v16, 0xbfb8aa3b, v10
	v_mul_f32_e32 v17, 0xbfb8aa3b, v11
	v_exp_f32_e32 v16, v16
	v_exp_f32_e32 v17, v17
	v_rcp_f32_e32 v14, v14
	v_rcp_f32_e32 v15, v15
	v_add_f32_e32 v16, 1.0, v16
	v_add_f32_e32 v17, 1.0, v17
	v_rcp_f32_e32 v16, v16
	v_rcp_f32_e32 v17, v17
	v_pk_mul_f32 v[8:9], v[8:9], v[14:15]
	v_pk_mul_f32 v[6:7], v[12:13], v[6:7]
	v_pk_mul_f32 v[8:9], v[8:9], v[0:1]
	v_pk_mul_f32 v[0:1], v[10:11], v[16:17]
	s_nop 0
	v_pk_mul_f32 v[10:11], v[0:1], v[2:3]
	v_cvt_pk_bf16_f32 v0, v4, v5
	v_mad_i64_i32 v[4:5], s[18:19], v18, s44, v[142:143]
	v_cvt_pk_bf16_f32 v1, v6, v7
	v_cvt_pk_bf16_f32 v2, v8, v9
	v_cvt_pk_bf16_f32 v3, v10, v11
	s_mov_b64 s[18:19], s[14:15]
	global_store_dwordx4 v[4:5], v[0:3], off
	s_cbranch_vccz .LBB0_1023
	s_waitcnt vmcnt(0)
	s_cmpk_gt_u32 s26, 0xff
	s_cbranch_scc1 .LBB0_1030
	s_barrier
